# v31 + nt on further last-use loads: FF2 epilogue hhat, GEMM2 gates (ga at mid, gb at epilogue), retention og, scan KV sums
# speedup vs baseline: 1.0173x; 1.0038x over previous
.LBB0_376:
	s_lshl_b64 s[4:5], s[60:61], 4
	s_or_b32 s4, s4, s11
	s_lshl_b64 s[6:7], s[4:5], 19
	s_add_u32 s46, s76, s6
	s_addc_u32 s47, s18, s7
	s_add_u32 s16, s59, s6
	s_addc_u32 s17, s82, s7
	s_sub_i32 s6, 11, s62
	s_cmpk_lt_u32 s96, 0x100
	s_cselect_b32 s45, s62, s6
	s_and_b64 s[6:7], s[74:75], exec
	s_cselect_b32 s6, s46, s16
	s_cselect_b32 s7, s47, s17
	s_add_u32 s6, s6, s0
	s_addc_u32 s7, s7, s1
	s_add_i32 s42, 0, 0x10000
	s_add_i32 s14, s42, s33
	s_add_i32 s44, s14, s34
	s_add_i32 s44, s44, s35
	s_barrier
	v_mbcnt_lo_u32_b32 v175, -1, 0
	v_mbcnt_hi_u32_b32 v175, -1, v175
	s_and_b64 s[14:15], s[84:85], exec
	v_lshlrev_b32_e32 v179, 3, v175
	v_add_u32_e32 v0, s77, v179
	s_cselect_b32 s15, s46, s16
	v_ashrrev_i32_e32 v1, 31, v0
	s_cselect_b32 s14, s47, s17
	s_add_u32 s16, s15, s28
	v_lshl_add_u64 v[0:1], v[0:1], 1, s[6:7]
	s_mov_b32 m0, s44
	s_addc_u32 s17, s14, s29
	s_add_i32 s20, s42, s56
	global_load_lds_dwordx4 v[0:1], off nt
	v_add_u32_e32 v0, s78, v179
	s_add_i32 s43, s20, s57
	v_ashrrev_i32_e32 v1, 31, v0
	s_add_i32 s43, s43, s64
	v_lshl_add_u64 v[0:1], v[0:1], 1, s[16:17]
	s_mov_b32 m0, s43
	s_add_u32 s18, s15, s38
	global_load_lds_dwordx4 v[0:1], off nt
	v_add_u32_e32 v0, s79, v179
	s_addc_u32 s19, s14, s39
	s_add_i32 s39, s20, s65
	v_ashrrev_i32_e32 v1, 31, v0
	s_add_i32 s39, s39, s80
	s_add_i32 s15, 0, 0x16000
	v_lshl_add_u64 v[0:1], v[0:1], 1, s[18:19]
	s_mov_b32 m0, s39
	v_add_u32_e32 v2, 0x400, v179
	s_add_i32 s14, s15, s33
	global_load_lds_dwordx4 v[0:1], off nt
	v_add_u32_e32 v0, s77, v2
	s_add_i32 s38, s14, s34
	v_ashrrev_i32_e32 v1, 31, v0
	s_add_i32 s38, s38, s35
	v_lshl_add_u64 v[0:1], v[0:1], 1, s[6:7]
	s_mov_b32 m0, s38
	s_add_i32 s14, s15, s56
	global_load_lds_dwordx4 v[0:1], off nt
	v_add_u32_e32 v0, s78, v2
	s_add_i32 s28, s14, s57
	v_ashrrev_i32_e32 v1, 31, v0
	s_add_i32 s28, s28, s64
	s_add_i32 s29, s14, s65
	v_lshl_add_u64 v[0:1], v[0:1], 1, s[16:17]
	s_mov_b32 m0, s28
	s_add_i32 s29, s29, s80
	s_lshl_b32 s14, s95, 16
	global_load_lds_dwordx4 v[0:1], off nt
	v_add_u32_e32 v0, s79, v2
	s_add_u32 s20, s46, s14
	v_and_b32_e32 v211, 31, v175
	v_ashrrev_i32_e32 v1, 31, v0
	s_addc_u32 s21, s47, 0
	s_lshl_b32 s14, s45, 5
	v_lshl_add_u64 v[0:1], v[0:1], 1, s[18:19]
	s_mov_b32 m0, s29
	v_or_b32_e32 v181, s14, v211
	v_ashrrev_i32_e32 v212, 5, v175
	global_load_lds_dwordx4 v[0:1], off nt
	v_lshlrev_b32_e32 v0, 5, v181
	v_ashrrev_i32_e32 v1, 31, v0
	v_lshlrev_b32_e32 v2, 3, v212
	v_lshl_add_u64 v[0:1], v[0:1], 1, s[20:21]
	v_ashrrev_i32_e32 v3, 31, v2
	v_lshl_add_u64 v[0:1], v[2:3], 1, v[0:1]
	s_movk_i32 s20, 0x4000
	v_add_co_u32_e32 v2, vcc, s20, v0
	s_mov_b32 s20, 0x8000
	s_nop 0
	v_addc_co_u32_e32 v3, vcc, 0, v1, vcc
	global_load_dwordx4 v[128:131], v[0:1], off
	global_load_dwordx4 v[132:135], v[0:1], off offset:32
	global_load_dwordx4 v[136:139], v[2:3], off
	global_load_dwordx4 v[140:143], v[2:3], off offset:32
	v_add_co_u32_e32 v2, vcc, s20, v0
	s_movk_i32 s20, 0x100
	s_nop 0
	v_addc_co_u32_e32 v3, vcc, 0, v1, vcc
	v_add_co_u32_e32 v0, vcc, 0xc000, v0
	global_load_dwordx4 v[144:147], v[2:3], off
	global_load_dwordx4 v[148:151], v[2:3], off offset:32
	v_addc_co_u32_e32 v1, vcc, 0, v1, vcc
	global_load_dwordx4 v[152:155], v[0:1], off
	global_load_dwordx4 v[156:159], v[0:1], off offset:32
	v_mbcnt_lo_u32_b32 v0, -1, 0
	v_mbcnt_hi_u32_b32 v0, -1, v0
	s_nop 0
	v_add_u32_e32 v0, s97, v0
	v_cmp_gt_i32_e32 vcc, s20, v0
	s_and_saveexec_b64 s[20:21], vcc
	s_cbranch_execz .LBB0_378
	s_lshl_b32 s11, s11, 11
	v_lshl_add_u32 v40, v0, 3, s11
	v_mul_f32_e32 v0, 0x43800000, v174
	s_mov_b32 s11, 0xc2fc0000
	v_mov_b32_e32 v1, 0x42800000
	v_cmp_gt_f32_e32 vcc, s11, v0
	s_and_b64 s[22:23], vcc, exec
	s_cselect_b32 s11, 0xffffffc0, 0
	v_cndmask_b32_e32 v0, 0, v1, vcc
	v_fmac_f32_e32 v0, 0x43800000, v174
	v_exp_f32_e32 v0, v0
	v_ashrrev_i32_e32 v41, 31, v40
	v_mov_b32_e32 v38, 0
	v_mov_b32_e32 v39, v38
	v_ldexp_f32 v36, v0, s11
	s_ashr_i32 s11, s10, 31
	v_lshl_add_u64 v[0:1], v[40:41], 1, s[8:9]
	s_lshl_b64 s[22:23], s[10:11], 16
	v_lshl_add_u64 v[2:3], v[0:1], 0, s[22:23]
	global_load_dwordx4 v[42:45], v[2:3], off nt
	s_or_b32 s22, s10, 1
	s_ashr_i32 s23, s22, 31
	s_lshl_b64 s[22:23], s[22:23], 16
	v_lshl_add_u64 v[2:3], v[0:1], 0, s[22:23]
	global_load_dwordx4 v[46:49], v[2:3], off nt
	s_or_b32 s22, s10, 2
	s_ashr_i32 s23, s22, 31
	s_lshl_b64 s[22:23], s[22:23], 16
	v_lshl_add_u64 v[2:3], v[0:1], 0, s[22:23]
	s_or_b32 s22, s10, 3
	s_ashr_i32 s23, s22, 31
	s_lshl_b64 s[22:23], s[22:23], 16
	v_lshl_add_u64 v[4:5], v[0:1], 0, s[22:23]
	global_load_dwordx4 v[50:53], v[2:3], off nt
	global_load_dwordx4 v[54:57], v[4:5], off nt
	s_or_b32 s22, s10, 4
	s_ashr_i32 s23, s22, 31
	s_lshl_b64 s[22:23], s[22:23], 16
	v_lshl_add_u64 v[2:3], v[0:1], 0, s[22:23]
	s_or_b32 s22, s10, 5
	s_ashr_i32 s23, s22, 31
	s_lshl_b64 s[22:23], s[22:23], 16
	v_lshl_add_u64 v[4:5], v[0:1], 0, s[22:23]
	global_load_dwordx4 v[58:61], v[2:3], off nt
	global_load_dwordx4 v[62:65], v[4:5], off nt
	s_or_b32 s22, s10, 6
	s_ashr_i32 s23, s22, 31
	s_lshl_b64 s[22:23], s[22:23], 16
	v_lshl_add_u64 v[2:3], v[0:1], 0, s[22:23]
	s_or_b32 s22, s10, 7
	s_ashr_i32 s23, s22, 31
	s_lshl_b64 s[22:23], s[22:23], 16
	v_lshl_add_u64 v[4:5], v[0:1], 0, s[22:23]
	global_load_dwordx4 v[32:35], v[2:3], off nt
	global_load_dwordx4 v[28:31], v[4:5], off nt
	s_or_b32 s22, s10, 8
	s_ashr_i32 s23, s22, 31
	s_lshl_b64 s[22:23], s[22:23], 16
	v_lshl_add_u64 v[2:3], v[0:1], 0, s[22:23]
	s_or_b32 s22, s10, 9
	s_ashr_i32 s23, s22, 31
	s_lshl_b64 s[22:23], s[22:23], 16
	v_lshl_add_u64 v[4:5], v[0:1], 0, s[22:23]
	global_load_dwordx4 v[24:27], v[2:3], off nt
	global_load_dwordx4 v[20:23], v[4:5], off nt
	s_or_b32 s22, s10, 10
	s_ashr_i32 s23, s22, 31
	s_lshl_b64 s[22:23], s[22:23], 16
	v_lshl_add_u64 v[2:3], v[0:1], 0, s[22:23]
	s_or_b32 s22, s10, 11
	s_ashr_i32 s23, s22, 31
	s_lshl_b64 s[22:23], s[22:23], 16
	v_lshl_add_u64 v[4:5], v[0:1], 0, s[22:23]
	global_load_dwordx4 v[16:19], v[2:3], off nt
	global_load_dwordx4 v[12:15], v[4:5], off nt
	s_or_b32 s22, s10, 12
	s_ashr_i32 s23, s22, 31
	s_lshl_b64 s[22:23], s[22:23], 16
	v_lshl_add_u64 v[2:3], v[0:1], 0, s[22:23]
	s_or_b32 s22, s10, 13
	s_ashr_i32 s23, s22, 31
	s_lshl_b64 s[22:23], s[22:23], 16
	v_lshl_add_u64 v[4:5], v[0:1], 0, s[22:23]
	global_load_dwordx4 v[8:11], v[2:3], off nt
	s_nop 0
	global_load_dwordx4 v[4:7], v[4:5], off nt
	s_or_b32 s10, s10, 14
	s_ashr_i32 s11, s10, 31
	s_lshl_b64 s[10:11], s[10:11], 16
	v_lshl_add_u64 v[0:1], v[0:1], 0, s[10:11]
	global_load_dwordx4 v[0:3], v[0:1], off nt
	s_lshl_b32 s22, s81, 20
	s_and_b32 s9, s9, 0xffff
	s_mov_b32 s11, 0x20000
	s_mov_b32 s10, 0x1000000
	v_lshl_add_u32 v37, v40, 1, s22
	v_mov_b32_e32 v40, v38
	v_mov_b32_e32 v41, v38
	buffer_store_dwordx4 v[38:41], v37, s[8:11], 0 offen sc1
	v_add_u32_e32 v70, 0x10000, v37
	s_nop 0
	v_mul_f32_e32 v38, 0, v36
	s_waitcnt vmcnt(0)
	v_lshlrev_b32_e32 v40, 16, v42
	v_and_b32_e32 v41, 0xffff0000, v42
	v_pk_add_f32 v[66:67], v[38:39], v[40:41] op_sel_hi:[0,1]
	v_lshlrev_b32_e32 v40, 16, v43
	v_and_b32_e32 v41, 0xffff0000, v43
	v_pk_add_f32 v[42:43], v[38:39], v[40:41] op_sel_hi:[0,1]
	v_lshlrev_b32_e32 v40, 16, v44
	v_and_b32_e32 v41, 0xffff0000, v44
	v_pk_add_f32 v[68:69], v[38:39], v[40:41] op_sel_hi:[0,1]
	v_lshlrev_b32_e32 v40, 16, v45
	v_and_b32_e32 v41, 0xffff0000, v45
	v_pk_add_f32 v[44:45], v[38:39], v[40:41] op_sel_hi:[0,1]
	v_cvt_pk_bf16_f32 v38, v66, v67
	v_cvt_pk_bf16_f32 v39, v42, v43
	v_cvt_pk_bf16_f32 v40, v68, v69
	v_cvt_pk_bf16_f32 v41, v44, v45
	buffer_store_dwordx4 v[38:41], v70, s[8:11], 0 offen sc1
	s_nop 1
	v_lshlrev_b32_e32 v38, 16, v46
	v_and_b32_e32 v39, 0xffff0000, v46
	v_pk_fma_f32 v[66:67], v[36:37], v[66:67], v[38:39] op_sel_hi:[0,1,1]
	v_lshlrev_b32_e32 v38, 16, v47
	v_and_b32_e32 v39, 0xffff0000, v47
	v_pk_fma_f32 v[42:43], v[36:37], v[42:43], v[38:39] op_sel_hi:[0,1,1]
	v_lshlrev_b32_e32 v38, 16, v48
	v_and_b32_e32 v39, 0xffff0000, v48
	v_pk_fma_f32 v[46:47], v[36:37], v[68:69], v[38:39] op_sel_hi:[0,1,1]
	v_lshlrev_b32_e32 v38, 16, v49
	v_and_b32_e32 v39, 0xffff0000, v49
	v_pk_fma_f32 v[44:45], v[36:37], v[44:45], v[38:39] op_sel_hi:[0,1,1]
	v_add_u32_e32 v48, 0x20000, v37
	v_cvt_pk_bf16_f32 v38, v66, v67
	v_cvt_pk_bf16_f32 v39, v42, v43
	v_cvt_pk_bf16_f32 v40, v46, v47
	v_cvt_pk_bf16_f32 v41, v44, v45
	buffer_store_dwordx4 v[38:41], v48, s[8:11], 0 offen sc1
	s_nop 1
	v_lshlrev_b32_e32 v38, 16, v50
	v_and_b32_e32 v39, 0xffff0000, v50
	v_pk_fma_f32 v[48:49], v[36:37], v[66:67], v[38:39] op_sel_hi:[0,1,1]
	v_lshlrev_b32_e32 v38, 16, v51
	v_and_b32_e32 v39, 0xffff0000, v51
	v_pk_fma_f32 v[42:43], v[36:37], v[42:43], v[38:39] op_sel_hi:[0,1,1]
	v_lshlrev_b32_e32 v38, 16, v52
	v_and_b32_e32 v39, 0xffff0000, v52
	v_pk_fma_f32 v[46:47], v[36:37], v[46:47], v[38:39] op_sel_hi:[0,1,1]
	v_lshlrev_b32_e32 v38, 16, v53
	v_and_b32_e32 v39, 0xffff0000, v53
	v_pk_fma_f32 v[44:45], v[36:37], v[44:45], v[38:39] op_sel_hi:[0,1,1]
	v_add_u32_e32 v50, 0x30000, v37
	v_cvt_pk_bf16_f32 v38, v48, v49
	v_cvt_pk_bf16_f32 v39, v42, v43
	v_cvt_pk_bf16_f32 v40, v46, v47
	v_cvt_pk_bf16_f32 v41, v44, v45
	buffer_store_dwordx4 v[38:41], v50, s[8:11], 0 offen sc1
	v_add_u32_e32 v50, 0x40000, v37
	s_nop 0
	v_lshlrev_b32_e32 v38, 16, v54
	v_and_b32_e32 v39, 0xffff0000, v54
	v_pk_fma_f32 v[48:49], v[36:37], v[48:49], v[38:39] op_sel_hi:[0,1,1]
	v_lshlrev_b32_e32 v38, 16, v55
	v_and_b32_e32 v39, 0xffff0000, v55
	v_pk_fma_f32 v[42:43], v[36:37], v[42:43], v[38:39] op_sel_hi:[0,1,1]
	v_lshlrev_b32_e32 v38, 16, v56
	v_and_b32_e32 v39, 0xffff0000, v56
	v_pk_fma_f32 v[46:47], v[36:37], v[46:47], v[38:39] op_sel_hi:[0,1,1]
	v_lshlrev_b32_e32 v38, 16, v57
	v_and_b32_e32 v39, 0xffff0000, v57
	v_pk_fma_f32 v[44:45], v[36:37], v[44:45], v[38:39] op_sel_hi:[0,1,1]
	v_cvt_pk_bf16_f32 v38, v48, v49
	v_cvt_pk_bf16_f32 v39, v42, v43
	v_cvt_pk_bf16_f32 v40, v46, v47
	v_cvt_pk_bf16_f32 v41, v44, v45
	buffer_store_dwordx4 v[38:41], v50, s[8:11], 0 offen sc1
	v_add_u32_e32 v50, 0x50000, v37
	s_nop 0
	v_lshlrev_b32_e32 v38, 16, v58
	v_and_b32_e32 v39, 0xffff0000, v58
	v_pk_fma_f32 v[48:49], v[36:37], v[48:49], v[38:39] op_sel_hi:[0,1,1]
	v_lshlrev_b32_e32 v38, 16, v59
	v_and_b32_e32 v39, 0xffff0000, v59
	v_pk_fma_f32 v[42:43], v[36:37], v[42:43], v[38:39] op_sel_hi:[0,1,1]
	v_lshlrev_b32_e32 v38, 16, v60
	v_and_b32_e32 v39, 0xffff0000, v60
	v_pk_fma_f32 v[46:47], v[36:37], v[46:47], v[38:39] op_sel_hi:[0,1,1]
	v_lshlrev_b32_e32 v38, 16, v61
	v_and_b32_e32 v39, 0xffff0000, v61
	v_pk_fma_f32 v[44:45], v[36:37], v[44:45], v[38:39] op_sel_hi:[0,1,1]
	v_cvt_pk_bf16_f32 v38, v48, v49
	v_cvt_pk_bf16_f32 v39, v42, v43
	v_cvt_pk_bf16_f32 v40, v46, v47
	v_cvt_pk_bf16_f32 v41, v44, v45
	buffer_store_dwordx4 v[38:41], v50, s[8:11], 0 offen sc1
	v_add_u32_e32 v50, 0x60000, v37
	s_nop 0
	v_lshlrev_b32_e32 v38, 16, v62
	v_and_b32_e32 v39, 0xffff0000, v62
	v_pk_fma_f32 v[48:49], v[36:37], v[48:49], v[38:39] op_sel_hi:[0,1,1]
	v_lshlrev_b32_e32 v38, 16, v63
	v_and_b32_e32 v39, 0xffff0000, v63
	v_pk_fma_f32 v[42:43], v[36:37], v[42:43], v[38:39] op_sel_hi:[0,1,1]
	v_lshlrev_b32_e32 v38, 16, v64
	v_and_b32_e32 v39, 0xffff0000, v64
	v_pk_fma_f32 v[46:47], v[36:37], v[46:47], v[38:39] op_sel_hi:[0,1,1]
	v_lshlrev_b32_e32 v38, 16, v65
	v_and_b32_e32 v39, 0xffff0000, v65
	v_pk_fma_f32 v[44:45], v[36:37], v[44:45], v[38:39] op_sel_hi:[0,1,1]
	v_cvt_pk_bf16_f32 v38, v48, v49
	v_cvt_pk_bf16_f32 v39, v42, v43
	v_cvt_pk_bf16_f32 v40, v46, v47
	v_cvt_pk_bf16_f32 v41, v44, v45
	buffer_store_dwordx4 v[38:41], v50, s[8:11], 0 offen sc1
	s_nop 1
	v_lshlrev_b32_e32 v38, 16, v32
	v_and_b32_e32 v39, 0xffff0000, v32
	v_lshlrev_b32_e32 v32, 16, v33
	v_and_b32_e32 v33, 0xffff0000, v33
	v_pk_fma_f32 v[40:41], v[36:37], v[42:43], v[32:33] op_sel_hi:[0,1,1]
	v_lshlrev_b32_e32 v32, 16, v34
	v_and_b32_e32 v33, 0xffff0000, v34
	v_pk_fma_f32 v[42:43], v[36:37], v[46:47], v[32:33] op_sel_hi:[0,1,1]
	v_lshlrev_b32_e32 v32, 16, v35
	v_and_b32_e32 v33, 0xffff0000, v35
	v_pk_fma_f32 v[38:39], v[36:37], v[48:49], v[38:39] op_sel_hi:[0,1,1]
	v_pk_fma_f32 v[44:45], v[36:37], v[44:45], v[32:33] op_sel_hi:[0,1,1]
	v_add_u32_e32 v46, 0x70000, v37
	v_cvt_pk_bf16_f32 v32, v38, v39
	v_cvt_pk_bf16_f32 v33, v40, v41
	v_cvt_pk_bf16_f32 v34, v42, v43
	v_cvt_pk_bf16_f32 v35, v44, v45
	buffer_store_dwordx4 v[32:35], v46, s[8:11], 0 offen sc1
	s_nop 1
	v_lshlrev_b32_e32 v32, 16, v28
	v_and_b32_e32 v33, 0xffff0000, v28
	v_lshlrev_b32_e32 v28, 16, v29
	v_and_b32_e32 v29, 0xffff0000, v29
	v_pk_fma_f32 v[34:35], v[36:37], v[40:41], v[28:29] op_sel_hi:[0,1,1]
	v_lshlrev_b32_e32 v28, 16, v30
	v_and_b32_e32 v29, 0xffff0000, v30
	v_pk_fma_f32 v[32:33], v[36:37], v[38:39], v[32:33] op_sel_hi:[0,1,1]
	v_pk_fma_f32 v[38:39], v[36:37], v[42:43], v[28:29] op_sel_hi:[0,1,1]
	v_lshlrev_b32_e32 v28, 16, v31
	v_and_b32_e32 v29, 0xffff0000, v31
	v_pk_fma_f32 v[40:41], v[36:37], v[44:45], v[28:29] op_sel_hi:[0,1,1]
	v_add_u32_e32 v42, 0x80000, v37
	v_cvt_pk_bf16_f32 v28, v32, v33
	v_cvt_pk_bf16_f32 v29, v34, v35
	v_cvt_pk_bf16_f32 v30, v38, v39
	v_cvt_pk_bf16_f32 v31, v40, v41
	buffer_store_dwordx4 v[28:31], v42, s[8:11], 0 offen sc1
	s_nop 1
	v_lshlrev_b32_e32 v28, 16, v24
	v_and_b32_e32 v29, 0xffff0000, v24
	v_lshlrev_b32_e32 v24, 16, v25
	v_and_b32_e32 v25, 0xffff0000, v25
	v_pk_fma_f32 v[30:31], v[36:37], v[34:35], v[24:25] op_sel_hi:[0,1,1]
	v_lshlrev_b32_e32 v24, 16, v26
	v_and_b32_e32 v25, 0xffff0000, v26
	v_pk_fma_f32 v[28:29], v[36:37], v[32:33], v[28:29] op_sel_hi:[0,1,1]
	v_pk_fma_f32 v[32:33], v[36:37], v[38:39], v[24:25] op_sel_hi:[0,1,1]
	v_lshlrev_b32_e32 v24, 16, v27
	v_and_b32_e32 v25, 0xffff0000, v27
	v_pk_fma_f32 v[34:35], v[36:37], v[40:41], v[24:25] op_sel_hi:[0,1,1]
	v_add_u32_e32 v38, 0x90000, v37
	v_cvt_pk_bf16_f32 v24, v28, v29
	v_cvt_pk_bf16_f32 v25, v30, v31
	v_cvt_pk_bf16_f32 v26, v32, v33
	v_cvt_pk_bf16_f32 v27, v34, v35
	buffer_store_dwordx4 v[24:27], v38, s[8:11], 0 offen sc1
	s_nop 1
	v_lshlrev_b32_e32 v24, 16, v20
	v_and_b32_e32 v25, 0xffff0000, v20
	v_lshlrev_b32_e32 v20, 16, v21
	v_and_b32_e32 v21, 0xffff0000, v21
	v_pk_fma_f32 v[26:27], v[36:37], v[30:31], v[20:21] op_sel_hi:[0,1,1]
	v_lshlrev_b32_e32 v20, 16, v22
	v_and_b32_e32 v21, 0xffff0000, v22
	v_pk_fma_f32 v[24:25], v[36:37], v[28:29], v[24:25] op_sel_hi:[0,1,1]
	v_pk_fma_f32 v[28:29], v[36:37], v[32:33], v[20:21] op_sel_hi:[0,1,1]
	v_lshlrev_b32_e32 v20, 16, v23
	v_and_b32_e32 v21, 0xffff0000, v23
	v_pk_fma_f32 v[30:31], v[36:37], v[34:35], v[20:21] op_sel_hi:[0,1,1]
	v_add_u32_e32 v32, 0xa0000, v37
	v_cvt_pk_bf16_f32 v20, v24, v25
	v_cvt_pk_bf16_f32 v21, v26, v27
	v_cvt_pk_bf16_f32 v22, v28, v29
	v_cvt_pk_bf16_f32 v23, v30, v31
	buffer_store_dwordx4 v[20:23], v32, s[8:11], 0 offen sc1
	s_nop 1
	v_lshlrev_b32_e32 v20, 16, v16
	v_and_b32_e32 v21, 0xffff0000, v16
	v_lshlrev_b32_e32 v16, 16, v17
	v_and_b32_e32 v17, 0xffff0000, v17
	v_pk_fma_f32 v[22:23], v[36:37], v[26:27], v[16:17] op_sel_hi:[0,1,1]
	v_lshlrev_b32_e32 v16, 16, v18
	v_and_b32_e32 v17, 0xffff0000, v18
	v_pk_fma_f32 v[20:21], v[36:37], v[24:25], v[20:21] op_sel_hi:[0,1,1]
	v_pk_fma_f32 v[24:25], v[36:37], v[28:29], v[16:17] op_sel_hi:[0,1,1]
	v_lshlrev_b32_e32 v16, 16, v19
	v_and_b32_e32 v17, 0xffff0000, v19
	v_pk_fma_f32 v[26:27], v[36:37], v[30:31], v[16:17] op_sel_hi:[0,1,1]
	v_add_u32_e32 v28, 0xb0000, v37
	v_cvt_pk_bf16_f32 v16, v20, v21
	v_cvt_pk_bf16_f32 v17, v22, v23
	v_cvt_pk_bf16_f32 v18, v24, v25
	v_cvt_pk_bf16_f32 v19, v26, v27
	buffer_store_dwordx4 v[16:19], v28, s[8:11], 0 offen sc1
	s_nop 1
	v_lshlrev_b32_e32 v16, 16, v12
	v_and_b32_e32 v17, 0xffff0000, v12
	v_lshlrev_b32_e32 v12, 16, v13
	v_and_b32_e32 v13, 0xffff0000, v13
	v_pk_fma_f32 v[18:19], v[36:37], v[22:23], v[12:13] op_sel_hi:[0,1,1]
	v_lshlrev_b32_e32 v12, 16, v14
	v_and_b32_e32 v13, 0xffff0000, v14
	v_pk_fma_f32 v[16:17], v[36:37], v[20:21], v[16:17] op_sel_hi:[0,1,1]
	v_pk_fma_f32 v[20:21], v[36:37], v[24:25], v[12:13] op_sel_hi:[0,1,1]
	v_lshlrev_b32_e32 v12, 16, v15
	v_and_b32_e32 v13, 0xffff0000, v15
	v_pk_fma_f32 v[22:23], v[36:37], v[26:27], v[12:13] op_sel_hi:[0,1,1]
	v_add_u32_e32 v24, 0xc0000, v37
	v_cvt_pk_bf16_f32 v12, v16, v17
	v_cvt_pk_bf16_f32 v13, v18, v19
	v_cvt_pk_bf16_f32 v14, v20, v21
	v_cvt_pk_bf16_f32 v15, v22, v23
	buffer_store_dwordx4 v[12:15], v24, s[8:11], 0 offen sc1
	s_nop 1
	v_lshlrev_b32_e32 v12, 16, v8
	v_and_b32_e32 v13, 0xffff0000, v8
	v_lshlrev_b32_e32 v8, 16, v9
	v_and_b32_e32 v9, 0xffff0000, v9
	v_pk_fma_f32 v[14:15], v[36:37], v[18:19], v[8:9] op_sel_hi:[0,1,1]
	v_lshlrev_b32_e32 v8, 16, v10
	v_and_b32_e32 v9, 0xffff0000, v10
	v_pk_fma_f32 v[12:13], v[36:37], v[16:17], v[12:13] op_sel_hi:[0,1,1]
	v_pk_fma_f32 v[16:17], v[36:37], v[20:21], v[8:9] op_sel_hi:[0,1,1]
	v_lshlrev_b32_e32 v8, 16, v11
	v_and_b32_e32 v9, 0xffff0000, v11
	v_pk_fma_f32 v[18:19], v[36:37], v[22:23], v[8:9] op_sel_hi:[0,1,1]
	v_add_u32_e32 v20, 0xd0000, v37
	v_cvt_pk_bf16_f32 v8, v12, v13
	v_cvt_pk_bf16_f32 v9, v14, v15
	v_cvt_pk_bf16_f32 v10, v16, v17
	v_cvt_pk_bf16_f32 v11, v18, v19
	buffer_store_dwordx4 v[8:11], v20, s[8:11], 0 offen sc1
	s_nop 1
	v_lshlrev_b32_e32 v8, 16, v4
	v_and_b32_e32 v9, 0xffff0000, v4
	v_lshlrev_b32_e32 v4, 16, v5
	v_and_b32_e32 v5, 0xffff0000, v5
	v_pk_fma_f32 v[10:11], v[36:37], v[14:15], v[4:5] op_sel_hi:[0,1,1]
	v_lshlrev_b32_e32 v4, 16, v6
	v_and_b32_e32 v5, 0xffff0000, v6
	v_pk_fma_f32 v[8:9], v[36:37], v[12:13], v[8:9] op_sel_hi:[0,1,1]
	v_pk_fma_f32 v[12:13], v[36:37], v[16:17], v[4:5] op_sel_hi:[0,1,1]
	v_lshlrev_b32_e32 v4, 16, v7
	v_and_b32_e32 v5, 0xffff0000, v7
	v_pk_fma_f32 v[14:15], v[36:37], v[18:19], v[4:5] op_sel_hi:[0,1,1]
	v_add_u32_e32 v16, 0xe0000, v37
	v_cvt_pk_bf16_f32 v4, v8, v9
	v_cvt_pk_bf16_f32 v5, v10, v11
	v_cvt_pk_bf16_f32 v6, v12, v13
	v_cvt_pk_bf16_f32 v7, v14, v15
	buffer_store_dwordx4 v[4:7], v16, s[8:11], 0 offen sc1
	s_nop 1
	v_lshlrev_b32_e32 v4, 16, v0
	v_and_b32_e32 v5, 0xffff0000, v0
	v_lshlrev_b32_e32 v0, 16, v1
	v_and_b32_e32 v1, 0xffff0000, v1
	v_pk_fma_f32 v[6:7], v[36:37], v[10:11], v[0:1] op_sel_hi:[0,1,1]
	v_lshlrev_b32_e32 v0, 16, v2
	v_and_b32_e32 v1, 0xffff0000, v2
	v_pk_fma_f32 v[4:5], v[36:37], v[8:9], v[4:5] op_sel_hi:[0,1,1]
	v_pk_fma_f32 v[8:9], v[36:37], v[12:13], v[0:1] op_sel_hi:[0,1,1]
	v_lshlrev_b32_e32 v0, 16, v3
	v_and_b32_e32 v1, 0xffff0000, v3
	v_pk_fma_f32 v[10:11], v[36:37], v[14:15], v[0:1] op_sel_hi:[0,1,1]
	v_add_u32_e32 v12, 0xf0000, v37
	v_cvt_pk_bf16_f32 v0, v4, v5
	v_cvt_pk_bf16_f32 v1, v6, v7
	v_cvt_pk_bf16_f32 v2, v8, v9
	v_cvt_pk_bf16_f32 v3, v10, v11
	buffer_store_dwordx4 v[0:3], v12, s[8:11], 0 offen sc1

.LBB0_413:
	s_lshl_b64 s[4:5], s[4:5], 21
	s_add_u32 s4, s54, s4
	s_addc_u32 s5, s55, s5
	s_lshl_b32 s6, s95, 17
	v_ashrrev_i32_e32 v213, 2, v175
	s_add_u32 s4, s4, s6
	v_add_lshl_u32 v128, v213, s14, 5
	s_addc_u32 s5, s5, 0
	v_ashrrev_i32_e32 v129, 31, v128
	v_lshl_add_u64 v[128:129], v[128:129], 1, s[4:5]
	v_lshlrev_b32_e32 v130, 1, v176
	v_mov_b32_e32 v131, 0
	v_lshl_add_u64 v[132:133], v[128:129], 0, v[130:131]
	s_mov_b64 s[4:5], 0x6c00000
	v_lshl_add_u64 v[206:207], v[132:133], 0, s[4:5]
	s_mov_b32 s4, 0x6c00000
	v_add_co_u32_e32 v208, vcc, s4, v132
	s_mov_b32 s4, 0x6c04000
	s_nop 0
	v_addc_co_u32_e32 v209, vcc, 0, v133, vcc
	v_add_co_u32_e32 v204, vcc, s4, v132
	s_mov_b32 s4, 0x6c08000
	s_nop 0
	v_addc_co_u32_e32 v205, vcc, 0, v133, vcc
	v_add_co_u32_e32 v202, vcc, s4, v132
	s_mov_b32 s4, 0x6c0c000
	s_nop 0
	v_addc_co_u32_e32 v203, vcc, 0, v133, vcc
	v_add_co_u32_e32 v200, vcc, s4, v132
	s_mov_b32 s4, 0x6c10000
	s_nop 0
	v_addc_co_u32_e32 v201, vcc, 0, v133, vcc
	v_add_co_u32_e32 v198, vcc, s4, v132
	s_mov_b32 s4, 0x6c14000
	s_nop 0
	v_addc_co_u32_e32 v199, vcc, 0, v133, vcc
	v_add_co_u32_e32 v196, vcc, s4, v132
	s_mov_b32 s4, 0x6c18000
	s_nop 0
	v_addc_co_u32_e32 v197, vcc, 0, v133, vcc
	v_add_co_u32_e32 v194, vcc, s4, v132
	s_mov_b32 s4, 0x6c1c000
	s_nop 0
	v_addc_co_u32_e32 v195, vcc, 0, v133, vcc
	v_add_co_u32_e32 v192, vcc, s4, v132
	v_lshlrev_b32_e32 v132, 2, v211
	v_lshl_or_b32 v221, s95, 10, v132
	s_waitcnt vmcnt(0) lgkmcnt(0)
	s_barrier
	global_load_dwordx4 v[188:191], v[208:209], off nt
	global_load_dwordx4 v[184:187], v[206:207], off offset:1024 nt
	global_load_dwordx4 v[180:183], v[204:205], off nt
	global_load_dwordx4 v[176:179], v[204:205], off offset:1024 nt
	global_load_dwordx4 v[172:175], v[202:203], off nt
	global_load_dwordx4 v[168:171], v[202:203], off offset:1024 nt
	global_load_dwordx4 v[164:167], v[200:201], off nt
	global_load_dwordx4 v[160:163], v[200:201], off offset:1024 nt
	global_load_dwordx4 v[156:159], v[198:199], off nt
	global_load_dwordx4 v[152:155], v[198:199], off offset:1024 nt
	global_load_dwordx4 v[148:151], v[196:197], off nt
	global_load_dwordx4 v[144:147], v[196:197], off offset:1024 nt
	global_load_dwordx4 v[140:143], v[194:195], off nt
	global_load_dwordx4 v[128:131], v[194:195], off offset:1024 nt
	global_load_dword v215, v221, s[50:51]
	global_load_dword v214, v221, s[50:51] offset:128
	v_mbcnt_lo_u32_b32 v132, -1, 0
	v_mbcnt_hi_u32_b32 v132, -1, v132
	v_and_b32_e32 v134, 64, v132
	v_addc_co_u32_e32 v193, vcc, 0, v133, vcc
	v_xor_b32_e32 v133, 16, v132
	v_add_u32_e32 v134, 64, v134
	v_cmp_lt_i32_e32 vcc, v133, v134
	global_load_dword v219, v221, s[50:51] offset:256
	global_load_dword v218, v221, s[50:51] offset:384
	global_load_dword v217, v221, s[50:51] offset:512
	global_load_dword v216, v221, s[50:51] offset:640
	v_cndmask_b32_e32 v132, v132, v133, vcc
	v_lshlrev_b32_e32 v220, 2, v132
	v_add_f32_e32 v132, 0, v0
	v_add_f32_e32 v132, v132, v16
	v_add_f32_e32 v132, v132, v32
	v_add_f32_e32 v132, v132, v48
	v_add_f32_e32 v132, v132, v64
	v_add_f32_e32 v132, v132, v80
	v_add_f32_e32 v132, v132, v96
	v_add_f32_e32 v132, v132, v112
	s_mov_b32 s7, 0xf800000
	s_mul_i32 s4, s62, 0x4200
	v_add_f32_dpp v132, v132, v132 quad_perm:[1,0,3,2] row_mask:0xf bank_mask:0xf bound_ctrl:1
	s_add_i32 s6, s4, 0
	s_movk_i32 s8, 0x840
	v_add_f32_dpp v132, v132, v132 quad_perm:[2,3,0,1] row_mask:0xf bank_mask:0xf bound_ctrl:1
	v_lshlrev_b32_e32 v211, 1, v211
	s_nop 0
	v_add_f32_dpp v132, v132, v132 row_ror:4 row_mask:0xf bank_mask:0xf bound_ctrl:1
	s_nop 1
	v_add_f32_dpp v132, v132, v132 row_ror:8 row_mask:0xf bank_mask:0xf bound_ctrl:1
	ds_bpermute_b32 v133, v220, v132
	s_waitcnt lgkmcnt(0)
	v_add_f32_e32 v132, v132, v133
	v_fmamk_f32 v223, v132, 0xbb800000, v16
	v_fmamk_f32 v222, v132, 0xbb800000, v0
	v_mul_f32_e32 v0, v223, v223
	v_fmac_f32_e32 v0, v222, v222
	v_fmamk_f32 v224, v132, 0xbb800000, v32
	v_fmac_f32_e32 v0, v224, v224
	v_fmamk_f32 v225, v132, 0xbb800000, v48
	v_fmac_f32_e32 v0, v225, v225
	v_fmamk_f32 v226, v132, 0xbb800000, v64
	v_fmac_f32_e32 v0, v226, v226
	v_fmamk_f32 v80, v132, 0xbb800000, v80
	v_fmac_f32_e32 v0, v80, v80
	v_fmamk_f32 v96, v132, 0xbb800000, v96
	v_fmac_f32_e32 v0, v96, v96
	v_fmamk_f32 v112, v132, 0xbb800000, v112
	v_fmac_f32_e32 v0, v112, v112
	s_nop 1
	v_add_f32_dpp v0, v0, v0 quad_perm:[1,0,3,2] row_mask:0xf bank_mask:0xf bound_ctrl:1
	s_nop 1
	v_add_f32_dpp v0, v0, v0 quad_perm:[2,3,0,1] row_mask:0xf bank_mask:0xf bound_ctrl:1
	s_nop 1
	v_add_f32_dpp v0, v0, v0 row_ror:4 row_mask:0xf bank_mask:0xf bound_ctrl:1
	s_nop 1
	v_add_f32_dpp v32, v0, v0 row_ror:8 row_mask:0xf bank_mask:0xf bound_ctrl:1
	global_load_dwordx4 v[136:139], v[192:193], off nt
	global_load_dwordx4 v[132:135], v[192:193], off offset:1024 nt
	global_load_dword v16, v221, s[50:51] offset:768
	global_load_dword v0, v221, s[50:51] offset:896
	ds_bpermute_b32 v48, v220, v32
	s_waitcnt lgkmcnt(0)
	v_add_f32_e32 v32, v32, v48
	v_mov_b32_e32 v48, 0x358637bd
	v_fmamk_f32 v32, v32, 0x3b800000, v48
	v_mul_f32_e32 v64, 0x4f800000, v32
	v_cmp_gt_f32_e32 vcc, s7, v32
	s_nop 1
	v_cndmask_b32_e32 v32, v32, v64, vcc
	v_sqrt_f32_e32 v64, v32
	s_nop 0
	v_add_u32_e32 v221, -1, v64
	v_fma_f32 v227, -v221, v64, v32
	v_cmp_ge_f32_e64 s[4:5], 0, v227
	v_add_u32_e32 v227, 1, v64
	s_nop 0
	v_cndmask_b32_e64 v221, v64, v221, s[4:5]
	v_fma_f32 v64, -v227, v64, v32
	v_cmp_lt_f32_e64 s[4:5], 0, v64
	s_nop 1
	v_cndmask_b32_e64 v64, v221, v227, s[4:5]
	v_mul_f32_e32 v221, 0x37800000, v64
	v_cndmask_b32_e32 v221, v64, v221, vcc
	v_mov_b32_e32 v64, 0x260
	v_cmp_class_f32_e32 vcc, v32, v64
	s_nop 1
	v_cndmask_b32_e32 v221, v221, v32, vcc
	v_div_scale_f32 v227, s[4:5], v221, v221, 1.0
	v_rcp_f32_e32 v228, v227
	v_mul_lo_u32 v32, v212, s8
	v_add3_u32 v32, s6, v32, v211
	v_fma_f32 v211, -v227, v228, 1.0
	v_fmac_f32_e32 v228, v211, v228
	v_div_scale_f32 v211, vcc, 1.0, v221, 1.0
	v_mul_f32_e32 v212, v211, v228
	v_fma_f32 v229, -v227, v212, v211
	v_fmac_f32_e32 v212, v229, v228
	v_fma_f32 v211, -v227, v212, v211
	v_div_fmas_f32 v211, v211, v228, v212
	v_div_fixup_f32 v211, v211, v221, 1.0
	v_add_f32_e32 v221, 0, v1
	v_add_f32_e32 v221, v221, v17
	v_mul_f32_e32 v212, v222, v211
	v_add_f32_e32 v221, v221, v33
	s_waitcnt vmcnt(9)
	v_mul_f32_e32 v212, v215, v212
	v_add_f32_e32 v221, v221, v49
	v_cvt_pk_bf16_f32 v212, v212, s0
	v_add_f32_e32 v221, v221, v65
	ds_write_b16 v32, v212
	v_mul_f32_e32 v212, v223, v211
	v_add_f32_e32 v221, v221, v81
	s_waitcnt vmcnt(8)
	v_mul_f32_e32 v212, v214, v212
	v_add_f32_e32 v221, v221, v97
	v_cvt_pk_bf16_f32 v212, v212, s0
	v_add_f32_e32 v221, v221, v113
	ds_write_b16 v32, v212 offset:64
	v_mul_f32_e32 v212, v224, v211
	v_add_f32_dpp v221, v221, v221 quad_perm:[1,0,3,2] row_mask:0xf bank_mask:0xf bound_ctrl:1
	s_waitcnt vmcnt(7)
	v_mul_f32_e32 v212, v219, v212
	v_cvt_pk_bf16_f32 v212, v212, s0
	v_add_f32_dpp v221, v221, v221 quad_perm:[2,3,0,1] row_mask:0xf bank_mask:0xf bound_ctrl:1
	ds_write_b16 v32, v212 offset:128
	v_mul_f32_e32 v212, v225, v211
	v_add_f32_dpp v221, v221, v221 row_ror:4 row_mask:0xf bank_mask:0xf bound_ctrl:1
	s_waitcnt vmcnt(6)
	v_mul_f32_e32 v212, v218, v212
	v_cvt_pk_bf16_f32 v212, v212, s0
	v_add_f32_dpp v221, v221, v221 row_ror:8 row_mask:0xf bank_mask:0xf bound_ctrl:1
	ds_bpermute_b32 v222, v220, v221
	ds_write_b16 v32, v212 offset:192
	v_mul_f32_e32 v212, v226, v211
	s_waitcnt vmcnt(5)
	v_mul_f32_e32 v212, v217, v212
	v_cvt_pk_bf16_f32 v212, v212, s0
	ds_write_b16 v32, v212 offset:256
	s_waitcnt lgkmcnt(2)
	v_add_f32_e32 v212, v221, v222
	v_fmamk_f32 v17, v212, 0xbb800000, v17
	v_fmamk_f32 v1, v212, 0xbb800000, v1
	v_mul_f32_e32 v221, v17, v17
	v_fmac_f32_e32 v221, v1, v1
	v_fmamk_f32 v33, v212, 0xbb800000, v33
	v_fmac_f32_e32 v221, v33, v33
	v_fmamk_f32 v49, v212, 0xbb800000, v49
	v_fmac_f32_e32 v221, v49, v49
	v_fmamk_f32 v65, v212, 0xbb800000, v65
	v_fmac_f32_e32 v221, v65, v65
	v_fmamk_f32 v81, v212, 0xbb800000, v81
	v_fmac_f32_e32 v221, v81, v81
	v_fmamk_f32 v97, v212, 0xbb800000, v97
	v_fmac_f32_e32 v221, v97, v97
	v_fmamk_f32 v113, v212, 0xbb800000, v113
	v_fmac_f32_e32 v221, v113, v113
	v_mul_f32_e32 v80, v80, v211
	s_waitcnt vmcnt(4)
	v_mul_f32_e32 v80, v216, v80
	v_add_f32_dpp v212, v221, v221 quad_perm:[1,0,3,2] row_mask:0xf bank_mask:0xf bound_ctrl:1
	v_cvt_pk_bf16_f32 v80, v80, s0
	ds_write_b16 v32, v80 offset:320
	v_add_f32_dpp v212, v212, v212 quad_perm:[2,3,0,1] row_mask:0xf bank_mask:0xf bound_ctrl:1
	v_mul_f32_e32 v80, v96, v211
	s_waitcnt vmcnt(1)
	v_mul_f32_e32 v80, v16, v80
	v_add_f32_dpp v212, v212, v212 row_ror:4 row_mask:0xf bank_mask:0xf bound_ctrl:1
	v_cvt_pk_bf16_f32 v80, v80, s0
	ds_write_b16 v32, v80 offset:384
	v_add_f32_dpp v212, v212, v212 row_ror:8 row_mask:0xf bank_mask:0xf bound_ctrl:1
	ds_bpermute_b32 v221, v220, v212
	v_mul_f32_e32 v80, v112, v211
	s_waitcnt vmcnt(0)
	v_mul_f32_e32 v80, v0, v80
	v_cvt_pk_bf16_f32 v80, v80, s0
	ds_write_b16 v32, v80 offset:448
	s_waitcnt lgkmcnt(1)
	v_add_f32_e32 v96, v212, v221
	v_fmamk_f32 v96, v96, 0x3b800000, v48
	v_mul_f32_e32 v212, 0x4f800000, v96
	v_cmp_gt_f32_e32 vcc, s7, v96
	s_nop 1
	v_cndmask_b32_e32 v96, v96, v212, vcc
	v_sqrt_f32_e32 v212, v96
	s_nop 0
	v_add_u32_e32 v112, -1, v212
	v_fma_f32 v211, -v112, v212, v96
	v_cmp_ge_f32_e64 s[4:5], 0, v211
	v_add_u32_e32 v211, 1, v212
	s_nop 0
	v_cndmask_b32_e64 v112, v212, v112, s[4:5]
	v_fma_f32 v212, -v211, v212, v96
	v_cmp_lt_f32_e64 s[4:5], 0, v212
	s_nop 1
	v_cndmask_b32_e64 v112, v112, v211, s[4:5]
	v_mul_f32_e32 v211, 0x37800000, v112
	v_cndmask_b32_e32 v112, v112, v211, vcc
	v_cmp_class_f32_e32 vcc, v96, v64
	s_nop 1
	v_cndmask_b32_e32 v96, v112, v96, vcc
	v_div_scale_f32 v112, s[4:5], v96, v96, 1.0
	v_rcp_f32_e32 v211, v112
	s_nop 0
	v_fma_f32 v80, -v112, v211, 1.0
	v_fmac_f32_e32 v211, v80, v211
	v_div_scale_f32 v80, vcc, 1.0, v96, 1.0
	v_mul_f32_e32 v212, v80, v211
	v_fma_f32 v221, -v112, v212, v80
	v_fmac_f32_e32 v212, v221, v211
	v_fma_f32 v80, -v112, v212, v80
	v_div_fmas_f32 v80, v80, v211, v212
	v_div_fixup_f32 v80, v80, v96, 1.0
	v_mul_f32_e32 v1, v1, v80
	v_mul_f32_e32 v1, v215, v1
	v_cvt_pk_bf16_f32 v1, v1, s0
	ds_write_b16 v32, v1 offset:528
	v_mul_f32_e32 v1, v17, v80
	v_add_f32_e32 v17, 0, v2
	v_add_f32_e32 v17, v17, v18
	v_add_f32_e32 v17, v17, v34
	v_add_f32_e32 v17, v17, v50
	v_add_f32_e32 v17, v17, v66
	v_add_f32_e32 v17, v17, v82
	v_add_f32_e32 v17, v17, v98
	v_add_f32_e32 v17, v17, v114
	v_mul_f32_e32 v1, v214, v1
	v_cvt_pk_bf16_f32 v1, v1, s0
	v_add_f32_dpp v17, v17, v17 quad_perm:[1,0,3,2] row_mask:0xf bank_mask:0xf bound_ctrl:1
	ds_write_b16 v32, v1 offset:592
	v_mul_f32_e32 v1, v33, v80
	v_add_f32_dpp v17, v17, v17 quad_perm:[2,3,0,1] row_mask:0xf bank_mask:0xf bound_ctrl:1
	v_mul_f32_e32 v1, v219, v1
	v_cvt_pk_bf16_f32 v1, v1, s0
	v_add_f32_dpp v17, v17, v17 row_ror:4 row_mask:0xf bank_mask:0xf bound_ctrl:1
	ds_write_b16 v32, v1 offset:656
	v_mul_f32_e32 v1, v49, v80
	v_add_f32_dpp v17, v17, v17 row_ror:8 row_mask:0xf bank_mask:0xf bound_ctrl:1
	ds_bpermute_b32 v33, v220, v17
	v_mul_f32_e32 v1, v218, v1
	v_cvt_pk_bf16_f32 v1, v1, s0
	ds_write_b16 v32, v1 offset:720
	v_mul_f32_e32 v1, v65, v80
	s_waitcnt lgkmcnt(1)
	v_add_f32_e32 v17, v17, v33
	v_fmamk_f32 v18, v17, 0xbb800000, v18
	v_fmamk_f32 v2, v17, 0xbb800000, v2
	v_mul_f32_e32 v33, v18, v18
	v_fmac_f32_e32 v33, v2, v2
	v_fmamk_f32 v34, v17, 0xbb800000, v34
	v_fmac_f32_e32 v33, v34, v34
	v_fmamk_f32 v49, v17, 0xbb800000, v50
	v_fmac_f32_e32 v33, v49, v49
	v_fmamk_f32 v50, v17, 0xbb800000, v66
	v_fmac_f32_e32 v33, v50, v50
	v_fmamk_f32 v65, v17, 0xbb800000, v82
	v_fmac_f32_e32 v33, v65, v65
	v_fmamk_f32 v66, v17, 0xbb800000, v98
	v_fmac_f32_e32 v33, v66, v66
	v_fmamk_f32 v17, v17, 0xbb800000, v114
	v_fmac_f32_e32 v33, v17, v17
	v_mul_f32_e32 v1, v217, v1
	v_cvt_pk_bf16_f32 v1, v1, s0
	v_add_f32_dpp v33, v33, v33 quad_perm:[1,0,3,2] row_mask:0xf bank_mask:0xf bound_ctrl:1
	ds_write_b16 v32, v1 offset:784
	v_mul_f32_e32 v1, v81, v80
	v_add_f32_dpp v33, v33, v33 quad_perm:[2,3,0,1] row_mask:0xf bank_mask:0xf bound_ctrl:1
	v_mul_f32_e32 v1, v216, v1
	v_cvt_pk_bf16_f32 v1, v1, s0
	v_add_f32_dpp v33, v33, v33 row_ror:4 row_mask:0xf bank_mask:0xf bound_ctrl:1
	ds_write_b16 v32, v1 offset:848
	v_mul_f32_e32 v1, v97, v80
	v_add_f32_dpp v33, v33, v33 row_ror:8 row_mask:0xf bank_mask:0xf bound_ctrl:1
	ds_bpermute_b32 v81, v220, v33
	v_mul_f32_e32 v1, v16, v1
	v_cvt_pk_bf16_f32 v1, v1, s0
	ds_write_b16 v32, v1 offset:912
	v_mul_f32_e32 v1, v113, v80
	s_waitcnt lgkmcnt(1)
	v_add_f32_e32 v33, v33, v81
	v_fmamk_f32 v33, v33, 0x3b800000, v48
	v_mul_f32_e32 v81, 0x4f800000, v33
	v_cmp_gt_f32_e32 vcc, s7, v33
	v_mul_f32_e32 v1, v0, v1
	v_cvt_pk_bf16_f32 v1, v1, s0
	v_cndmask_b32_e32 v33, v33, v81, vcc
	v_sqrt_f32_e32 v81, v33
	ds_write_b16 v32, v1 offset:976
	v_add_u32_e32 v80, -1, v81
	v_fma_f32 v82, -v80, v81, v33
	v_cmp_ge_f32_e64 s[4:5], 0, v82
	v_add_u32_e32 v82, 1, v81
	s_nop 0
	v_cndmask_b32_e64 v80, v81, v80, s[4:5]
	v_fma_f32 v81, -v82, v81, v33
	v_cmp_lt_f32_e64 s[4:5], 0, v81
	s_nop 1
	v_cndmask_b32_e64 v80, v80, v82, s[4:5]
	v_mul_f32_e32 v81, 0x37800000, v80
	v_cndmask_b32_e32 v80, v80, v81, vcc
	v_cmp_class_f32_e32 vcc, v33, v64
	s_nop 1
	v_cndmask_b32_e32 v33, v80, v33, vcc
	v_div_scale_f32 v80, s[4:5], v33, v33, 1.0
	v_rcp_f32_e32 v81, v80
	s_nop 0
	v_fma_f32 v1, -v80, v81, 1.0
	v_fmac_f32_e32 v81, v1, v81
	v_div_scale_f32 v1, vcc, 1.0, v33, 1.0
	v_mul_f32_e32 v82, v1, v81
	v_fma_f32 v96, -v80, v82, v1
	v_fmac_f32_e32 v82, v96, v81
	v_fma_f32 v1, -v80, v82, v1
	v_div_fmas_f32 v1, v1, v81, v82
	v_div_fixup_f32 v1, v1, v33, 1.0
	v_mul_f32_e32 v2, v2, v1
	v_mul_f32_e32 v2, v215, v2
	v_cvt_pk_bf16_f32 v2, v2, s0
	ds_write_b16 v32, v2 offset:1056
	v_mul_f32_e32 v2, v18, v1
	v_add_f32_e32 v18, 0, v3
	v_add_f32_e32 v18, v18, v19
	v_add_f32_e32 v18, v18, v35
	v_add_f32_e32 v18, v18, v51
	v_add_f32_e32 v18, v18, v67
	v_add_f32_e32 v18, v18, v83
	v_add_f32_e32 v18, v18, v99
	v_add_f32_e32 v18, v18, v115
	v_mul_f32_e32 v2, v214, v2
	v_cvt_pk_bf16_f32 v2, v2, s0
	v_add_f32_dpp v18, v18, v18 quad_perm:[1,0,3,2] row_mask:0xf bank_mask:0xf bound_ctrl:1
	ds_write_b16 v32, v2 offset:1120
	v_mul_f32_e32 v2, v34, v1
	v_add_f32_dpp v18, v18, v18 quad_perm:[2,3,0,1] row_mask:0xf bank_mask:0xf bound_ctrl:1
	v_mul_f32_e32 v2, v219, v2
	v_cvt_pk_bf16_f32 v2, v2, s0
	v_add_f32_dpp v18, v18, v18 row_ror:4 row_mask:0xf bank_mask:0xf bound_ctrl:1
	ds_write_b16 v32, v2 offset:1184
	v_mul_f32_e32 v2, v49, v1
	v_add_f32_dpp v18, v18, v18 row_ror:8 row_mask:0xf bank_mask:0xf bound_ctrl:1
	ds_bpermute_b32 v33, v220, v18
	v_mul_f32_e32 v2, v218, v2
	v_cvt_pk_bf16_f32 v2, v2, s0
	ds_write_b16 v32, v2 offset:1248
	v_mul_f32_e32 v2, v50, v1
	s_waitcnt lgkmcnt(1)
	v_add_f32_e32 v18, v18, v33
	v_fmamk_f32 v19, v18, 0xbb800000, v19
	v_fmamk_f32 v3, v18, 0xbb800000, v3
	v_mul_f32_e32 v33, v19, v19
	v_fmac_f32_e32 v33, v3, v3
	v_fmamk_f32 v34, v18, 0xbb800000, v35
	v_fmac_f32_e32 v33, v34, v34
	v_fmamk_f32 v35, v18, 0xbb800000, v51
	v_fmac_f32_e32 v33, v35, v35
	v_fmamk_f32 v49, v18, 0xbb800000, v67
	v_fmac_f32_e32 v33, v49, v49
	v_fmamk_f32 v50, v18, 0xbb800000, v83
	v_fmac_f32_e32 v33, v50, v50
	v_fmamk_f32 v51, v18, 0xbb800000, v99
	v_fmac_f32_e32 v33, v51, v51
	v_fmamk_f32 v18, v18, 0xbb800000, v115
	v_fmac_f32_e32 v33, v18, v18
	v_mul_f32_e32 v2, v217, v2
	v_cvt_pk_bf16_f32 v2, v2, s0
	v_add_f32_dpp v33, v33, v33 quad_perm:[1,0,3,2] row_mask:0xf bank_mask:0xf bound_ctrl:1
	ds_write_b16 v32, v2 offset:1312
	v_mul_f32_e32 v2, v65, v1
	v_add_f32_dpp v33, v33, v33 quad_perm:[2,3,0,1] row_mask:0xf bank_mask:0xf bound_ctrl:1
	v_mul_f32_e32 v2, v216, v2
	v_cvt_pk_bf16_f32 v2, v2, s0
	v_add_f32_dpp v33, v33, v33 row_ror:4 row_mask:0xf bank_mask:0xf bound_ctrl:1
	ds_write_b16 v32, v2 offset:1376
	v_mul_f32_e32 v2, v66, v1
	v_add_f32_dpp v33, v33, v33 row_ror:8 row_mask:0xf bank_mask:0xf bound_ctrl:1
	ds_bpermute_b32 v65, v220, v33
	v_mul_f32_e32 v2, v16, v2
	v_cvt_pk_bf16_f32 v2, v2, s0
	ds_write_b16 v32, v2 offset:1440
	v_mul_f32_e32 v1, v17, v1
	s_waitcnt lgkmcnt(1)
	v_add_f32_e32 v33, v33, v65
	v_fmamk_f32 v33, v33, 0x3b800000, v48
	v_mul_f32_e32 v65, 0x4f800000, v33
	v_cmp_gt_f32_e32 vcc, s7, v33
	v_mul_f32_e32 v1, v0, v1
	v_cvt_pk_bf16_f32 v1, v1, s0
	v_cndmask_b32_e32 v33, v33, v65, vcc
	v_sqrt_f32_e32 v65, v33
	ds_write_b16 v32, v1 offset:1504
	v_add_u32_e32 v2, -1, v65
	v_fma_f32 v17, -v2, v65, v33
	v_cmp_ge_f32_e64 s[4:5], 0, v17
	v_add_u32_e32 v17, 1, v65
	s_nop 0
	v_cndmask_b32_e64 v2, v65, v2, s[4:5]
	v_fma_f32 v65, -v17, v65, v33
	v_cmp_lt_f32_e64 s[4:5], 0, v65
	s_nop 1
	v_cndmask_b32_e64 v2, v2, v17, s[4:5]
	v_mul_f32_e32 v17, 0x37800000, v2
	v_cndmask_b32_e32 v2, v2, v17, vcc
	v_cmp_class_f32_e32 vcc, v33, v64
	s_nop 1
	v_cndmask_b32_e32 v2, v2, v33, vcc
	v_div_scale_f32 v17, s[4:5], v2, v2, 1.0
	v_rcp_f32_e32 v33, v17
	s_nop 0
	v_fma_f32 v1, -v17, v33, 1.0
	v_fmac_f32_e32 v33, v1, v33
	v_div_scale_f32 v1, vcc, 1.0, v2, 1.0
	v_mul_f32_e32 v65, v1, v33
	v_fma_f32 v66, -v17, v65, v1
	v_fmac_f32_e32 v65, v66, v33
	v_fma_f32 v1, -v17, v65, v1
	v_div_fmas_f32 v1, v1, v33, v65
	v_div_fixup_f32 v1, v1, v2, 1.0
	v_mul_f32_e32 v2, v3, v1
	v_add_f32_e32 v3, 0, v4
	v_add_f32_e32 v3, v3, v20
	v_add_f32_e32 v3, v3, v36
	v_add_f32_e32 v3, v3, v52
	v_add_f32_e32 v3, v3, v68
	v_add_f32_e32 v3, v3, v84
	v_add_f32_e32 v3, v3, v100
	v_add_f32_e32 v3, v3, v116
	v_mul_f32_e32 v2, v215, v2
	v_cvt_pk_bf16_f32 v2, v2, s0
	v_add_f32_dpp v3, v3, v3 quad_perm:[1,0,3,2] row_mask:0xf bank_mask:0xf bound_ctrl:1
	ds_write_b16 v32, v2 offset:1584
	v_mul_f32_e32 v2, v19, v1
	v_add_f32_dpp v3, v3, v3 quad_perm:[2,3,0,1] row_mask:0xf bank_mask:0xf bound_ctrl:1
	v_mul_f32_e32 v2, v214, v2
	v_cvt_pk_bf16_f32 v2, v2, s0
	v_add_f32_dpp v3, v3, v3 row_ror:4 row_mask:0xf bank_mask:0xf bound_ctrl:1
	ds_write_b16 v32, v2 offset:1648
	v_mul_f32_e32 v2, v34, v1
	v_add_f32_dpp v3, v3, v3 row_ror:8 row_mask:0xf bank_mask:0xf bound_ctrl:1
	ds_bpermute_b32 v17, v220, v3
	v_mul_f32_e32 v2, v219, v2
	v_cvt_pk_bf16_f32 v2, v2, s0
	ds_write_b16 v32, v2 offset:1712
	v_mul_f32_e32 v2, v35, v1
	s_waitcnt lgkmcnt(1)
	v_add_f32_e32 v3, v3, v17
	v_fmamk_f32 v17, v3, 0xbb800000, v20
	v_fmamk_f32 v4, v3, 0xbb800000, v4
	v_mul_f32_e32 v19, v17, v17
	v_fmac_f32_e32 v19, v4, v4
	v_fmamk_f32 v20, v3, 0xbb800000, v36
	v_fmac_f32_e32 v19, v20, v20
	v_fmamk_f32 v33, v3, 0xbb800000, v52
	v_fmac_f32_e32 v19, v33, v33
	v_fmamk_f32 v34, v3, 0xbb800000, v68
	v_fmac_f32_e32 v19, v34, v34
	v_fmamk_f32 v35, v3, 0xbb800000, v84
	v_fmac_f32_e32 v19, v35, v35
	v_fmamk_f32 v36, v3, 0xbb800000, v100
	v_fmac_f32_e32 v19, v36, v36
	v_fmamk_f32 v3, v3, 0xbb800000, v116
	v_fmac_f32_e32 v19, v3, v3
	v_mul_f32_e32 v2, v218, v2
	v_cvt_pk_bf16_f32 v2, v2, s0
	v_add_f32_dpp v19, v19, v19 quad_perm:[1,0,3,2] row_mask:0xf bank_mask:0xf bound_ctrl:1
	ds_write_b16 v32, v2 offset:1776
	v_mul_f32_e32 v2, v49, v1
	v_add_f32_dpp v19, v19, v19 quad_perm:[2,3,0,1] row_mask:0xf bank_mask:0xf bound_ctrl:1
	v_mul_f32_e32 v2, v217, v2
	v_cvt_pk_bf16_f32 v2, v2, s0
	v_add_f32_dpp v19, v19, v19 row_ror:4 row_mask:0xf bank_mask:0xf bound_ctrl:1
	ds_write_b16 v32, v2 offset:1840
	v_mul_f32_e32 v2, v50, v1
	v_add_f32_dpp v19, v19, v19 row_ror:8 row_mask:0xf bank_mask:0xf bound_ctrl:1
	ds_bpermute_b32 v49, v220, v19
	v_mul_f32_e32 v2, v216, v2
	v_cvt_pk_bf16_f32 v2, v2, s0
	ds_write_b16 v32, v2 offset:1904
	v_mul_f32_e32 v2, v51, v1
	s_waitcnt lgkmcnt(1)
	v_add_f32_e32 v19, v19, v49
	v_fmamk_f32 v19, v19, 0x3b800000, v48
	v_mul_f32_e32 v49, 0x4f800000, v19
	v_cmp_gt_f32_e32 vcc, s7, v19
	v_mul_f32_e32 v2, v16, v2
	v_cvt_pk_bf16_f32 v2, v2, s0
	v_cndmask_b32_e32 v19, v19, v49, vcc
	v_sqrt_f32_e32 v49, v19
	ds_write_b16 v32, v2 offset:1968
	v_mul_f32_e32 v1, v18, v1
	v_mul_f32_e32 v1, v0, v1
	v_add_u32_e32 v2, -1, v49
	v_fma_f32 v18, -v2, v49, v19
	v_cmp_ge_f32_e64 s[4:5], 0, v18
	v_add_u32_e32 v18, 1, v49
	v_cvt_pk_bf16_f32 v1, v1, s0
	v_cndmask_b32_e64 v2, v49, v2, s[4:5]
	v_fma_f32 v49, -v18, v49, v19
	v_cmp_lt_f32_e64 s[4:5], 0, v49
	ds_write_b16 v32, v1 offset:2032
	s_nop 0
	v_cndmask_b32_e64 v2, v2, v18, s[4:5]
	v_mul_f32_e32 v18, 0x37800000, v2
	v_cndmask_b32_e32 v2, v2, v18, vcc
	v_cmp_class_f32_e32 vcc, v19, v64
	s_nop 1
	v_cndmask_b32_e32 v2, v2, v19, vcc
	v_div_scale_f32 v18, s[4:5], v2, v2, 1.0
	v_rcp_f32_e32 v19, v18
	s_nop 0
	v_fma_f32 v1, -v18, v19, 1.0
	v_fmac_f32_e32 v19, v1, v19
	v_div_scale_f32 v1, vcc, 1.0, v2, 1.0
	v_mul_f32_e32 v49, v1, v19
	v_fma_f32 v50, -v18, v49, v1
	v_fmac_f32_e32 v49, v50, v19
	v_fma_f32 v1, -v18, v49, v1
	v_div_fmas_f32 v1, v1, v19, v49
	v_div_fixup_f32 v1, v1, v2, 1.0
	v_mul_f32_e32 v2, v4, v1
	v_add_f32_e32 v4, 0, v5
	v_add_f32_e32 v4, v4, v21
	v_add_f32_e32 v4, v4, v37
	v_add_f32_e32 v4, v4, v53
	v_add_f32_e32 v4, v4, v69
	v_add_f32_e32 v4, v4, v85
	v_add_f32_e32 v4, v4, v101
	v_add_f32_e32 v4, v4, v117
	v_mul_f32_e32 v2, v215, v2
	v_cvt_pk_bf16_f32 v2, v2, s0
	v_add_f32_dpp v4, v4, v4 quad_perm:[1,0,3,2] row_mask:0xf bank_mask:0xf bound_ctrl:1
	ds_write_b16 v32, v2 offset:4224
	v_mul_f32_e32 v2, v17, v1
	v_add_f32_dpp v4, v4, v4 quad_perm:[2,3,0,1] row_mask:0xf bank_mask:0xf bound_ctrl:1
	v_mul_f32_e32 v2, v214, v2
	v_cvt_pk_bf16_f32 v2, v2, s0
	v_add_f32_dpp v4, v4, v4 row_ror:4 row_mask:0xf bank_mask:0xf bound_ctrl:1
	ds_write_b16 v32, v2 offset:4288
	v_mul_f32_e32 v2, v20, v1
	v_add_f32_dpp v4, v4, v4 row_ror:8 row_mask:0xf bank_mask:0xf bound_ctrl:1
	ds_bpermute_b32 v17, v220, v4
	v_mul_f32_e32 v2, v219, v2
	v_cvt_pk_bf16_f32 v2, v2, s0
	ds_write_b16 v32, v2 offset:4352
	v_mul_f32_e32 v2, v33, v1
	s_waitcnt lgkmcnt(1)
	v_add_f32_e32 v4, v4, v17
	v_fmamk_f32 v17, v4, 0xbb800000, v21
	v_fmamk_f32 v5, v4, 0xbb800000, v5
	v_mul_f32_e32 v18, v17, v17
	v_fmac_f32_e32 v18, v5, v5
	v_fmamk_f32 v19, v4, 0xbb800000, v37
	v_fmac_f32_e32 v18, v19, v19
	v_fmamk_f32 v20, v4, 0xbb800000, v53
	v_mul_f32_e32 v2, v218, v2
	v_fmac_f32_e32 v18, v20, v20
	v_fmamk_f32 v21, v4, 0xbb800000, v69
	v_cvt_pk_bf16_f32 v2, v2, s0
	v_fmac_f32_e32 v18, v21, v21
	v_fmamk_f32 v33, v4, 0xbb800000, v85
	ds_write_b16 v32, v2 offset:4416
	v_mul_f32_e32 v2, v34, v1
	v_fmac_f32_e32 v18, v33, v33
	v_fmamk_f32 v34, v4, 0xbb800000, v101
	v_fmac_f32_e32 v18, v34, v34
	v_fmamk_f32 v4, v4, 0xbb800000, v117
	v_fmac_f32_e32 v18, v4, v4
	v_mul_f32_e32 v2, v217, v2
	v_cvt_pk_bf16_f32 v2, v2, s0
	v_add_f32_dpp v18, v18, v18 quad_perm:[1,0,3,2] row_mask:0xf bank_mask:0xf bound_ctrl:1
	ds_write_b16 v32, v2 offset:4480
	v_mul_f32_e32 v2, v35, v1
	v_add_f32_dpp v18, v18, v18 quad_perm:[2,3,0,1] row_mask:0xf bank_mask:0xf bound_ctrl:1
	v_mul_f32_e32 v2, v216, v2
	v_cvt_pk_bf16_f32 v2, v2, s0
	v_add_f32_dpp v18, v18, v18 row_ror:4 row_mask:0xf bank_mask:0xf bound_ctrl:1
	ds_write_b16 v32, v2 offset:4544
	v_mul_f32_e32 v2, v36, v1
	v_add_f32_dpp v18, v18, v18 row_ror:8 row_mask:0xf bank_mask:0xf bound_ctrl:1
	ds_bpermute_b32 v35, v220, v18
	v_mul_f32_e32 v2, v16, v2
	v_cvt_pk_bf16_f32 v2, v2, s0
	ds_write_b16 v32, v2 offset:4608
	v_mul_f32_e32 v1, v3, v1
	s_waitcnt lgkmcnt(1)
	v_add_f32_e32 v18, v18, v35
	v_fmamk_f32 v18, v18, 0x3b800000, v48
	v_mul_f32_e32 v35, 0x4f800000, v18
	v_cmp_gt_f32_e32 vcc, s7, v18
	v_mul_f32_e32 v1, v0, v1
	v_cvt_pk_bf16_f32 v1, v1, s0
	v_cndmask_b32_e32 v18, v18, v35, vcc
	v_sqrt_f32_e32 v35, v18
	ds_write_b16 v32, v1 offset:4672
	v_add_u32_e32 v2, -1, v35
	v_fma_f32 v3, -v2, v35, v18
	v_cmp_ge_f32_e64 s[4:5], 0, v3
	v_add_u32_e32 v3, 1, v35
	s_nop 0
	v_cndmask_b32_e64 v2, v35, v2, s[4:5]
	v_fma_f32 v35, -v3, v35, v18
	v_cmp_lt_f32_e64 s[4:5], 0, v35
	s_nop 1
	v_cndmask_b32_e64 v2, v2, v3, s[4:5]
	v_mul_f32_e32 v3, 0x37800000, v2
	v_cndmask_b32_e32 v2, v2, v3, vcc
	v_cmp_class_f32_e32 vcc, v18, v64
	s_nop 1
	v_cndmask_b32_e32 v2, v2, v18, vcc
	v_div_scale_f32 v3, s[4:5], v2, v2, 1.0
	v_rcp_f32_e32 v18, v3
	s_nop 0
	v_fma_f32 v1, -v3, v18, 1.0
	v_fmac_f32_e32 v18, v1, v18
	v_div_scale_f32 v1, vcc, 1.0, v2, 1.0
	v_mul_f32_e32 v35, v1, v18
	v_fma_f32 v36, -v3, v35, v1
	v_fmac_f32_e32 v35, v36, v18
	v_fma_f32 v1, -v3, v35, v1
	v_add_f32_e32 v3, 0, v6
	v_add_f32_e32 v3, v3, v22
	v_add_f32_e32 v3, v3, v38
	v_add_f32_e32 v3, v3, v54
	v_add_f32_e32 v3, v3, v70
	v_add_f32_e32 v3, v3, v86
	v_add_f32_e32 v3, v3, v102
	v_add_f32_e32 v3, v3, v118
	v_div_fmas_f32 v1, v1, v18, v35
	v_div_fixup_f32 v1, v1, v2, 1.0
	v_add_f32_dpp v3, v3, v3 quad_perm:[1,0,3,2] row_mask:0xf bank_mask:0xf bound_ctrl:1
	v_mul_f32_e32 v2, v5, v1
	v_mul_f32_e32 v2, v215, v2
	v_add_f32_dpp v3, v3, v3 quad_perm:[2,3,0,1] row_mask:0xf bank_mask:0xf bound_ctrl:1
	v_cvt_pk_bf16_f32 v2, v2, s0
	ds_write_b16 v32, v2 offset:4752
	v_add_f32_dpp v3, v3, v3 row_ror:4 row_mask:0xf bank_mask:0xf bound_ctrl:1
	v_mul_f32_e32 v2, v17, v1
	v_mul_f32_e32 v2, v214, v2
	v_add_f32_dpp v3, v3, v3 row_ror:8 row_mask:0xf bank_mask:0xf bound_ctrl:1
	ds_bpermute_b32 v5, v220, v3
	v_cvt_pk_bf16_f32 v2, v2, s0
	ds_write_b16 v32, v2 offset:4816
	v_mul_f32_e32 v2, v19, v1
	v_mul_f32_e32 v2, v219, v2
	s_waitcnt lgkmcnt(1)
	v_add_f32_e32 v3, v3, v5
	v_fmamk_f32 v5, v3, 0xbb800000, v6
	v_fmamk_f32 v6, v3, 0xbb800000, v22
	v_cvt_pk_bf16_f32 v2, v2, s0
	v_mul_f32_e32 v17, v6, v6
	ds_write_b16 v32, v2 offset:4880
	v_mul_f32_e32 v2, v20, v1
	v_fmac_f32_e32 v17, v5, v5
	v_fmamk_f32 v18, v3, 0xbb800000, v38
	v_mul_f32_e32 v2, v218, v2
	v_fmac_f32_e32 v17, v18, v18
	v_fmamk_f32 v19, v3, 0xbb800000, v54
	v_cvt_pk_bf16_f32 v2, v2, s0
	v_fmac_f32_e32 v17, v19, v19
	v_fmamk_f32 v20, v3, 0xbb800000, v70
	ds_write_b16 v32, v2 offset:4944
	v_mul_f32_e32 v2, v21, v1
	v_fmac_f32_e32 v17, v20, v20
	v_fmamk_f32 v21, v3, 0xbb800000, v86
	v_fmac_f32_e32 v17, v21, v21
	v_fmamk_f32 v22, v3, 0xbb800000, v102
	v_fmac_f32_e32 v17, v22, v22
	v_fmamk_f32 v3, v3, 0xbb800000, v118
	v_fmac_f32_e32 v17, v3, v3
	v_mul_f32_e32 v2, v217, v2
	v_cvt_pk_bf16_f32 v2, v2, s0
	v_add_f32_dpp v17, v17, v17 quad_perm:[1,0,3,2] row_mask:0xf bank_mask:0xf bound_ctrl:1
	ds_write_b16 v32, v2 offset:5008
	v_mul_f32_e32 v2, v33, v1
	v_add_f32_dpp v17, v17, v17 quad_perm:[2,3,0,1] row_mask:0xf bank_mask:0xf bound_ctrl:1
	v_mul_f32_e32 v2, v216, v2
	v_cvt_pk_bf16_f32 v2, v2, s0
	v_add_f32_dpp v17, v17, v17 row_ror:4 row_mask:0xf bank_mask:0xf bound_ctrl:1
	ds_write_b16 v32, v2 offset:5072
	v_mul_f32_e32 v2, v34, v1
	v_add_f32_dpp v17, v17, v17 row_ror:8 row_mask:0xf bank_mask:0xf bound_ctrl:1
	ds_bpermute_b32 v33, v220, v17
	v_mul_f32_e32 v2, v16, v2
	v_cvt_pk_bf16_f32 v2, v2, s0
	ds_write_b16 v32, v2 offset:5136
	v_mul_f32_e32 v1, v4, v1
	s_waitcnt lgkmcnt(1)
	v_add_f32_e32 v17, v17, v33
	v_fmamk_f32 v17, v17, 0x3b800000, v48
	v_mul_f32_e32 v33, 0x4f800000, v17
	v_cmp_gt_f32_e32 vcc, s7, v17
	v_mul_f32_e32 v1, v0, v1
	v_cvt_pk_bf16_f32 v1, v1, s0
	v_cndmask_b32_e32 v17, v17, v33, vcc
	v_sqrt_f32_e32 v33, v17
	ds_write_b16 v32, v1 offset:5200
	v_add_u32_e32 v2, -1, v33
	v_fma_f32 v4, -v2, v33, v17
	v_cmp_ge_f32_e64 s[4:5], 0, v4
	v_add_u32_e32 v4, 1, v33
	s_nop 0
	v_cndmask_b32_e64 v2, v33, v2, s[4:5]
	v_fma_f32 v33, -v4, v33, v17
	v_cmp_lt_f32_e64 s[4:5], 0, v33
	s_nop 1
	v_cndmask_b32_e64 v2, v2, v4, s[4:5]
	v_mul_f32_e32 v4, 0x37800000, v2
	v_cndmask_b32_e32 v2, v2, v4, vcc
	v_cmp_class_f32_e32 vcc, v17, v64
	s_nop 1
	v_cndmask_b32_e32 v2, v2, v17, vcc
	v_div_scale_f32 v4, s[4:5], v2, v2, 1.0
	v_rcp_f32_e32 v17, v4
	s_nop 0
	v_fma_f32 v1, -v4, v17, 1.0
	v_fmac_f32_e32 v17, v1, v17
	v_div_scale_f32 v1, vcc, 1.0, v2, 1.0
	v_mul_f32_e32 v33, v1, v17
	v_fma_f32 v34, -v4, v33, v1
	v_fmac_f32_e32 v33, v34, v17
	v_fma_f32 v1, -v4, v33, v1
	v_add_f32_e32 v4, 0, v7
	v_add_f32_e32 v4, v4, v23
	v_add_f32_e32 v4, v4, v39
	v_add_f32_e32 v4, v4, v55
	v_add_f32_e32 v4, v4, v71
	v_add_f32_e32 v4, v4, v87
	v_add_f32_e32 v4, v4, v103
	v_div_fmas_f32 v1, v1, v17, v33
	v_add_f32_e32 v4, v4, v119
	v_div_fixup_f32 v1, v1, v2, 1.0
	v_mul_f32_e32 v2, v5, v1
	v_add_f32_dpp v4, v4, v4 quad_perm:[1,0,3,2] row_mask:0xf bank_mask:0xf bound_ctrl:1
	v_mul_f32_e32 v2, v215, v2
	v_cvt_pk_bf16_f32 v2, v2, s0
	v_add_f32_dpp v4, v4, v4 quad_perm:[2,3,0,1] row_mask:0xf bank_mask:0xf bound_ctrl:1
	ds_write_b16 v32, v2 offset:5280
	v_mul_f32_e32 v2, v6, v1
	v_add_f32_dpp v4, v4, v4 row_ror:4 row_mask:0xf bank_mask:0xf bound_ctrl:1
	v_mul_f32_e32 v2, v214, v2
	v_cvt_pk_bf16_f32 v2, v2, s0
	v_add_f32_dpp v4, v4, v4 row_ror:8 row_mask:0xf bank_mask:0xf bound_ctrl:1
	ds_bpermute_b32 v5, v220, v4
	ds_write_b16 v32, v2 offset:5344
	v_mul_f32_e32 v2, v18, v1
	v_mul_f32_e32 v2, v219, v2
	v_cvt_pk_bf16_f32 v2, v2, s0
	s_waitcnt lgkmcnt(1)
	v_add_f32_e32 v4, v4, v5
	ds_write_b16 v32, v2 offset:5408
	v_mul_f32_e32 v2, v19, v1
	v_fmamk_f32 v6, v4, 0xbb800000, v23
	v_mul_f32_e32 v2, v218, v2
	v_fmamk_f32 v5, v4, 0xbb800000, v7
	v_mul_f32_e32 v7, v6, v6
	v_cvt_pk_bf16_f32 v2, v2, s0
	v_fmac_f32_e32 v7, v5, v5
	v_fmamk_f32 v17, v4, 0xbb800000, v39
	ds_write_b16 v32, v2 offset:5472
	v_mul_f32_e32 v2, v20, v1
	v_fmac_f32_e32 v7, v17, v17
	v_fmamk_f32 v18, v4, 0xbb800000, v55
	v_mul_f32_e32 v2, v217, v2
	v_fmac_f32_e32 v7, v18, v18
	v_fmamk_f32 v19, v4, 0xbb800000, v71
	v_cvt_pk_bf16_f32 v2, v2, s0
	v_fmac_f32_e32 v7, v19, v19
	v_fmamk_f32 v20, v4, 0xbb800000, v87
	ds_write_b16 v32, v2 offset:5536
	v_mul_f32_e32 v2, v21, v1
	v_fmac_f32_e32 v7, v20, v20
	v_fmamk_f32 v21, v4, 0xbb800000, v103
	v_fmac_f32_e32 v7, v21, v21
	v_fmamk_f32 v4, v4, 0xbb800000, v119
	v_fmac_f32_e32 v7, v4, v4
	v_mul_f32_e32 v2, v216, v2
	v_cvt_pk_bf16_f32 v2, v2, s0
	v_add_f32_dpp v7, v7, v7 quad_perm:[1,0,3,2] row_mask:0xf bank_mask:0xf bound_ctrl:1
	ds_write_b16 v32, v2 offset:5600
	v_mul_f32_e32 v2, v22, v1
	v_add_f32_dpp v7, v7, v7 quad_perm:[2,3,0,1] row_mask:0xf bank_mask:0xf bound_ctrl:1
	v_mul_f32_e32 v2, v16, v2
	v_cvt_pk_bf16_f32 v2, v2, s0
	v_add_f32_dpp v7, v7, v7 row_ror:4 row_mask:0xf bank_mask:0xf bound_ctrl:1
	ds_write_b16 v32, v2 offset:5664
	v_mul_f32_e32 v1, v3, v1
	v_add_f32_dpp v7, v7, v7 row_ror:8 row_mask:0xf bank_mask:0xf bound_ctrl:1
	ds_bpermute_b32 v23, v220, v7
	v_mul_f32_e32 v1, v0, v1
	v_cvt_pk_bf16_f32 v1, v1, s0
	ds_write_b16 v32, v1 offset:5728
	s_waitcnt lgkmcnt(1)
	v_add_f32_e32 v7, v7, v23
	v_fmamk_f32 v7, v7, 0x3b800000, v48
	v_mul_f32_e32 v22, 0x4f800000, v7
	v_cmp_gt_f32_e32 vcc, s7, v7
	s_nop 1
	v_cndmask_b32_e32 v7, v7, v22, vcc
	v_sqrt_f32_e32 v22, v7
	s_nop 0
	v_add_u32_e32 v2, -1, v22
	v_fma_f32 v3, -v2, v22, v7
	v_cmp_ge_f32_e64 s[4:5], 0, v3
	v_add_u32_e32 v3, 1, v22
	s_nop 0
	v_cndmask_b32_e64 v2, v22, v2, s[4:5]
	v_fma_f32 v22, -v3, v22, v7
	v_cmp_lt_f32_e64 s[4:5], 0, v22
	s_nop 1
	v_cndmask_b32_e64 v2, v2, v3, s[4:5]
	v_mul_f32_e32 v3, 0x37800000, v2
	v_cndmask_b32_e32 v2, v2, v3, vcc
	v_cmp_class_f32_e32 vcc, v7, v64
	s_nop 1
	v_cndmask_b32_e32 v2, v2, v7, vcc
	v_div_scale_f32 v3, s[4:5], v2, v2, 1.0
	v_rcp_f32_e32 v7, v3
	s_nop 0
	v_fma_f32 v1, -v3, v7, 1.0
	v_fmac_f32_e32 v7, v1, v7
	v_div_scale_f32 v1, vcc, 1.0, v2, 1.0
	v_mul_f32_e32 v22, v1, v7
	v_fma_f32 v23, -v3, v22, v1
	v_fmac_f32_e32 v22, v23, v7
	v_fma_f32 v1, -v3, v22, v1
	v_add_f32_e32 v3, 0, v8
	v_add_f32_e32 v3, v3, v24
	v_add_f32_e32 v3, v3, v40
	v_add_f32_e32 v3, v3, v56
	v_add_f32_e32 v3, v3, v72
	v_add_f32_e32 v3, v3, v88
	v_add_f32_e32 v3, v3, v104
	v_div_fmas_f32 v1, v1, v7, v22
	v_add_f32_e32 v3, v3, v120
	v_div_fixup_f32 v1, v1, v2, 1.0
	v_mul_f32_e32 v2, v5, v1
	v_add_f32_dpp v3, v3, v3 quad_perm:[1,0,3,2] row_mask:0xf bank_mask:0xf bound_ctrl:1
	v_mul_f32_e32 v2, v215, v2
	v_cvt_pk_bf16_f32 v2, v2, s0
	v_add_f32_dpp v3, v3, v3 quad_perm:[2,3,0,1] row_mask:0xf bank_mask:0xf bound_ctrl:1
	ds_write_b16 v32, v2 offset:5808
	v_mul_f32_e32 v2, v6, v1
	v_add_f32_dpp v3, v3, v3 row_ror:4 row_mask:0xf bank_mask:0xf bound_ctrl:1
	v_mul_f32_e32 v2, v214, v2
	v_cvt_pk_bf16_f32 v2, v2, s0
	v_add_f32_dpp v3, v3, v3 row_ror:8 row_mask:0xf bank_mask:0xf bound_ctrl:1
	ds_bpermute_b32 v5, v220, v3
	ds_write_b16 v32, v2 offset:5872
	v_mul_f32_e32 v2, v17, v1
	v_mul_f32_e32 v2, v219, v2
	v_cvt_pk_bf16_f32 v2, v2, s0
	s_waitcnt lgkmcnt(1)
	v_add_f32_e32 v3, v3, v5
	ds_write_b16 v32, v2 offset:5936
	v_mul_f32_e32 v2, v18, v1
	v_fmamk_f32 v6, v3, 0xbb800000, v24
	v_mul_f32_e32 v2, v218, v2
	v_fmamk_f32 v5, v3, 0xbb800000, v8
	v_mul_f32_e32 v7, v6, v6
	v_cvt_pk_bf16_f32 v2, v2, s0
	v_fmac_f32_e32 v7, v5, v5
	v_fmamk_f32 v8, v3, 0xbb800000, v40
	ds_write_b16 v32, v2 offset:6000
	v_mul_f32_e32 v2, v19, v1
	v_fmac_f32_e32 v7, v8, v8
	v_fmamk_f32 v17, v3, 0xbb800000, v56
	v_mul_f32_e32 v2, v217, v2
	v_fmac_f32_e32 v7, v17, v17
	v_fmamk_f32 v18, v3, 0xbb800000, v72
	v_cvt_pk_bf16_f32 v2, v2, s0
	v_fmac_f32_e32 v7, v18, v18
	v_fmamk_f32 v19, v3, 0xbb800000, v88
	ds_write_b16 v32, v2 offset:6064
	v_mul_f32_e32 v2, v20, v1
	v_fmac_f32_e32 v7, v19, v19
	v_fmamk_f32 v20, v3, 0xbb800000, v104
	v_fmac_f32_e32 v7, v20, v20
	v_fmamk_f32 v3, v3, 0xbb800000, v120
	v_fmac_f32_e32 v7, v3, v3
	v_mul_f32_e32 v2, v216, v2
	v_cvt_pk_bf16_f32 v2, v2, s0
	v_add_f32_dpp v7, v7, v7 quad_perm:[1,0,3,2] row_mask:0xf bank_mask:0xf bound_ctrl:1
	ds_write_b16 v32, v2 offset:6128
	v_mul_f32_e32 v2, v21, v1
	v_add_f32_dpp v7, v7, v7 quad_perm:[2,3,0,1] row_mask:0xf bank_mask:0xf bound_ctrl:1
	v_mul_f32_e32 v2, v16, v2
	v_cvt_pk_bf16_f32 v2, v2, s0
	v_add_f32_dpp v7, v7, v7 row_ror:4 row_mask:0xf bank_mask:0xf bound_ctrl:1
	ds_write_b16 v32, v2 offset:6192
	v_mul_f32_e32 v1, v4, v1
	v_add_f32_dpp v7, v7, v7 row_ror:8 row_mask:0xf bank_mask:0xf bound_ctrl:1
	ds_bpermute_b32 v22, v220, v7
	v_mul_f32_e32 v1, v0, v1
	v_cvt_pk_bf16_f32 v1, v1, s0
	ds_write_b16 v32, v1 offset:6256
	s_waitcnt lgkmcnt(1)
	v_add_f32_e32 v7, v7, v22
	v_fmamk_f32 v7, v7, 0x3b800000, v48
	v_mul_f32_e32 v21, 0x4f800000, v7
	v_cmp_gt_f32_e32 vcc, s7, v7
	s_nop 1
	v_cndmask_b32_e32 v7, v7, v21, vcc
	v_sqrt_f32_e32 v21, v7
	s_nop 0
	v_add_u32_e32 v2, -1, v21
	v_fma_f32 v4, -v2, v21, v7
	v_cmp_ge_f32_e64 s[4:5], 0, v4
	v_add_u32_e32 v4, 1, v21
	s_nop 0
	v_cndmask_b32_e64 v2, v21, v2, s[4:5]
	v_fma_f32 v21, -v4, v21, v7
	v_cmp_lt_f32_e64 s[4:5], 0, v21
	s_nop 1
	v_cndmask_b32_e64 v2, v2, v4, s[4:5]
	v_mul_f32_e32 v4, 0x37800000, v2
	v_cndmask_b32_e32 v2, v2, v4, vcc
	v_cmp_class_f32_e32 vcc, v7, v64
	s_nop 1
	v_cndmask_b32_e32 v2, v2, v7, vcc
	v_div_scale_f32 v4, s[4:5], v2, v2, 1.0
	v_rcp_f32_e32 v7, v4
	s_nop 0
	v_fma_f32 v1, -v4, v7, 1.0
	v_fmac_f32_e32 v7, v1, v7
	v_div_scale_f32 v1, vcc, 1.0, v2, 1.0
	v_mul_f32_e32 v21, v1, v7
	v_fma_f32 v22, -v4, v21, v1
	v_fmac_f32_e32 v21, v22, v7
	v_fma_f32 v1, -v4, v21, v1
	v_add_f32_e32 v4, 0, v9
	v_add_f32_e32 v4, v4, v25
	v_add_f32_e32 v4, v4, v41
	v_add_f32_e32 v4, v4, v57
	v_add_f32_e32 v4, v4, v73
	v_add_f32_e32 v4, v4, v89
	v_add_f32_e32 v4, v4, v105
	v_div_fmas_f32 v1, v1, v7, v21
	v_add_f32_e32 v4, v4, v121
	v_div_fixup_f32 v1, v1, v2, 1.0
	v_mul_f32_e32 v2, v5, v1
	v_add_f32_dpp v4, v4, v4 quad_perm:[1,0,3,2] row_mask:0xf bank_mask:0xf bound_ctrl:1
	v_mul_f32_e32 v2, v215, v2
	v_cvt_pk_bf16_f32 v2, v2, s0
	v_add_f32_dpp v4, v4, v4 quad_perm:[2,3,0,1] row_mask:0xf bank_mask:0xf bound_ctrl:1
	ds_write_b16 v32, v2 offset:8448
	v_mul_f32_e32 v2, v6, v1
	v_add_f32_dpp v4, v4, v4 row_ror:4 row_mask:0xf bank_mask:0xf bound_ctrl:1
	v_mul_f32_e32 v2, v214, v2
	v_cvt_pk_bf16_f32 v2, v2, s0
	v_add_f32_dpp v4, v4, v4 row_ror:8 row_mask:0xf bank_mask:0xf bound_ctrl:1
	ds_bpermute_b32 v5, v220, v4
	ds_write_b16 v32, v2 offset:8512
	v_mul_f32_e32 v2, v8, v1
	v_mul_f32_e32 v2, v219, v2
	v_cvt_pk_bf16_f32 v2, v2, s0
	s_waitcnt lgkmcnt(1)
	v_add_f32_e32 v4, v4, v5
	ds_write_b16 v32, v2 offset:8576
	v_mul_f32_e32 v2, v17, v1
	v_fmamk_f32 v6, v4, 0xbb800000, v25
	v_mul_f32_e32 v2, v218, v2
	v_fmamk_f32 v5, v4, 0xbb800000, v9
	v_mul_f32_e32 v7, v6, v6
	v_cvt_pk_bf16_f32 v2, v2, s0
	v_fmac_f32_e32 v7, v5, v5
	v_fmamk_f32 v8, v4, 0xbb800000, v41
	ds_write_b16 v32, v2 offset:8640
	v_mul_f32_e32 v2, v18, v1
	v_fmac_f32_e32 v7, v8, v8
	v_fmamk_f32 v9, v4, 0xbb800000, v57
	v_mul_f32_e32 v2, v217, v2
	v_fmac_f32_e32 v7, v9, v9
	v_fmamk_f32 v17, v4, 0xbb800000, v73
	v_cvt_pk_bf16_f32 v2, v2, s0
	v_fmac_f32_e32 v7, v17, v17
	v_fmamk_f32 v18, v4, 0xbb800000, v89
	ds_write_b16 v32, v2 offset:8704
	v_mul_f32_e32 v2, v19, v1
	v_fmac_f32_e32 v7, v18, v18
	v_fmamk_f32 v19, v4, 0xbb800000, v105
	v_fmac_f32_e32 v7, v19, v19
	v_fmamk_f32 v4, v4, 0xbb800000, v121
	v_fmac_f32_e32 v7, v4, v4
	v_mul_f32_e32 v2, v216, v2
	v_cvt_pk_bf16_f32 v2, v2, s0
	v_add_f32_dpp v7, v7, v7 quad_perm:[1,0,3,2] row_mask:0xf bank_mask:0xf bound_ctrl:1
	ds_write_b16 v32, v2 offset:8768
	v_mul_f32_e32 v2, v20, v1
	v_add_f32_dpp v7, v7, v7 quad_perm:[2,3,0,1] row_mask:0xf bank_mask:0xf bound_ctrl:1
	v_mul_f32_e32 v2, v16, v2
	v_cvt_pk_bf16_f32 v2, v2, s0
	v_add_f32_dpp v7, v7, v7 row_ror:4 row_mask:0xf bank_mask:0xf bound_ctrl:1
	ds_write_b16 v32, v2 offset:8832
	v_mul_f32_e32 v1, v3, v1
	v_add_f32_dpp v7, v7, v7 row_ror:8 row_mask:0xf bank_mask:0xf bound_ctrl:1
	ds_bpermute_b32 v21, v220, v7
	v_mul_f32_e32 v1, v0, v1
	v_cvt_pk_bf16_f32 v1, v1, s0
	ds_write_b16 v32, v1 offset:8896
	s_waitcnt lgkmcnt(1)
	v_add_f32_e32 v7, v7, v21
	v_fmamk_f32 v7, v7, 0x3b800000, v48
	v_mul_f32_e32 v20, 0x4f800000, v7
	v_cmp_gt_f32_e32 vcc, s7, v7
	s_nop 1
	v_cndmask_b32_e32 v7, v7, v20, vcc
	v_sqrt_f32_e32 v20, v7
	s_nop 0
	v_add_u32_e32 v2, -1, v20
	v_fma_f32 v3, -v2, v20, v7
	v_cmp_ge_f32_e64 s[4:5], 0, v3
	v_add_u32_e32 v3, 1, v20
	s_nop 0
	v_cndmask_b32_e64 v2, v20, v2, s[4:5]
	v_fma_f32 v20, -v3, v20, v7
	v_cmp_lt_f32_e64 s[4:5], 0, v20
	s_nop 1
	v_cndmask_b32_e64 v2, v2, v3, s[4:5]
	v_mul_f32_e32 v3, 0x37800000, v2
	v_cndmask_b32_e32 v2, v2, v3, vcc
	v_cmp_class_f32_e32 vcc, v7, v64
	s_nop 1
	v_cndmask_b32_e32 v2, v2, v7, vcc
	v_div_scale_f32 v3, s[4:5], v2, v2, 1.0
	v_rcp_f32_e32 v7, v3
	s_nop 0
	v_fma_f32 v1, -v3, v7, 1.0
	v_fmac_f32_e32 v7, v1, v7
	v_div_scale_f32 v1, vcc, 1.0, v2, 1.0
	v_mul_f32_e32 v20, v1, v7
	v_fma_f32 v21, -v3, v20, v1
	v_fmac_f32_e32 v20, v21, v7
	v_fma_f32 v1, -v3, v20, v1
	v_add_f32_e32 v3, 0, v10
	v_add_f32_e32 v3, v3, v26
	v_add_f32_e32 v3, v3, v42
	v_add_f32_e32 v3, v3, v58
	v_add_f32_e32 v3, v3, v74
	v_add_f32_e32 v3, v3, v90
	v_add_f32_e32 v3, v3, v106
	v_div_fmas_f32 v1, v1, v7, v20
	v_add_f32_e32 v3, v3, v122
	v_div_fixup_f32 v1, v1, v2, 1.0
	v_mul_f32_e32 v2, v5, v1
	v_add_f32_dpp v3, v3, v3 quad_perm:[1,0,3,2] row_mask:0xf bank_mask:0xf bound_ctrl:1
	v_mul_f32_e32 v2, v215, v2
	v_cvt_pk_bf16_f32 v2, v2, s0
	v_add_f32_dpp v3, v3, v3 quad_perm:[2,3,0,1] row_mask:0xf bank_mask:0xf bound_ctrl:1
	ds_write_b16 v32, v2 offset:8976
	v_mul_f32_e32 v2, v6, v1
	v_add_f32_dpp v3, v3, v3 row_ror:4 row_mask:0xf bank_mask:0xf bound_ctrl:1
	v_mul_f32_e32 v2, v214, v2
	v_cvt_pk_bf16_f32 v2, v2, s0
	v_add_f32_dpp v3, v3, v3 row_ror:8 row_mask:0xf bank_mask:0xf bound_ctrl:1
	ds_bpermute_b32 v5, v220, v3
	ds_write_b16 v32, v2 offset:9040
	v_mul_f32_e32 v2, v8, v1
	v_mul_f32_e32 v2, v219, v2
	v_cvt_pk_bf16_f32 v2, v2, s0
	s_waitcnt lgkmcnt(1)
	v_add_f32_e32 v3, v3, v5
	ds_write_b16 v32, v2 offset:9104
	v_mul_f32_e32 v2, v9, v1
	v_fmamk_f32 v6, v3, 0xbb800000, v26
	v_mul_f32_e32 v2, v218, v2
	v_fmamk_f32 v5, v3, 0xbb800000, v10
	v_mul_f32_e32 v7, v6, v6
	v_cvt_pk_bf16_f32 v2, v2, s0
	v_fmac_f32_e32 v7, v5, v5
	v_fmamk_f32 v8, v3, 0xbb800000, v42
	ds_write_b16 v32, v2 offset:9168
	v_mul_f32_e32 v2, v17, v1
	v_fmac_f32_e32 v7, v8, v8
	v_fmamk_f32 v9, v3, 0xbb800000, v58
	v_mul_f32_e32 v2, v217, v2
	v_fmac_f32_e32 v7, v9, v9
	v_fmamk_f32 v10, v3, 0xbb800000, v74
	v_cvt_pk_bf16_f32 v2, v2, s0
	v_fmac_f32_e32 v7, v10, v10
	v_fmamk_f32 v17, v3, 0xbb800000, v90
	ds_write_b16 v32, v2 offset:9232
	v_mul_f32_e32 v2, v18, v1
	v_fmac_f32_e32 v7, v17, v17
	v_fmamk_f32 v18, v3, 0xbb800000, v106
	v_fmac_f32_e32 v7, v18, v18
	v_fmamk_f32 v3, v3, 0xbb800000, v122
	v_fmac_f32_e32 v7, v3, v3
	v_mul_f32_e32 v2, v216, v2
	v_cvt_pk_bf16_f32 v2, v2, s0
	v_add_f32_dpp v7, v7, v7 quad_perm:[1,0,3,2] row_mask:0xf bank_mask:0xf bound_ctrl:1
	ds_write_b16 v32, v2 offset:9296
	v_mul_f32_e32 v2, v19, v1
	v_add_f32_dpp v7, v7, v7 quad_perm:[2,3,0,1] row_mask:0xf bank_mask:0xf bound_ctrl:1
	v_mul_f32_e32 v2, v16, v2
	v_cvt_pk_bf16_f32 v2, v2, s0
	v_add_f32_dpp v7, v7, v7 row_ror:4 row_mask:0xf bank_mask:0xf bound_ctrl:1
	ds_write_b16 v32, v2 offset:9360
	v_mul_f32_e32 v1, v4, v1
	v_add_f32_dpp v7, v7, v7 row_ror:8 row_mask:0xf bank_mask:0xf bound_ctrl:1
	ds_bpermute_b32 v20, v220, v7
	v_mul_f32_e32 v1, v0, v1
	v_cvt_pk_bf16_f32 v1, v1, s0
	ds_write_b16 v32, v1 offset:9424
	s_waitcnt lgkmcnt(1)
	v_add_f32_e32 v7, v7, v20
	v_fmamk_f32 v7, v7, 0x3b800000, v48
	v_mul_f32_e32 v19, 0x4f800000, v7
	v_cmp_gt_f32_e32 vcc, s7, v7
	s_nop 1
	v_cndmask_b32_e32 v7, v7, v19, vcc
	v_sqrt_f32_e32 v19, v7
	s_nop 0
	v_add_u32_e32 v2, -1, v19
	v_fma_f32 v4, -v2, v19, v7
	v_cmp_ge_f32_e64 s[4:5], 0, v4
	v_add_u32_e32 v4, 1, v19
	s_nop 0
	v_cndmask_b32_e64 v2, v19, v2, s[4:5]
	v_fma_f32 v19, -v4, v19, v7
	v_cmp_lt_f32_e64 s[4:5], 0, v19
	s_nop 1
	v_cndmask_b32_e64 v2, v2, v4, s[4:5]
	v_mul_f32_e32 v4, 0x37800000, v2
	v_cndmask_b32_e32 v2, v2, v4, vcc
	v_cmp_class_f32_e32 vcc, v7, v64
	s_nop 1
	v_cndmask_b32_e32 v2, v2, v7, vcc
	v_div_scale_f32 v4, s[4:5], v2, v2, 1.0
	v_rcp_f32_e32 v7, v4
	s_nop 0
	v_fma_f32 v1, -v4, v7, 1.0
	v_fmac_f32_e32 v7, v1, v7
	v_div_scale_f32 v1, vcc, 1.0, v2, 1.0
	v_mul_f32_e32 v19, v1, v7
	v_fma_f32 v20, -v4, v19, v1
	v_fmac_f32_e32 v19, v20, v7
	v_fma_f32 v1, -v4, v19, v1
	v_add_f32_e32 v4, 0, v11
	v_add_f32_e32 v4, v4, v27
	v_add_f32_e32 v4, v4, v43
	v_add_f32_e32 v4, v4, v59
	v_add_f32_e32 v4, v4, v75
	v_add_f32_e32 v4, v4, v91
	v_add_f32_e32 v4, v4, v107
	v_div_fmas_f32 v1, v1, v7, v19
	v_add_f32_e32 v4, v4, v123
	v_div_fixup_f32 v1, v1, v2, 1.0
	v_mul_f32_e32 v2, v5, v1
	v_add_f32_dpp v4, v4, v4 quad_perm:[1,0,3,2] row_mask:0xf bank_mask:0xf bound_ctrl:1
	v_mul_f32_e32 v2, v215, v2
	v_cvt_pk_bf16_f32 v2, v2, s0
	v_add_f32_dpp v4, v4, v4 quad_perm:[2,3,0,1] row_mask:0xf bank_mask:0xf bound_ctrl:1
	ds_write_b16 v32, v2 offset:9504
	v_mul_f32_e32 v2, v6, v1
	v_add_f32_dpp v4, v4, v4 row_ror:4 row_mask:0xf bank_mask:0xf bound_ctrl:1
	v_mul_f32_e32 v2, v214, v2
	v_cvt_pk_bf16_f32 v2, v2, s0
	v_add_f32_dpp v4, v4, v4 row_ror:8 row_mask:0xf bank_mask:0xf bound_ctrl:1
	ds_bpermute_b32 v5, v220, v4
	ds_write_b16 v32, v2 offset:9568
	v_mul_f32_e32 v2, v8, v1
	v_mul_f32_e32 v2, v219, v2
	v_cvt_pk_bf16_f32 v2, v2, s0
	s_waitcnt lgkmcnt(1)
	v_add_f32_e32 v4, v4, v5
	ds_write_b16 v32, v2 offset:9632
	v_mul_f32_e32 v2, v9, v1
	v_fmamk_f32 v6, v4, 0xbb800000, v27
	v_mul_f32_e32 v2, v218, v2
	v_fmamk_f32 v5, v4, 0xbb800000, v11
	v_mul_f32_e32 v7, v6, v6
	v_cvt_pk_bf16_f32 v2, v2, s0
	v_fmac_f32_e32 v7, v5, v5
	v_fmamk_f32 v8, v4, 0xbb800000, v43
	ds_write_b16 v32, v2 offset:9696
	v_mul_f32_e32 v2, v10, v1
	v_fmac_f32_e32 v7, v8, v8
	v_fmamk_f32 v9, v4, 0xbb800000, v59
	v_mul_f32_e32 v2, v217, v2
	v_fmac_f32_e32 v7, v9, v9
	v_fmamk_f32 v10, v4, 0xbb800000, v75
	v_cvt_pk_bf16_f32 v2, v2, s0
	v_fmac_f32_e32 v7, v10, v10
	v_fmamk_f32 v11, v4, 0xbb800000, v91
	ds_write_b16 v32, v2 offset:9760
	v_mul_f32_e32 v2, v17, v1
	v_fmac_f32_e32 v7, v11, v11
	v_fmamk_f32 v17, v4, 0xbb800000, v107
	v_fmac_f32_e32 v7, v17, v17
	v_fmamk_f32 v4, v4, 0xbb800000, v123
	v_fmac_f32_e32 v7, v4, v4
	v_mul_f32_e32 v2, v216, v2
	v_cvt_pk_bf16_f32 v2, v2, s0
	v_add_f32_dpp v7, v7, v7 quad_perm:[1,0,3,2] row_mask:0xf bank_mask:0xf bound_ctrl:1
	ds_write_b16 v32, v2 offset:9824
	v_mul_f32_e32 v2, v18, v1
	v_add_f32_dpp v7, v7, v7 quad_perm:[2,3,0,1] row_mask:0xf bank_mask:0xf bound_ctrl:1
	v_mul_f32_e32 v2, v16, v2
	v_cvt_pk_bf16_f32 v2, v2, s0
	v_add_f32_dpp v7, v7, v7 row_ror:4 row_mask:0xf bank_mask:0xf bound_ctrl:1
	ds_write_b16 v32, v2 offset:9888
	v_mul_f32_e32 v1, v3, v1
	v_add_f32_dpp v7, v7, v7 row_ror:8 row_mask:0xf bank_mask:0xf bound_ctrl:1
	ds_bpermute_b32 v19, v220, v7
	v_mul_f32_e32 v1, v0, v1
	v_cvt_pk_bf16_f32 v1, v1, s0
	ds_write_b16 v32, v1 offset:9952
	s_waitcnt lgkmcnt(1)
	v_add_f32_e32 v7, v7, v19
	v_fmamk_f32 v7, v7, 0x3b800000, v48
	v_mul_f32_e32 v18, 0x4f800000, v7
	v_cmp_gt_f32_e32 vcc, s7, v7
	s_nop 1
	v_cndmask_b32_e32 v7, v7, v18, vcc
	v_sqrt_f32_e32 v18, v7
	s_nop 0
	v_add_u32_e32 v2, -1, v18
	v_fma_f32 v3, -v2, v18, v7
	v_cmp_ge_f32_e64 s[4:5], 0, v3
	v_add_u32_e32 v3, 1, v18
	s_nop 0
	v_cndmask_b32_e64 v2, v18, v2, s[4:5]
	v_fma_f32 v18, -v3, v18, v7
	v_cmp_lt_f32_e64 s[4:5], 0, v18
	s_nop 1
	v_cndmask_b32_e64 v2, v2, v3, s[4:5]
	v_mul_f32_e32 v3, 0x37800000, v2
	v_cndmask_b32_e32 v2, v2, v3, vcc
	v_cmp_class_f32_e32 vcc, v7, v64
	s_nop 1
	v_cndmask_b32_e32 v2, v2, v7, vcc
	v_div_scale_f32 v3, s[4:5], v2, v2, 1.0
	v_rcp_f32_e32 v7, v3
	s_nop 0
	v_fma_f32 v1, -v3, v7, 1.0
	v_fmac_f32_e32 v7, v1, v7
	v_div_scale_f32 v1, vcc, 1.0, v2, 1.0
	v_mul_f32_e32 v18, v1, v7
	v_fma_f32 v19, -v3, v18, v1
	v_fmac_f32_e32 v18, v19, v7
	v_fma_f32 v1, -v3, v18, v1
	v_add_f32_e32 v3, 0, v12
	v_add_f32_e32 v3, v3, v28
	v_add_f32_e32 v3, v3, v44
	v_add_f32_e32 v3, v3, v60
	v_add_f32_e32 v3, v3, v76
	v_add_f32_e32 v3, v3, v92
	v_div_fmas_f32 v1, v1, v7, v18
	v_add_f32_e32 v3, v3, v108
	v_div_fixup_f32 v1, v1, v2, 1.0
	v_add_f32_e32 v3, v3, v124
	v_mul_f32_e32 v2, v5, v1
	v_mul_f32_e32 v2, v215, v2
	v_add_f32_dpp v3, v3, v3 quad_perm:[1,0,3,2] row_mask:0xf bank_mask:0xf bound_ctrl:1
	v_cvt_pk_bf16_f32 v2, v2, s0
	ds_write_b16 v32, v2 offset:10032
	v_add_f32_dpp v3, v3, v3 quad_perm:[2,3,0,1] row_mask:0xf bank_mask:0xf bound_ctrl:1
	v_mul_f32_e32 v2, v6, v1
	v_mul_f32_e32 v2, v214, v2
	v_add_f32_dpp v3, v3, v3 row_ror:4 row_mask:0xf bank_mask:0xf bound_ctrl:1
	v_cvt_pk_bf16_f32 v2, v2, s0
	ds_write_b16 v32, v2 offset:10096
	v_add_f32_dpp v3, v3, v3 row_ror:8 row_mask:0xf bank_mask:0xf bound_ctrl:1
	ds_bpermute_b32 v5, v220, v3
	v_mul_f32_e32 v2, v8, v1
	v_mul_f32_e32 v2, v219, v2
	v_cvt_pk_bf16_f32 v2, v2, s0
	ds_write_b16 v32, v2 offset:10160
	v_mul_f32_e32 v2, v9, v1
	s_waitcnt lgkmcnt(1)
	v_add_f32_e32 v3, v3, v5
	v_mul_f32_e32 v2, v218, v2
	v_fmamk_f32 v6, v3, 0xbb800000, v28
	v_cvt_pk_bf16_f32 v2, v2, s0
	v_fmamk_f32 v5, v3, 0xbb800000, v12
	v_mul_f32_e32 v7, v6, v6
	ds_write_b16 v32, v2 offset:10224
	v_mul_f32_e32 v2, v10, v1
	v_fmac_f32_e32 v7, v5, v5
	v_fmamk_f32 v8, v3, 0xbb800000, v44
	v_mul_f32_e32 v2, v217, v2
	v_fmac_f32_e32 v7, v8, v8
	v_fmamk_f32 v9, v3, 0xbb800000, v60
	v_cvt_pk_bf16_f32 v2, v2, s0
	v_fmac_f32_e32 v7, v9, v9
	v_fmamk_f32 v10, v3, 0xbb800000, v76
	ds_write_b16 v32, v2 offset:10288
	v_mul_f32_e32 v2, v11, v1
	v_fmac_f32_e32 v7, v10, v10
	v_fmamk_f32 v11, v3, 0xbb800000, v92
	v_fmac_f32_e32 v7, v11, v11
	v_fmamk_f32 v12, v3, 0xbb800000, v108
	v_fmac_f32_e32 v7, v12, v12
	v_fmamk_f32 v3, v3, 0xbb800000, v124
	v_fmac_f32_e32 v7, v3, v3
	v_mul_f32_e32 v2, v216, v2
	v_cvt_pk_bf16_f32 v2, v2, s0
	v_add_f32_dpp v7, v7, v7 quad_perm:[1,0,3,2] row_mask:0xf bank_mask:0xf bound_ctrl:1
	ds_write_b16 v32, v2 offset:10352
	v_mul_f32_e32 v2, v17, v1
	v_add_f32_dpp v7, v7, v7 quad_perm:[2,3,0,1] row_mask:0xf bank_mask:0xf bound_ctrl:1
	v_mul_f32_e32 v2, v16, v2
	v_cvt_pk_bf16_f32 v2, v2, s0
	v_add_f32_dpp v7, v7, v7 row_ror:4 row_mask:0xf bank_mask:0xf bound_ctrl:1
	ds_write_b16 v32, v2 offset:10416
	v_mul_f32_e32 v1, v4, v1
	v_add_f32_dpp v7, v7, v7 row_ror:8 row_mask:0xf bank_mask:0xf bound_ctrl:1
	ds_bpermute_b32 v18, v220, v7
	v_mul_f32_e32 v1, v0, v1
	v_cvt_pk_bf16_f32 v1, v1, s0
	ds_write_b16 v32, v1 offset:10480
	s_waitcnt lgkmcnt(1)
	v_add_f32_e32 v7, v7, v18
	v_fmamk_f32 v7, v7, 0x3b800000, v48
	v_mul_f32_e32 v17, 0x4f800000, v7
	v_cmp_gt_f32_e32 vcc, s7, v7
	s_nop 1
	v_cndmask_b32_e32 v7, v7, v17, vcc
	v_sqrt_f32_e32 v17, v7
	s_nop 0
	v_add_u32_e32 v2, -1, v17
	v_fma_f32 v4, -v2, v17, v7
	v_cmp_ge_f32_e64 s[4:5], 0, v4
	v_add_u32_e32 v4, 1, v17
	s_nop 0
	v_cndmask_b32_e64 v2, v17, v2, s[4:5]
	v_fma_f32 v17, -v4, v17, v7
	v_cmp_lt_f32_e64 s[4:5], 0, v17
	s_nop 1
	v_cndmask_b32_e64 v2, v2, v4, s[4:5]
	v_mul_f32_e32 v4, 0x37800000, v2
	v_cndmask_b32_e32 v2, v2, v4, vcc
	v_cmp_class_f32_e32 vcc, v7, v64
	s_nop 1
	v_cndmask_b32_e32 v2, v2, v7, vcc
	v_div_scale_f32 v4, s[4:5], v2, v2, 1.0
	v_rcp_f32_e32 v7, v4
	s_nop 0
	v_fma_f32 v1, -v4, v7, 1.0
	v_fmac_f32_e32 v7, v1, v7
	v_div_scale_f32 v1, vcc, 1.0, v2, 1.0
	v_mul_f32_e32 v17, v1, v7
	v_fma_f32 v18, -v4, v17, v1
	v_fmac_f32_e32 v17, v18, v7
	v_fma_f32 v1, -v4, v17, v1
	v_add_f32_e32 v4, 0, v13
	v_add_f32_e32 v4, v4, v29
	v_add_f32_e32 v4, v4, v45
	v_add_f32_e32 v4, v4, v61
	v_add_f32_e32 v4, v4, v77
	v_add_f32_e32 v4, v4, v93
	v_div_fmas_f32 v1, v1, v7, v17
	v_add_f32_e32 v4, v4, v109
	v_div_fixup_f32 v1, v1, v2, 1.0
	v_add_f32_e32 v4, v4, v125
	v_mul_f32_e32 v2, v5, v1
	v_mul_f32_e32 v2, v215, v2
	v_add_f32_dpp v4, v4, v4 quad_perm:[1,0,3,2] row_mask:0xf bank_mask:0xf bound_ctrl:1
	v_cvt_pk_bf16_f32 v2, v2, s0
	ds_write_b16 v32, v2 offset:12672
	v_add_f32_dpp v4, v4, v4 quad_perm:[2,3,0,1] row_mask:0xf bank_mask:0xf bound_ctrl:1
	v_mul_f32_e32 v2, v6, v1
	v_mul_f32_e32 v2, v214, v2
	v_add_f32_dpp v4, v4, v4 row_ror:4 row_mask:0xf bank_mask:0xf bound_ctrl:1
	v_cvt_pk_bf16_f32 v2, v2, s0
	ds_write_b16 v32, v2 offset:12736
	v_add_f32_dpp v4, v4, v4 row_ror:8 row_mask:0xf bank_mask:0xf bound_ctrl:1
	ds_bpermute_b32 v5, v220, v4
	v_mul_f32_e32 v2, v8, v1
	v_mul_f32_e32 v2, v219, v2
	v_cvt_pk_bf16_f32 v2, v2, s0
	ds_write_b16 v32, v2 offset:12800
	v_mul_f32_e32 v2, v9, v1
	s_waitcnt lgkmcnt(1)
	v_add_f32_e32 v4, v4, v5
	v_mul_f32_e32 v2, v218, v2
	v_fmamk_f32 v6, v4, 0xbb800000, v29
	v_cvt_pk_bf16_f32 v2, v2, s0
	v_fmamk_f32 v5, v4, 0xbb800000, v13
	v_mul_f32_e32 v7, v6, v6
	ds_write_b16 v32, v2 offset:12864
	v_mul_f32_e32 v2, v10, v1
	v_fmac_f32_e32 v7, v5, v5
	v_fmamk_f32 v8, v4, 0xbb800000, v45
	v_mul_f32_e32 v2, v217, v2
	v_fmac_f32_e32 v7, v8, v8
	v_fmamk_f32 v9, v4, 0xbb800000, v61
	v_cvt_pk_bf16_f32 v2, v2, s0
	v_fmac_f32_e32 v7, v9, v9
	v_fmamk_f32 v10, v4, 0xbb800000, v77
	ds_write_b16 v32, v2 offset:12928
	v_mul_f32_e32 v2, v11, v1
	v_fmac_f32_e32 v7, v10, v10
	v_fmamk_f32 v11, v4, 0xbb800000, v93
	v_fmac_f32_e32 v7, v11, v11
	v_fmamk_f32 v13, v4, 0xbb800000, v109
	v_fmac_f32_e32 v7, v13, v13
	v_fmamk_f32 v4, v4, 0xbb800000, v125
	v_fmac_f32_e32 v7, v4, v4
	v_mul_f32_e32 v2, v216, v2
	v_cvt_pk_bf16_f32 v2, v2, s0
	v_add_f32_dpp v7, v7, v7 quad_perm:[1,0,3,2] row_mask:0xf bank_mask:0xf bound_ctrl:1
	ds_write_b16 v32, v2 offset:12992
	v_mul_f32_e32 v2, v12, v1
	v_add_f32_dpp v7, v7, v7 quad_perm:[2,3,0,1] row_mask:0xf bank_mask:0xf bound_ctrl:1
	v_mul_f32_e32 v2, v16, v2
	v_cvt_pk_bf16_f32 v2, v2, s0
	v_add_f32_dpp v7, v7, v7 row_ror:4 row_mask:0xf bank_mask:0xf bound_ctrl:1
	ds_write_b16 v32, v2 offset:13056
	v_mul_f32_e32 v1, v3, v1
	v_add_f32_dpp v7, v7, v7 row_ror:8 row_mask:0xf bank_mask:0xf bound_ctrl:1
	ds_bpermute_b32 v17, v220, v7
	v_mul_f32_e32 v1, v0, v1
	v_cvt_pk_bf16_f32 v1, v1, s0
	ds_write_b16 v32, v1 offset:13120
	s_waitcnt lgkmcnt(1)
	v_add_f32_e32 v7, v7, v17
	v_fmamk_f32 v7, v7, 0x3b800000, v48
	v_mul_f32_e32 v12, 0x4f800000, v7
	v_cmp_gt_f32_e32 vcc, s7, v7
	s_nop 1
	v_cndmask_b32_e32 v7, v7, v12, vcc
	v_sqrt_f32_e32 v12, v7
	s_nop 0
	v_add_u32_e32 v2, -1, v12
	v_fma_f32 v3, -v2, v12, v7
	v_cmp_ge_f32_e64 s[4:5], 0, v3
	v_add_u32_e32 v3, 1, v12
	s_nop 0
	v_cndmask_b32_e64 v2, v12, v2, s[4:5]
	v_fma_f32 v12, -v3, v12, v7
	v_cmp_lt_f32_e64 s[4:5], 0, v12
	s_nop 1
	v_cndmask_b32_e64 v2, v2, v3, s[4:5]
	v_mul_f32_e32 v3, 0x37800000, v2
	v_cndmask_b32_e32 v2, v2, v3, vcc
	v_cmp_class_f32_e32 vcc, v7, v64
	s_nop 1
	v_cndmask_b32_e32 v2, v2, v7, vcc
	v_div_scale_f32 v3, s[4:5], v2, v2, 1.0
	v_rcp_f32_e32 v7, v3
	s_nop 0
	v_fma_f32 v1, -v3, v7, 1.0
	v_fmac_f32_e32 v7, v1, v7
	v_div_scale_f32 v1, vcc, 1.0, v2, 1.0
	v_mul_f32_e32 v12, v1, v7
	v_fma_f32 v17, -v3, v12, v1
	v_fmac_f32_e32 v12, v17, v7
	v_fma_f32 v1, -v3, v12, v1
	v_add_f32_e32 v3, 0, v14
	v_add_f32_e32 v3, v3, v30
	v_add_f32_e32 v3, v3, v46
	v_add_f32_e32 v3, v3, v62
	v_add_f32_e32 v3, v3, v78
	v_add_f32_e32 v3, v3, v94
	v_div_fmas_f32 v1, v1, v7, v12
	v_add_f32_e32 v3, v3, v110
	v_div_fixup_f32 v1, v1, v2, 1.0
	v_add_f32_e32 v3, v3, v126
	v_mul_f32_e32 v2, v5, v1
	v_mul_f32_e32 v2, v215, v2
	v_add_f32_dpp v3, v3, v3 quad_perm:[1,0,3,2] row_mask:0xf bank_mask:0xf bound_ctrl:1
	v_cvt_pk_bf16_f32 v2, v2, s0
	ds_write_b16 v32, v2 offset:13200
	v_add_f32_dpp v3, v3, v3 quad_perm:[2,3,0,1] row_mask:0xf bank_mask:0xf bound_ctrl:1
	v_mul_f32_e32 v2, v6, v1
	v_mul_f32_e32 v2, v214, v2
	v_add_f32_dpp v3, v3, v3 row_ror:4 row_mask:0xf bank_mask:0xf bound_ctrl:1
	v_cvt_pk_bf16_f32 v2, v2, s0
	ds_write_b16 v32, v2 offset:13264
	v_add_f32_dpp v3, v3, v3 row_ror:8 row_mask:0xf bank_mask:0xf bound_ctrl:1
	ds_bpermute_b32 v5, v220, v3
	v_mul_f32_e32 v2, v8, v1
	v_mul_f32_e32 v2, v219, v2
	v_cvt_pk_bf16_f32 v2, v2, s0
	ds_write_b16 v32, v2 offset:13328
	v_mul_f32_e32 v2, v9, v1
	s_waitcnt lgkmcnt(1)
	v_add_f32_e32 v3, v3, v5
	v_mul_f32_e32 v2, v218, v2
	v_fmamk_f32 v6, v3, 0xbb800000, v30
	v_cvt_pk_bf16_f32 v2, v2, s0
	v_fmamk_f32 v5, v3, 0xbb800000, v14
	v_mul_f32_e32 v7, v6, v6
	ds_write_b16 v32, v2 offset:13392
	v_mul_f32_e32 v2, v10, v1
	v_fmac_f32_e32 v7, v5, v5
	v_fmamk_f32 v8, v3, 0xbb800000, v46
	v_mul_f32_e32 v2, v217, v2
	v_fmac_f32_e32 v7, v8, v8
	v_fmamk_f32 v9, v3, 0xbb800000, v62
	v_cvt_pk_bf16_f32 v2, v2, s0
	v_fmac_f32_e32 v7, v9, v9
	v_fmamk_f32 v10, v3, 0xbb800000, v78
	ds_write_b16 v32, v2 offset:13456
	v_mul_f32_e32 v2, v11, v1
	v_fmac_f32_e32 v7, v10, v10
	v_fmamk_f32 v11, v3, 0xbb800000, v94
	v_fmac_f32_e32 v7, v11, v11
	v_fmamk_f32 v12, v3, 0xbb800000, v110
	v_fmac_f32_e32 v7, v12, v12
	v_fmamk_f32 v3, v3, 0xbb800000, v126
	v_fmac_f32_e32 v7, v3, v3
	v_mul_f32_e32 v2, v216, v2
	v_cvt_pk_bf16_f32 v2, v2, s0
	v_add_f32_dpp v7, v7, v7 quad_perm:[1,0,3,2] row_mask:0xf bank_mask:0xf bound_ctrl:1
	ds_write_b16 v32, v2 offset:13520
	v_mul_f32_e32 v2, v13, v1
	v_add_f32_dpp v7, v7, v7 quad_perm:[2,3,0,1] row_mask:0xf bank_mask:0xf bound_ctrl:1
	v_mul_f32_e32 v2, v16, v2
	v_cvt_pk_bf16_f32 v2, v2, s0
	v_add_f32_dpp v7, v7, v7 row_ror:4 row_mask:0xf bank_mask:0xf bound_ctrl:1
	ds_write_b16 v32, v2 offset:13584
	v_mul_f32_e32 v1, v4, v1
	v_add_f32_dpp v7, v7, v7 row_ror:8 row_mask:0xf bank_mask:0xf bound_ctrl:1
	ds_bpermute_b32 v14, v220, v7
	v_mul_f32_e32 v1, v0, v1
	v_cvt_pk_bf16_f32 v1, v1, s0
	ds_write_b16 v32, v1 offset:13648
	v_and_b32_e32 v17, 0xffff0000, v191
	s_waitcnt lgkmcnt(1)
	v_add_f32_e32 v7, v7, v14
	v_fmamk_f32 v7, v7, 0x3b800000, v48
	v_mul_f32_e32 v13, 0x4f800000, v7
	v_cmp_gt_f32_e32 vcc, s7, v7
	s_nop 1
	v_cndmask_b32_e32 v7, v7, v13, vcc
	v_sqrt_f32_e32 v13, v7
	s_nop 0
	v_add_u32_e32 v2, -1, v13
	v_fma_f32 v4, -v2, v13, v7
	v_cmp_ge_f32_e64 s[4:5], 0, v4
	v_add_u32_e32 v4, 1, v13
	s_nop 0
	v_cndmask_b32_e64 v2, v13, v2, s[4:5]
	v_fma_f32 v13, -v4, v13, v7
	v_cmp_lt_f32_e64 s[4:5], 0, v13
	s_nop 1
	v_cndmask_b32_e64 v2, v2, v4, s[4:5]
	v_mul_f32_e32 v4, 0x37800000, v2
	v_cndmask_b32_e32 v2, v2, v4, vcc
	v_cmp_class_f32_e32 vcc, v7, v64
	s_nop 1
	v_cndmask_b32_e32 v2, v2, v7, vcc
	v_div_scale_f32 v4, s[4:5], v2, v2, 1.0
	v_rcp_f32_e32 v7, v4
	s_nop 0
	v_fma_f32 v1, -v4, v7, 1.0
	v_fmac_f32_e32 v7, v1, v7
	v_div_scale_f32 v1, vcc, 1.0, v2, 1.0
	v_mul_f32_e32 v13, v1, v7
	v_fma_f32 v14, -v4, v13, v1
	v_fmac_f32_e32 v13, v14, v7
	v_fma_f32 v1, -v4, v13, v1
	v_add_f32_e32 v4, 0, v15
	v_add_f32_e32 v4, v4, v31
	v_add_f32_e32 v4, v4, v47
	v_add_f32_e32 v4, v4, v63
	v_add_f32_e32 v4, v4, v79
	v_add_f32_e32 v4, v4, v95
	v_add_f32_e32 v4, v4, v111
	v_add_f32_e32 v4, v4, v127
	v_div_fmas_f32 v1, v1, v7, v13
	v_div_fixup_f32 v1, v1, v2, 1.0
	v_add_f32_dpp v4, v4, v4 quad_perm:[1,0,3,2] row_mask:0xf bank_mask:0xf bound_ctrl:1
	v_mul_f32_e32 v2, v5, v1
	v_mul_f32_e32 v2, v215, v2
	v_add_f32_dpp v4, v4, v4 quad_perm:[2,3,0,1] row_mask:0xf bank_mask:0xf bound_ctrl:1
	v_cvt_pk_bf16_f32 v2, v2, s0
	ds_write_b16 v32, v2 offset:13728
	v_add_f32_dpp v4, v4, v4 row_ror:4 row_mask:0xf bank_mask:0xf bound_ctrl:1
	v_mul_f32_e32 v2, v6, v1
	v_mul_f32_e32 v2, v214, v2
	v_add_f32_dpp v4, v4, v4 row_ror:8 row_mask:0xf bank_mask:0xf bound_ctrl:1
	ds_bpermute_b32 v5, v220, v4
	v_cvt_pk_bf16_f32 v2, v2, s0
	ds_write_b16 v32, v2 offset:13792
	v_mul_f32_e32 v2, v8, v1
	v_mul_f32_e32 v2, v219, v2
	s_waitcnt lgkmcnt(1)
	v_add_f32_e32 v4, v4, v5
	v_fmac_f32_e32 v31, 0xbb800000, v4
	v_fmac_f32_e32 v15, 0xbb800000, v4
	v_mul_f32_e32 v5, v31, v31
	v_fmac_f32_e32 v5, v15, v15
	v_fmac_f32_e32 v47, 0xbb800000, v4
	v_fmac_f32_e32 v5, v47, v47
	v_fmac_f32_e32 v63, 0xbb800000, v4
	v_fmac_f32_e32 v5, v63, v63
	v_fmac_f32_e32 v79, 0xbb800000, v4
	v_fmac_f32_e32 v5, v79, v79
	v_fmac_f32_e32 v95, 0xbb800000, v4
	v_fmac_f32_e32 v5, v95, v95
	v_fmac_f32_e32 v111, 0xbb800000, v4
	v_fmac_f32_e32 v5, v111, v111
	v_fmac_f32_e32 v127, 0xbb800000, v4
	v_fmac_f32_e32 v5, v127, v127
	v_cvt_pk_bf16_f32 v2, v2, s0
	ds_write_b16 v32, v2 offset:13856
	v_add_f32_dpp v4, v5, v5 quad_perm:[1,0,3,2] row_mask:0xf bank_mask:0xf bound_ctrl:1
	v_mul_f32_e32 v2, v9, v1
	v_mul_f32_e32 v2, v218, v2
	v_add_f32_dpp v4, v4, v4 quad_perm:[2,3,0,1] row_mask:0xf bank_mask:0xf bound_ctrl:1
	v_cvt_pk_bf16_f32 v2, v2, s0
	ds_write_b16 v32, v2 offset:13920
	v_add_f32_dpp v4, v4, v4 row_ror:4 row_mask:0xf bank_mask:0xf bound_ctrl:1
	v_mul_f32_e32 v2, v10, v1
	v_mul_f32_e32 v2, v217, v2
	v_add_f32_dpp v4, v4, v4 row_ror:8 row_mask:0xf bank_mask:0xf bound_ctrl:1
	ds_bpermute_b32 v5, v220, v4
	v_cvt_pk_bf16_f32 v2, v2, s0
	ds_write_b16 v32, v2 offset:13984
	v_mul_f32_e32 v2, v11, v1
	v_mul_f32_e32 v2, v216, v2
	s_waitcnt lgkmcnt(1)
	v_add_f32_e32 v4, v4, v5
	v_fmac_f32_e32 v48, 0x3b800000, v4
	v_mul_f32_e32 v4, 0x4f800000, v48
	v_cmp_gt_f32_e32 vcc, s7, v48
	v_cvt_pk_bf16_f32 v2, v2, s0
	ds_write_b16 v32, v2 offset:14048
	v_cndmask_b32_e32 v4, v48, v4, vcc
	v_sqrt_f32_e32 v5, v4
	v_mul_f32_e32 v2, v12, v1
	v_mul_f32_e32 v2, v16, v2
	v_cvt_pk_bf16_f32 v2, v2, s0
	ds_write_b16 v32, v2 offset:14112
	v_add_u32_e32 v2, -1, v5
	v_mul_f32_e32 v1, v3, v1
	v_fma_f32 v3, -v2, v5, v4
	v_cmp_ge_f32_e64 s[4:5], 0, v3
	v_add_u32_e32 v3, 1, v5
	v_mul_f32_e32 v1, v0, v1
	v_cndmask_b32_e64 v2, v5, v2, s[4:5]
	v_fma_f32 v5, -v3, v5, v4
	v_cmp_lt_f32_e64 s[4:5], 0, v5
	v_cvt_pk_bf16_f32 v1, v1, s0
	ds_write_b16 v32, v1 offset:14176
	v_cndmask_b32_e64 v2, v2, v3, s[4:5]
	v_mul_f32_e32 v3, 0x37800000, v2
	v_cndmask_b32_e32 v2, v2, v3, vcc
	v_cmp_class_f32_e32 vcc, v4, v64
	v_lshlrev_b32_e32 v12, 16, v188
	v_and_b32_e32 v13, 0xffff0000, v188
	v_cndmask_b32_e32 v2, v2, v4, vcc
	v_div_scale_f32 v3, s[4:5], v2, v2, 1.0
	v_rcp_f32_e32 v4, v3
	s_movk_i32 s4, 0x210
	v_fma_f32 v1, -v3, v4, 1.0
	v_fmac_f32_e32 v4, v1, v4
	v_div_scale_f32 v1, vcc, 1.0, v2, 1.0
	v_mul_f32_e32 v5, v1, v4
	v_fma_f32 v6, -v3, v5, v1
	v_fmac_f32_e32 v5, v6, v4
	v_fma_f32 v1, -v3, v5, v1
	v_div_fmas_f32 v1, v1, v4, v5
	v_div_fixup_f32 v1, v1, v2, 1.0
	v_mul_f32_e32 v2, v15, v1
	v_mul_f32_e32 v2, v215, v2
	v_cvt_pk_bf16_f32 v2, v2, s0
	ds_write_b16 v32, v2 offset:14256
	v_mul_f32_e32 v2, v31, v1
	v_mul_f32_e32 v2, v214, v2
	v_cvt_pk_bf16_f32 v2, v2, s0
	ds_write_b16 v32, v2 offset:14320
	v_mul_f32_e32 v2, v47, v1
	v_mul_f32_e32 v2, v219, v2
	v_cvt_pk_bf16_f32 v2, v2, s0
	ds_write_b16 v32, v2 offset:14384
	v_mul_f32_e32 v2, v63, v1
	v_mul_f32_e32 v2, v218, v2
	v_cvt_pk_bf16_f32 v2, v2, s0
	ds_write_b16 v32, v2 offset:14448
	v_mul_f32_e32 v2, v79, v1
	v_mul_f32_e32 v2, v217, v2
	v_cvt_pk_bf16_f32 v2, v2, s0
	ds_write_b16 v32, v2 offset:14512
	v_mul_f32_e32 v2, v95, v1
	v_mul_f32_e32 v2, v216, v2
	v_cvt_pk_bf16_f32 v2, v2, s0
	ds_write_b16 v32, v2 offset:14576
	v_mul_f32_e32 v2, v111, v1
	v_mul_f32_e32 v1, v127, v1
	v_mul_f32_e32 v2, v16, v2
	v_mul_f32_e32 v0, v0, v1
	v_cvt_pk_bf16_f32 v2, v2, s0
	v_cvt_pk_bf16_f32 v0, v0, s0
	ds_write_b16 v32, v2 offset:14640
	ds_write_b16 v32, v0 offset:14704
	s_waitcnt lgkmcnt(0)
	v_mul_lo_u32 v0, v213, s4
	v_lshlrev_b32_e32 v1, 4, v210
	v_add3_u32 v0, s6, v0, v1
	ds_read_b128 v[2:5], v0
	ds_read_b128 v[6:9], v0 offset:64
	v_lshlrev_b32_e32 v16, 16, v191
	s_and_b64 vcc, exec, s[70:71]
	s_waitcnt lgkmcnt(1)
	v_lshlrev_b32_e32 v10, 16, v2
	v_and_b32_e32 v11, 0xffff0000, v2
	v_pk_mul_f32 v[10:11], v[12:13], v[10:11]
	v_lshlrev_b32_e32 v12, 16, v189
	v_cvt_pk_bf16_f32 v2, v10, v11
	v_lshlrev_b32_e32 v10, 16, v3
	v_and_b32_e32 v11, 0xffff0000, v3
	v_and_b32_e32 v13, 0xffff0000, v189
	v_pk_mul_f32 v[10:11], v[12:13], v[10:11]
	v_lshlrev_b32_e32 v12, 16, v190
	v_cvt_pk_bf16_f32 v3, v10, v11
	v_lshlrev_b32_e32 v10, 16, v4
	v_and_b32_e32 v11, 0xffff0000, v4
	v_and_b32_e32 v13, 0xffff0000, v190
	v_pk_mul_f32 v[10:11], v[12:13], v[10:11]
	v_lshlrev_b32_e32 v14, 16, v5
	v_cvt_pk_bf16_f32 v4, v10, v11
	ds_read_b128 v[10:13], v0 offset:8448
	v_and_b32_e32 v15, 0xffff0000, v5
	v_pk_mul_f32 v[14:15], v[16:17], v[14:15]
	v_lshlrev_b32_e32 v16, 16, v184
	v_cvt_pk_bf16_f32 v5, v14, v15
	global_store_dwordx4 v[208:209], v[2:5], off
	ds_read_b128 v[2:5], v0 offset:8512
	s_waitcnt lgkmcnt(1)
	v_lshlrev_b32_e32 v14, 16, v10
	v_and_b32_e32 v15, 0xffff0000, v10
	v_and_b32_e32 v17, 0xffff0000, v184
	v_pk_mul_f32 v[14:15], v[16:17], v[14:15]
	v_lshlrev_b32_e32 v16, 16, v185
	v_cvt_pk_bf16_f32 v10, v14, v15
	v_lshlrev_b32_e32 v14, 16, v11
	v_and_b32_e32 v15, 0xffff0000, v11
	v_and_b32_e32 v17, 0xffff0000, v185
	v_pk_mul_f32 v[14:15], v[16:17], v[14:15]
	v_lshlrev_b32_e32 v16, 16, v186
	v_cvt_pk_bf16_f32 v11, v14, v15
	v_lshlrev_b32_e32 v14, 16, v12
	v_and_b32_e32 v15, 0xffff0000, v12
	v_and_b32_e32 v17, 0xffff0000, v186
	v_pk_mul_f32 v[14:15], v[16:17], v[14:15]
	v_lshlrev_b32_e32 v16, 16, v187
	v_cvt_pk_bf16_f32 v12, v14, v15
	v_lshlrev_b32_e32 v14, 16, v13
	v_and_b32_e32 v15, 0xffff0000, v13
	v_and_b32_e32 v17, 0xffff0000, v187
	v_pk_mul_f32 v[14:15], v[16:17], v[14:15]
	v_lshlrev_b32_e32 v16, 16, v175
	v_cvt_pk_bf16_f32 v13, v14, v15
	global_store_dwordx4 v[206:207], v[10:13], off offset:1024
	v_and_b32_e32 v17, 0xffff0000, v175
	s_nop 0
	v_lshlrev_b32_e32 v10, 16, v6
	v_and_b32_e32 v11, 0xffff0000, v6
	v_lshlrev_b32_e32 v12, 16, v180
	v_and_b32_e32 v13, 0xffff0000, v180
	v_pk_mul_f32 v[10:11], v[12:13], v[10:11]
	v_lshlrev_b32_e32 v12, 16, v181
	v_cvt_pk_bf16_f32 v6, v10, v11
	v_lshlrev_b32_e32 v10, 16, v7
	v_and_b32_e32 v11, 0xffff0000, v7
	v_and_b32_e32 v13, 0xffff0000, v181
	v_pk_mul_f32 v[10:11], v[12:13], v[10:11]
	v_lshlrev_b32_e32 v12, 16, v182
	v_cvt_pk_bf16_f32 v7, v10, v11
	v_lshlrev_b32_e32 v10, 16, v8
	v_and_b32_e32 v11, 0xffff0000, v8
	v_and_b32_e32 v13, 0xffff0000, v182
	v_pk_mul_f32 v[10:11], v[12:13], v[10:11]
	v_lshlrev_b32_e32 v12, 16, v183
	v_cvt_pk_bf16_f32 v8, v10, v11
	v_lshlrev_b32_e32 v10, 16, v9
	v_and_b32_e32 v11, 0xffff0000, v9
	v_and_b32_e32 v13, 0xffff0000, v183
	v_pk_mul_f32 v[10:11], v[12:13], v[10:11]
	v_lshlrev_b32_e32 v12, 16, v179
	v_cvt_pk_bf16_f32 v9, v10, v11
	global_store_dwordx4 v[204:205], v[6:9], off
	s_waitcnt lgkmcnt(0)
	v_lshlrev_b32_e32 v10, 16, v5
	v_and_b32_e32 v11, 0xffff0000, v5
	v_lshlrev_b32_e32 v6, 16, v2
	v_and_b32_e32 v7, 0xffff0000, v2
	v_lshlrev_b32_e32 v8, 16, v176
	v_and_b32_e32 v9, 0xffff0000, v176
	v_pk_mul_f32 v[6:7], v[8:9], v[6:7]
	v_lshlrev_b32_e32 v8, 16, v177
	v_cvt_pk_bf16_f32 v2, v6, v7
	v_lshlrev_b32_e32 v6, 16, v3
	v_and_b32_e32 v7, 0xffff0000, v3
	v_and_b32_e32 v9, 0xffff0000, v177
	v_pk_mul_f32 v[6:7], v[8:9], v[6:7]
	v_lshlrev_b32_e32 v8, 16, v178
	v_cvt_pk_bf16_f32 v3, v6, v7
	v_lshlrev_b32_e32 v6, 16, v4
	v_and_b32_e32 v7, 0xffff0000, v4
	v_and_b32_e32 v9, 0xffff0000, v178
	v_pk_mul_f32 v[6:7], v[8:9], v[6:7]
	v_and_b32_e32 v13, 0xffff0000, v179
	v_cvt_pk_bf16_f32 v4, v6, v7
	ds_read_b128 v[6:9], v0 offset:128
	v_pk_mul_f32 v[10:11], v[12:13], v[10:11]
	v_lshlrev_b32_e32 v12, 16, v172
	v_cvt_pk_bf16_f32 v5, v10, v11
	global_store_dwordx4 v[204:205], v[2:5], off offset:1024
	ds_read_b128 v[2:5], v0 offset:192
	s_waitcnt lgkmcnt(1)
	v_lshlrev_b32_e32 v10, 16, v6
	v_and_b32_e32 v11, 0xffff0000, v6
	v_and_b32_e32 v13, 0xffff0000, v172
	v_pk_mul_f32 v[10:11], v[12:13], v[10:11]
	v_lshlrev_b32_e32 v12, 16, v173
	v_cvt_pk_bf16_f32 v6, v10, v11
	v_lshlrev_b32_e32 v10, 16, v7
	v_and_b32_e32 v11, 0xffff0000, v7
	v_and_b32_e32 v13, 0xffff0000, v173
	v_pk_mul_f32 v[10:11], v[12:13], v[10:11]
	v_lshlrev_b32_e32 v12, 16, v174
	v_cvt_pk_bf16_f32 v7, v10, v11
	v_lshlrev_b32_e32 v10, 16, v8
	v_and_b32_e32 v11, 0xffff0000, v8
	v_and_b32_e32 v13, 0xffff0000, v174
	v_pk_mul_f32 v[10:11], v[12:13], v[10:11]
	v_lshlrev_b32_e32 v14, 16, v9
	v_cvt_pk_bf16_f32 v8, v10, v11
	ds_read_b128 v[10:13], v0 offset:8576
	v_and_b32_e32 v15, 0xffff0000, v9
	v_pk_mul_f32 v[14:15], v[16:17], v[14:15]
	v_lshlrev_b32_e32 v16, 16, v168
	v_cvt_pk_bf16_f32 v9, v14, v15
	global_store_dwordx4 v[202:203], v[6:9], off
	ds_read_b128 v[6:9], v0 offset:8640
	s_waitcnt lgkmcnt(1)
	v_lshlrev_b32_e32 v14, 16, v10
	v_and_b32_e32 v15, 0xffff0000, v10
	v_and_b32_e32 v17, 0xffff0000, v168
	v_pk_mul_f32 v[14:15], v[16:17], v[14:15]
	v_lshlrev_b32_e32 v16, 16, v169
	v_cvt_pk_bf16_f32 v10, v14, v15
	v_lshlrev_b32_e32 v14, 16, v11
	v_and_b32_e32 v15, 0xffff0000, v11
	v_and_b32_e32 v17, 0xffff0000, v169
	v_pk_mul_f32 v[14:15], v[16:17], v[14:15]
	v_lshlrev_b32_e32 v16, 16, v170
	v_cvt_pk_bf16_f32 v11, v14, v15
	v_lshlrev_b32_e32 v14, 16, v12
	v_and_b32_e32 v15, 0xffff0000, v12
	v_and_b32_e32 v17, 0xffff0000, v170
	v_pk_mul_f32 v[14:15], v[16:17], v[14:15]
	v_lshlrev_b32_e32 v16, 16, v171
	v_cvt_pk_bf16_f32 v12, v14, v15
	v_lshlrev_b32_e32 v14, 16, v13
	v_and_b32_e32 v15, 0xffff0000, v13
	v_and_b32_e32 v17, 0xffff0000, v171
	v_pk_mul_f32 v[14:15], v[16:17], v[14:15]
	v_lshlrev_b32_e32 v16, 16, v159
	v_cvt_pk_bf16_f32 v13, v14, v15
	global_store_dwordx4 v[202:203], v[10:13], off offset:1024
	v_and_b32_e32 v17, 0xffff0000, v159
	s_nop 0
	v_lshlrev_b32_e32 v10, 16, v2
	v_and_b32_e32 v11, 0xffff0000, v2
	v_lshlrev_b32_e32 v12, 16, v164
	v_and_b32_e32 v13, 0xffff0000, v164
	v_pk_mul_f32 v[10:11], v[12:13], v[10:11]
	v_lshlrev_b32_e32 v12, 16, v165
	v_cvt_pk_bf16_f32 v2, v10, v11
	v_lshlrev_b32_e32 v10, 16, v3
	v_and_b32_e32 v11, 0xffff0000, v3
	v_and_b32_e32 v13, 0xffff0000, v165
	v_pk_mul_f32 v[10:11], v[12:13], v[10:11]
	v_lshlrev_b32_e32 v12, 16, v166
	v_cvt_pk_bf16_f32 v3, v10, v11
	v_lshlrev_b32_e32 v10, 16, v4
	v_and_b32_e32 v11, 0xffff0000, v4
	v_and_b32_e32 v13, 0xffff0000, v166
	v_pk_mul_f32 v[10:11], v[12:13], v[10:11]
	v_lshlrev_b32_e32 v12, 16, v167
	v_cvt_pk_bf16_f32 v4, v10, v11
	v_lshlrev_b32_e32 v10, 16, v5
	v_and_b32_e32 v11, 0xffff0000, v5
	v_and_b32_e32 v13, 0xffff0000, v167
	v_pk_mul_f32 v[10:11], v[12:13], v[10:11]
	v_lshlrev_b32_e32 v12, 16, v163
	v_cvt_pk_bf16_f32 v5, v10, v11
	global_store_dwordx4 v[200:201], v[2:5], off
	s_waitcnt lgkmcnt(0)
	v_lshlrev_b32_e32 v10, 16, v9
	v_and_b32_e32 v11, 0xffff0000, v9
	v_lshlrev_b32_e32 v2, 16, v6
	v_and_b32_e32 v3, 0xffff0000, v6
	v_lshlrev_b32_e32 v4, 16, v160
	v_and_b32_e32 v5, 0xffff0000, v160
	v_pk_mul_f32 v[2:3], v[4:5], v[2:3]
	v_lshlrev_b32_e32 v4, 16, v7
	v_and_b32_e32 v5, 0xffff0000, v7
	v_lshlrev_b32_e32 v6, 16, v161
	v_and_b32_e32 v7, 0xffff0000, v161
	v_pk_mul_f32 v[4:5], v[6:7], v[4:5]
	v_cvt_pk_bf16_f32 v2, v2, v3
	v_cvt_pk_bf16_f32 v3, v4, v5
	v_lshlrev_b32_e32 v4, 16, v8
	v_and_b32_e32 v5, 0xffff0000, v8
	v_lshlrev_b32_e32 v6, 16, v162
	v_and_b32_e32 v7, 0xffff0000, v162
	v_pk_mul_f32 v[4:5], v[6:7], v[4:5]
	ds_read_b128 v[6:9], v0 offset:256
	v_and_b32_e32 v13, 0xffff0000, v163
	v_pk_mul_f32 v[10:11], v[12:13], v[10:11]
	v_cvt_pk_bf16_f32 v4, v4, v5
	v_cvt_pk_bf16_f32 v5, v10, v11
	global_store_dwordx4 v[200:201], v[2:5], off offset:1024
	ds_read_b128 v[2:5], v0 offset:320
	s_waitcnt lgkmcnt(1)
	v_lshlrev_b32_e32 v10, 16, v6
	v_and_b32_e32 v11, 0xffff0000, v6
	v_lshlrev_b32_e32 v12, 16, v156
	v_and_b32_e32 v13, 0xffff0000, v156
	v_pk_mul_f32 v[10:11], v[12:13], v[10:11]
	v_lshlrev_b32_e32 v12, 16, v157
	v_cvt_pk_bf16_f32 v6, v10, v11
	v_lshlrev_b32_e32 v10, 16, v7
	v_and_b32_e32 v11, 0xffff0000, v7
	v_and_b32_e32 v13, 0xffff0000, v157
	v_pk_mul_f32 v[10:11], v[12:13], v[10:11]
	v_lshlrev_b32_e32 v12, 16, v158
	v_cvt_pk_bf16_f32 v7, v10, v11
	v_lshlrev_b32_e32 v10, 16, v8
	v_and_b32_e32 v11, 0xffff0000, v8
	v_and_b32_e32 v13, 0xffff0000, v158
	v_pk_mul_f32 v[10:11], v[12:13], v[10:11]
	v_lshlrev_b32_e32 v14, 16, v9
	v_cvt_pk_bf16_f32 v8, v10, v11
	ds_read_b128 v[10:13], v0 offset:8704
	v_and_b32_e32 v15, 0xffff0000, v9
	v_pk_mul_f32 v[14:15], v[16:17], v[14:15]
	v_lshlrev_b32_e32 v16, 16, v152
	v_cvt_pk_bf16_f32 v9, v14, v15
	global_store_dwordx4 v[198:199], v[6:9], off
	ds_read_b128 v[6:9], v0 offset:8768
	s_waitcnt lgkmcnt(1)
	v_lshlrev_b32_e32 v14, 16, v10
	v_and_b32_e32 v15, 0xffff0000, v10
	v_and_b32_e32 v17, 0xffff0000, v152
	v_pk_mul_f32 v[14:15], v[16:17], v[14:15]
	v_lshlrev_b32_e32 v16, 16, v153
	v_cvt_pk_bf16_f32 v10, v14, v15
	v_lshlrev_b32_e32 v14, 16, v11
	v_and_b32_e32 v15, 0xffff0000, v11
	v_and_b32_e32 v17, 0xffff0000, v153
	v_pk_mul_f32 v[14:15], v[16:17], v[14:15]
	v_lshlrev_b32_e32 v16, 16, v154
	v_cvt_pk_bf16_f32 v11, v14, v15
	v_lshlrev_b32_e32 v14, 16, v12
	v_and_b32_e32 v15, 0xffff0000, v12
	v_and_b32_e32 v17, 0xffff0000, v154
	v_pk_mul_f32 v[14:15], v[16:17], v[14:15]
	v_lshlrev_b32_e32 v16, 16, v155
	v_cvt_pk_bf16_f32 v12, v14, v15
	v_lshlrev_b32_e32 v14, 16, v13
	v_and_b32_e32 v15, 0xffff0000, v13
	v_and_b32_e32 v17, 0xffff0000, v155
	v_pk_mul_f32 v[14:15], v[16:17], v[14:15]
	v_lshlrev_b32_e32 v16, 16, v143
	v_cvt_pk_bf16_f32 v13, v14, v15
	global_store_dwordx4 v[198:199], v[10:13], off offset:1024
	v_and_b32_e32 v17, 0xffff0000, v143
	s_nop 0
	v_lshlrev_b32_e32 v10, 16, v2
	v_and_b32_e32 v11, 0xffff0000, v2
	v_lshlrev_b32_e32 v12, 16, v148
	v_and_b32_e32 v13, 0xffff0000, v148
	v_pk_mul_f32 v[10:11], v[12:13], v[10:11]
	v_lshlrev_b32_e32 v12, 16, v149
	v_cvt_pk_bf16_f32 v2, v10, v11
	v_lshlrev_b32_e32 v10, 16, v3
	v_and_b32_e32 v11, 0xffff0000, v3
	v_and_b32_e32 v13, 0xffff0000, v149
	v_pk_mul_f32 v[10:11], v[12:13], v[10:11]
	v_lshlrev_b32_e32 v12, 16, v150
	v_cvt_pk_bf16_f32 v3, v10, v11
	v_lshlrev_b32_e32 v10, 16, v4
	v_and_b32_e32 v11, 0xffff0000, v4
	v_and_b32_e32 v13, 0xffff0000, v150
	v_pk_mul_f32 v[10:11], v[12:13], v[10:11]
	v_lshlrev_b32_e32 v12, 16, v151
	v_cvt_pk_bf16_f32 v4, v10, v11
	v_lshlrev_b32_e32 v10, 16, v5
	v_and_b32_e32 v11, 0xffff0000, v5
	v_and_b32_e32 v13, 0xffff0000, v151
	v_pk_mul_f32 v[10:11], v[12:13], v[10:11]
	v_lshlrev_b32_e32 v12, 16, v147
	v_cvt_pk_bf16_f32 v5, v10, v11
	global_store_dwordx4 v[196:197], v[2:5], off
	s_waitcnt lgkmcnt(0)
	v_lshlrev_b32_e32 v10, 16, v9
	v_and_b32_e32 v11, 0xffff0000, v9
	v_lshlrev_b32_e32 v2, 16, v6
	v_and_b32_e32 v3, 0xffff0000, v6
	v_lshlrev_b32_e32 v4, 16, v144
	v_and_b32_e32 v5, 0xffff0000, v144
	v_pk_mul_f32 v[2:3], v[4:5], v[2:3]
	v_lshlrev_b32_e32 v4, 16, v7
	v_and_b32_e32 v5, 0xffff0000, v7
	v_lshlrev_b32_e32 v6, 16, v145
	v_and_b32_e32 v7, 0xffff0000, v145
	v_pk_mul_f32 v[4:5], v[6:7], v[4:5]
	v_cvt_pk_bf16_f32 v2, v2, v3
	v_cvt_pk_bf16_f32 v3, v4, v5
	v_lshlrev_b32_e32 v4, 16, v8
	v_and_b32_e32 v5, 0xffff0000, v8
	v_lshlrev_b32_e32 v6, 16, v146
	v_and_b32_e32 v7, 0xffff0000, v146
	v_pk_mul_f32 v[4:5], v[6:7], v[4:5]
	ds_read_b128 v[6:9], v0 offset:384
	v_and_b32_e32 v13, 0xffff0000, v147
	v_pk_mul_f32 v[10:11], v[12:13], v[10:11]
	v_cvt_pk_bf16_f32 v4, v4, v5
	v_cvt_pk_bf16_f32 v5, v10, v11
	global_store_dwordx4 v[196:197], v[2:5], off offset:1024
	ds_read_b128 v[2:5], v0 offset:448
	s_waitcnt lgkmcnt(1)
	v_lshlrev_b32_e32 v10, 16, v6
	v_and_b32_e32 v11, 0xffff0000, v6
	v_lshlrev_b32_e32 v12, 16, v140
	v_and_b32_e32 v13, 0xffff0000, v140
	v_pk_mul_f32 v[10:11], v[12:13], v[10:11]
	v_lshlrev_b32_e32 v12, 16, v141
	v_cvt_pk_bf16_f32 v6, v10, v11
	v_lshlrev_b32_e32 v10, 16, v7
	v_and_b32_e32 v11, 0xffff0000, v7
	v_and_b32_e32 v13, 0xffff0000, v141
	v_pk_mul_f32 v[10:11], v[12:13], v[10:11]
	v_lshlrev_b32_e32 v12, 16, v142
	v_cvt_pk_bf16_f32 v7, v10, v11
	v_lshlrev_b32_e32 v10, 16, v8
	v_and_b32_e32 v11, 0xffff0000, v8
	v_and_b32_e32 v13, 0xffff0000, v142
	v_pk_mul_f32 v[10:11], v[12:13], v[10:11]
	v_lshlrev_b32_e32 v14, 16, v9
	v_cvt_pk_bf16_f32 v8, v10, v11
	ds_read_b128 v[10:13], v0 offset:8832
	v_and_b32_e32 v15, 0xffff0000, v9
	v_pk_mul_f32 v[14:15], v[16:17], v[14:15]
	s_nop 0
	v_cvt_pk_bf16_f32 v9, v14, v15
	global_store_dwordx4 v[194:195], v[6:9], off
	ds_read_b128 v[6:9], v0 offset:8896
	s_waitcnt lgkmcnt(1)
	v_lshlrev_b32_e32 v0, 16, v10
	v_and_b32_e32 v1, 0xffff0000, v10
	v_lshlrev_b32_e32 v14, 16, v128
	v_and_b32_e32 v15, 0xffff0000, v128
	v_pk_mul_f32 v[0:1], v[14:15], v[0:1]
	v_lshlrev_b32_e32 v14, 16, v129
	v_cvt_pk_bf16_f32 v10, v0, v1
	v_lshlrev_b32_e32 v0, 16, v11
	v_and_b32_e32 v1, 0xffff0000, v11
	v_and_b32_e32 v15, 0xffff0000, v129
	v_pk_mul_f32 v[0:1], v[14:15], v[0:1]
	v_lshlrev_b32_e32 v14, 16, v130
	v_cvt_pk_bf16_f32 v11, v0, v1
	v_lshlrev_b32_e32 v0, 16, v12
	v_and_b32_e32 v1, 0xffff0000, v12
	v_and_b32_e32 v15, 0xffff0000, v130
	v_pk_mul_f32 v[0:1], v[14:15], v[0:1]
	v_lshlrev_b32_e32 v14, 16, v131
	v_cvt_pk_bf16_f32 v12, v0, v1
	v_lshlrev_b32_e32 v0, 16, v13
	v_and_b32_e32 v1, 0xffff0000, v13
	v_and_b32_e32 v15, 0xffff0000, v131
	v_pk_mul_f32 v[0:1], v[14:15], v[0:1]
	s_nop 0
	v_cvt_pk_bf16_f32 v13, v0, v1
	global_store_dwordx4 v[194:195], v[10:13], off offset:1024
	v_lshlrev_b32_e32 v0, 16, v2
	v_and_b32_e32 v1, 0xffff0000, v2
	v_lshlrev_b32_e32 v10, 16, v136
	v_and_b32_e32 v11, 0xffff0000, v136
	v_pk_mul_f32 v[0:1], v[10:11], v[0:1]
	v_lshlrev_b32_e32 v2, 16, v3
	v_and_b32_e32 v3, 0xffff0000, v3
	v_lshlrev_b32_e32 v10, 16, v137
	v_and_b32_e32 v11, 0xffff0000, v137
	v_pk_mul_f32 v[2:3], v[10:11], v[2:3]
	v_cvt_pk_bf16_f32 v0, v0, v1
	v_cvt_pk_bf16_f32 v1, v2, v3
	v_lshlrev_b32_e32 v2, 16, v4
	v_and_b32_e32 v3, 0xffff0000, v4
	v_lshlrev_b32_e32 v10, 16, v138
	v_and_b32_e32 v11, 0xffff0000, v138
	v_pk_mul_f32 v[2:3], v[10:11], v[2:3]
	v_lshlrev_b32_e32 v4, 16, v5
	v_and_b32_e32 v5, 0xffff0000, v5
	v_lshlrev_b32_e32 v10, 16, v139
	v_and_b32_e32 v11, 0xffff0000, v139
	v_pk_mul_f32 v[4:5], v[10:11], v[4:5]
	v_cvt_pk_bf16_f32 v2, v2, v3
	v_cvt_pk_bf16_f32 v3, v4, v5
	global_store_dwordx4 v[192:193], v[0:3], off
	v_lshlrev_b32_e32 v4, 16, v133
	v_and_b32_e32 v5, 0xffff0000, v133
	s_waitcnt lgkmcnt(0)
	v_lshlrev_b32_e32 v0, 16, v6
	v_and_b32_e32 v1, 0xffff0000, v6
	v_lshlrev_b32_e32 v2, 16, v132
	v_and_b32_e32 v3, 0xffff0000, v132
	v_pk_mul_f32 v[0:1], v[2:3], v[0:1]
	v_lshlrev_b32_e32 v2, 16, v7
	v_and_b32_e32 v3, 0xffff0000, v7
	v_pk_mul_f32 v[2:3], v[4:5], v[2:3]
	v_cvt_pk_bf16_f32 v0, v0, v1
	v_cvt_pk_bf16_f32 v1, v2, v3
	v_lshlrev_b32_e32 v2, 16, v8
	v_and_b32_e32 v3, 0xffff0000, v8
	v_lshlrev_b32_e32 v4, 16, v134
	v_and_b32_e32 v5, 0xffff0000, v134
	v_pk_mul_f32 v[2:3], v[4:5], v[2:3]
	v_lshlrev_b32_e32 v4, 16, v9
	v_and_b32_e32 v5, 0xffff0000, v9
	v_lshlrev_b32_e32 v6, 16, v135
	v_and_b32_e32 v7, 0xffff0000, v135
	v_pk_mul_f32 v[4:5], v[6:7], v[4:5]
	v_cvt_pk_bf16_f32 v2, v2, v3
	v_cvt_pk_bf16_f32 v3, v4, v5
	global_store_dwordx4 v[192:193], v[0:3], off offset:1024
	s_barrier
	s_waitcnt vmcnt(0)
	s_barrier
	s_cbranch_vccnz .LBB0_434
	v_mbcnt_lo_u32_b32 v0, -1, 0
	v_mbcnt_hi_u32_b32 v0, -1, v0
	s_nop 0
	v_cmp_eq_u32_e32 vcc, 0, v0
	s_and_saveexec_b64 s[0:1], vcc
	s_cbranch_execz .LBB0_433
	v_readlane_b32 s4, v251, 24
	v_readlane_b32 s5, v251, 25
	s_andn2_b64 vcc, exec, s[4:5]
	s_cbranch_vccnz .LBB0_417
	buffer_wbl2 sc1
	s_waitcnt vmcnt(0)

.LBB0_440:
	v_mov_b32_e32 v1, v208
	v_mov_b32_e32 v164, v209
	s_add_u32 s19, s84, s42
	s_addc_u32 s21, s85, s43
	v_lshlrev_b32_e32 v2, 4, v1
	s_add_u32 s38, s19, s8
	v_lshl_add_u32 v2, v164, 8, v2
	s_addc_u32 s39, s21, s9
	v_ashrrev_i32_e32 v3, 31, v2
	v_lshl_add_u64 v[2:3], s[38:39], 0, v[2:3]
	v_lshl_add_u64 v[132:133], v[2:3], 0, s[12:13]
	v_add_co_u32_e32 v2, vcc, s80, v2
	v_lshlrev_b32_e32 v164, 3, v164
	s_nop 0
	v_addc_co_u32_e32 v3, vcc, 0, v3, vcc
	global_load_dwordx4 v[156:159], v[132:133], off offset:1024 nt
	global_load_dwordx4 v[152:155], v[132:133], off offset:2048 nt
	global_load_dwordx4 v[160:163], v[2:3], off offset:-4096 nt
	global_load_dwordx4 v[148:151], v[132:133], off offset:3072 nt
	global_load_dwordx4 v[144:147], v[2:3], off nt
	global_load_dwordx4 v[140:143], v[2:3], off offset:1024 nt
	global_load_dwordx4 v[136:139], v[2:3], off offset:2048 nt
	s_nop 0
	global_load_dwordx4 v[132:135], v[2:3], off offset:3072 nt
	v_add_u32_e32 v2, s72, v1
	s_lshl_b64 s[28:29], s[28:29], 19
	s_add_u32 s19, s69, s28
	s_addc_u32 s21, s70, s29
	s_lshl_b32 s28, s40, 3
	s_or_b32 s28, s28, s71
	s_ashr_i32 s29, s28, 31
	s_lshl_b64 s[28:29], s[28:29], 14
	s_add_u32 s28, s19, s28
	v_ashrrev_i32_e32 v3, 31, v2
	s_addc_u32 s29, s21, s29
	v_lshlrev_b64 v[2:3], 6, v[2:3]
	v_ashrrev_i32_e32 v165, 31, v164
	v_lshl_add_u64 v[2:3], s[28:29], 0, v[2:3]
	s_waitcnt vmcnt(0)
	v_cvt_f32_ubyte0_e32 v1, v160
	v_lshl_add_u64 v[2:3], v[164:165], 1, v[2:3]
	v_max_f32_e32 v164, 1.0, v1
	v_cvt_f32_ubyte0_e32 v1, v161
	v_max_f32_e32 v166, 1.0, v1
	v_cvt_f32_ubyte1_e32 v1, v160
	v_max_f32_e32 v165, 1.0, v1
	v_cvt_f32_ubyte1_e32 v1, v161
	v_pk_mul_f32 v[164:165], v[164:165], s[16:17] op_sel_hi:[1,0]
	v_max_f32_e32 v167, 1.0, v1
	v_pk_mul_f32 v[128:129], v[128:129], v[164:165]
	v_pk_mul_f32 v[164:165], v[166:167], s[16:17] op_sel_hi:[1,0]
	v_cvt_f32_ubyte2_e32 v1, v160
	v_pk_mul_f32 v[164:165], v[124:125], v[164:165]
	v_max_f32_e32 v124, 1.0, v1
	v_cvt_f32_ubyte2_e32 v1, v161
	v_max_f32_e32 v166, 1.0, v1
	v_cvt_f32_ubyte3_e32 v1, v160
	v_max_f32_e32 v125, 1.0, v1
	v_cvt_f32_ubyte3_e32 v1, v161
	v_pk_mul_f32 v[124:125], v[124:125], s[16:17] op_sel_hi:[1,0]
	v_max_f32_e32 v167, 1.0, v1
	v_pk_mul_f32 v[130:131], v[130:131], v[124:125]
	v_pk_mul_f32 v[124:125], v[166:167], s[16:17] op_sel_hi:[1,0]
	v_cvt_f32_ubyte0_e32 v1, v162
	v_pk_mul_f32 v[160:161], v[126:127], v[124:125]
	v_cvt_pk_bf16_f32 v124, v128, v129
	v_cvt_pk_bf16_f32 v125, v130, v131
	v_cvt_pk_bf16_f32 v126, v164, v165
	v_cvt_pk_bf16_f32 v127, v160, v161
	global_store_dwordx4 v[2:3], v[124:127], off
	s_mov_b32 s40, s18
	s_mov_b32 s28, s20
	v_max_f32_e32 v124, 1.0, v1
	v_cvt_f32_ubyte0_e32 v1, v163
	v_max_f32_e32 v126, 1.0, v1
	v_cvt_f32_ubyte1_e32 v1, v162
	v_max_f32_e32 v125, 1.0, v1
	v_cvt_f32_ubyte1_e32 v1, v163
	v_pk_mul_f32 v[124:125], v[124:125], s[16:17] op_sel_hi:[1,0]
	v_max_f32_e32 v127, 1.0, v1
	v_pk_mul_f32 v[120:121], v[120:121], v[124:125]
	v_pk_mul_f32 v[124:125], v[126:127], s[16:17] op_sel_hi:[1,0]
	v_cvt_f32_ubyte2_e32 v1, v162
	v_pk_mul_f32 v[116:117], v[116:117], v[124:125]
	v_max_f32_e32 v124, 1.0, v1
	v_cvt_f32_ubyte2_e32 v1, v163
	v_max_f32_e32 v126, 1.0, v1
	v_cvt_f32_ubyte3_e32 v1, v162
	v_max_f32_e32 v125, 1.0, v1
	v_cvt_f32_ubyte3_e32 v1, v163
	v_pk_mul_f32 v[124:125], v[124:125], s[16:17] op_sel_hi:[1,0]
	v_max_f32_e32 v127, 1.0, v1
	v_pk_mul_f32 v[122:123], v[122:123], v[124:125]
	v_pk_mul_f32 v[124:125], v[126:127], s[16:17] op_sel_hi:[1,0]
	v_cvt_f32_ubyte0_e32 v1, v156
	v_pk_mul_f32 v[124:125], v[118:119], v[124:125]
	v_cvt_pk_bf16_f32 v118, v120, v121
	v_cvt_pk_bf16_f32 v120, v116, v117
	v_add_co_u32_e32 v116, vcc, s67, v2
	v_cvt_pk_bf16_f32 v119, v122, v123
	v_cvt_pk_bf16_f32 v121, v124, v125
	v_addc_co_u32_e32 v117, vcc, 0, v3, vcc
	global_store_dwordx4 v[116:117], v[118:121], off
	s_mov_b64 s[46:47], s[26:27]
	s_mov_b64 s[38:39], s[22:23]
	v_max_f32_e32 v118, 1.0, v1
	v_cvt_f32_ubyte0_e32 v1, v157
	v_max_f32_e32 v120, 1.0, v1
	v_cvt_f32_ubyte1_e32 v1, v156
	v_max_f32_e32 v119, 1.0, v1
	v_cvt_f32_ubyte1_e32 v1, v157
	v_pk_mul_f32 v[118:119], v[118:119], s[16:17] op_sel_hi:[1,0]
	v_max_f32_e32 v121, 1.0, v1
	v_pk_mul_f32 v[112:113], v[112:113], v[118:119]
	v_pk_mul_f32 v[118:119], v[120:121], s[16:17] op_sel_hi:[1,0]
	v_cvt_f32_ubyte2_e32 v1, v156
	v_pk_mul_f32 v[118:119], v[108:109], v[118:119]
	v_max_f32_e32 v108, 1.0, v1
	v_cvt_f32_ubyte2_e32 v1, v157
	v_max_f32_e32 v120, 1.0, v1
	v_cvt_f32_ubyte3_e32 v1, v156
	v_max_f32_e32 v109, 1.0, v1
	v_cvt_f32_ubyte3_e32 v1, v157
	v_pk_mul_f32 v[108:109], v[108:109], s[16:17] op_sel_hi:[1,0]
	v_max_f32_e32 v121, 1.0, v1
	v_pk_mul_f32 v[114:115], v[114:115], v[108:109]
	v_pk_mul_f32 v[108:109], v[120:121], s[16:17] op_sel_hi:[1,0]
	v_cvt_f32_ubyte0_e32 v1, v158
	v_pk_mul_f32 v[120:121], v[110:111], v[108:109]
	v_cvt_pk_bf16_f32 v108, v112, v113
	v_cvt_pk_bf16_f32 v109, v114, v115
	v_cvt_pk_bf16_f32 v110, v118, v119
	v_cvt_pk_bf16_f32 v111, v120, v121
	global_store_dwordx4 v[2:3], v[108:111], off offset:1024
	s_nop 1
	v_max_f32_e32 v108, 1.0, v1
	v_cvt_f32_ubyte0_e32 v1, v159
	v_max_f32_e32 v110, 1.0, v1
	v_cvt_f32_ubyte1_e32 v1, v158
	v_max_f32_e32 v109, 1.0, v1
	v_cvt_f32_ubyte1_e32 v1, v159
	v_pk_mul_f32 v[108:109], v[108:109], s[16:17] op_sel_hi:[1,0]
	v_max_f32_e32 v111, 1.0, v1
	v_pk_mul_f32 v[104:105], v[104:105], v[108:109]
	v_pk_mul_f32 v[108:109], v[110:111], s[16:17] op_sel_hi:[1,0]
	v_cvt_f32_ubyte2_e32 v1, v158
	v_pk_mul_f32 v[108:109], v[100:101], v[108:109]
	v_max_f32_e32 v100, 1.0, v1
	v_cvt_f32_ubyte2_e32 v1, v159
	v_max_f32_e32 v110, 1.0, v1
	v_cvt_f32_ubyte3_e32 v1, v158
	v_max_f32_e32 v101, 1.0, v1
	v_cvt_f32_ubyte3_e32 v1, v159
	v_pk_mul_f32 v[100:101], v[100:101], s[16:17] op_sel_hi:[1,0]
	v_max_f32_e32 v111, 1.0, v1
	v_pk_mul_f32 v[106:107], v[106:107], v[100:101]
	v_pk_mul_f32 v[100:101], v[110:111], s[16:17] op_sel_hi:[1,0]
	v_cvt_f32_ubyte0_e32 v1, v152
	v_pk_mul_f32 v[110:111], v[102:103], v[100:101]
	v_cvt_pk_bf16_f32 v100, v104, v105
	v_cvt_pk_bf16_f32 v101, v106, v107
	v_cvt_pk_bf16_f32 v102, v108, v109
	v_cvt_pk_bf16_f32 v103, v110, v111
	global_store_dwordx4 v[116:117], v[100:103], off offset:1024
	s_nop 1
	v_max_f32_e32 v100, 1.0, v1
	v_cvt_f32_ubyte0_e32 v1, v153
	v_max_f32_e32 v102, 1.0, v1
	v_cvt_f32_ubyte1_e32 v1, v152
	v_max_f32_e32 v101, 1.0, v1
	v_cvt_f32_ubyte1_e32 v1, v153
	v_pk_mul_f32 v[100:101], v[100:101], s[16:17] op_sel_hi:[1,0]
	v_max_f32_e32 v103, 1.0, v1
	v_pk_mul_f32 v[96:97], v[96:97], v[100:101]
	v_pk_mul_f32 v[100:101], v[102:103], s[16:17] op_sel_hi:[1,0]
	v_cvt_f32_ubyte2_e32 v1, v152
	v_pk_mul_f32 v[100:101], v[92:93], v[100:101]
	v_max_f32_e32 v92, 1.0, v1
	v_cvt_f32_ubyte2_e32 v1, v153
	v_max_f32_e32 v102, 1.0, v1
	v_cvt_f32_ubyte3_e32 v1, v152
	v_max_f32_e32 v93, 1.0, v1
	v_cvt_f32_ubyte3_e32 v1, v153
	v_pk_mul_f32 v[92:93], v[92:93], s[16:17] op_sel_hi:[1,0]
	v_max_f32_e32 v103, 1.0, v1
	v_pk_mul_f32 v[98:99], v[98:99], v[92:93]
	v_pk_mul_f32 v[92:93], v[102:103], s[16:17] op_sel_hi:[1,0]
	v_cvt_f32_ubyte0_e32 v1, v154
	v_pk_mul_f32 v[102:103], v[94:95], v[92:93]
	v_cvt_pk_bf16_f32 v92, v96, v97
	v_cvt_pk_bf16_f32 v93, v98, v99
	v_cvt_pk_bf16_f32 v94, v100, v101
	v_cvt_pk_bf16_f32 v95, v102, v103
	global_store_dwordx4 v[2:3], v[92:95], off offset:2048
	s_nop 1
	v_max_f32_e32 v92, 1.0, v1
	v_cvt_f32_ubyte0_e32 v1, v155
	v_max_f32_e32 v94, 1.0, v1
	v_cvt_f32_ubyte1_e32 v1, v154
	v_max_f32_e32 v93, 1.0, v1
	v_cvt_f32_ubyte1_e32 v1, v155
	v_pk_mul_f32 v[92:93], v[92:93], s[16:17] op_sel_hi:[1,0]
	v_max_f32_e32 v95, 1.0, v1
	v_pk_mul_f32 v[88:89], v[88:89], v[92:93]
	v_pk_mul_f32 v[92:93], v[94:95], s[16:17] op_sel_hi:[1,0]
	v_cvt_f32_ubyte2_e32 v1, v154
	v_pk_mul_f32 v[92:93], v[84:85], v[92:93]
	v_max_f32_e32 v84, 1.0, v1
	v_cvt_f32_ubyte2_e32 v1, v155
	v_max_f32_e32 v94, 1.0, v1
	v_cvt_f32_ubyte3_e32 v1, v154
	v_max_f32_e32 v85, 1.0, v1
	v_cvt_f32_ubyte3_e32 v1, v155
	v_pk_mul_f32 v[84:85], v[84:85], s[16:17] op_sel_hi:[1,0]
	v_max_f32_e32 v95, 1.0, v1
	v_pk_mul_f32 v[90:91], v[90:91], v[84:85]
	v_pk_mul_f32 v[84:85], v[94:95], s[16:17] op_sel_hi:[1,0]
	v_cvt_f32_ubyte0_e32 v1, v148
	v_pk_mul_f32 v[94:95], v[86:87], v[84:85]
	v_cvt_pk_bf16_f32 v84, v88, v89
	v_cvt_pk_bf16_f32 v85, v90, v91
	v_cvt_pk_bf16_f32 v86, v92, v93
	v_cvt_pk_bf16_f32 v87, v94, v95
	global_store_dwordx4 v[116:117], v[84:87], off offset:2048
	s_nop 1
	v_max_f32_e32 v84, 1.0, v1
	v_cvt_f32_ubyte0_e32 v1, v149
	v_max_f32_e32 v86, 1.0, v1
	v_cvt_f32_ubyte1_e32 v1, v148
	v_max_f32_e32 v85, 1.0, v1
	v_cvt_f32_ubyte1_e32 v1, v149
	v_pk_mul_f32 v[84:85], v[84:85], s[16:17] op_sel_hi:[1,0]
	v_max_f32_e32 v87, 1.0, v1
	v_pk_mul_f32 v[80:81], v[80:81], v[84:85]
	v_pk_mul_f32 v[84:85], v[86:87], s[16:17] op_sel_hi:[1,0]
	v_cvt_f32_ubyte2_e32 v1, v148
	v_pk_mul_f32 v[84:85], v[76:77], v[84:85]
	v_max_f32_e32 v76, 1.0, v1
	v_cvt_f32_ubyte2_e32 v1, v149
	v_max_f32_e32 v86, 1.0, v1
	v_cvt_f32_ubyte3_e32 v1, v148
	v_max_f32_e32 v77, 1.0, v1
	v_cvt_f32_ubyte3_e32 v1, v149
	v_pk_mul_f32 v[76:77], v[76:77], s[16:17] op_sel_hi:[1,0]
	v_max_f32_e32 v87, 1.0, v1
	v_pk_mul_f32 v[82:83], v[82:83], v[76:77]
	v_pk_mul_f32 v[76:77], v[86:87], s[16:17] op_sel_hi:[1,0]
	v_cvt_f32_ubyte0_e32 v1, v150
	v_pk_mul_f32 v[86:87], v[78:79], v[76:77]
	v_cvt_pk_bf16_f32 v76, v80, v81
	v_cvt_pk_bf16_f32 v77, v82, v83
	v_cvt_pk_bf16_f32 v78, v84, v85
	v_cvt_pk_bf16_f32 v79, v86, v87
	global_store_dwordx4 v[2:3], v[76:79], off offset:3072
	s_nop 1
	v_max_f32_e32 v76, 1.0, v1
	v_cvt_f32_ubyte0_e32 v1, v151
	v_max_f32_e32 v78, 1.0, v1
	v_cvt_f32_ubyte1_e32 v1, v150
	v_max_f32_e32 v77, 1.0, v1
	v_cvt_f32_ubyte1_e32 v1, v151
	v_pk_mul_f32 v[76:77], v[76:77], s[16:17] op_sel_hi:[1,0]
	v_max_f32_e32 v79, 1.0, v1
	v_pk_mul_f32 v[72:73], v[72:73], v[76:77]
	v_pk_mul_f32 v[76:77], v[78:79], s[16:17] op_sel_hi:[1,0]
	v_cvt_f32_ubyte2_e32 v1, v150
	v_pk_mul_f32 v[76:77], v[68:69], v[76:77]
	v_max_f32_e32 v68, 1.0, v1
	v_cvt_f32_ubyte2_e32 v1, v151
	v_max_f32_e32 v78, 1.0, v1
	v_cvt_f32_ubyte3_e32 v1, v150
	v_max_f32_e32 v69, 1.0, v1
	v_cvt_f32_ubyte3_e32 v1, v151
	v_pk_mul_f32 v[68:69], v[68:69], s[16:17] op_sel_hi:[1,0]
	v_max_f32_e32 v79, 1.0, v1
	v_pk_mul_f32 v[74:75], v[74:75], v[68:69]
	v_pk_mul_f32 v[68:69], v[78:79], s[16:17] op_sel_hi:[1,0]
	v_cvt_f32_ubyte0_e32 v1, v144
	v_pk_mul_f32 v[78:79], v[70:71], v[68:69]
	v_cvt_pk_bf16_f32 v68, v72, v73
	v_cvt_pk_bf16_f32 v69, v74, v75
	v_cvt_pk_bf16_f32 v70, v76, v77
	v_cvt_pk_bf16_f32 v71, v78, v79
	global_store_dwordx4 v[116:117], v[68:71], off offset:3072
	s_nop 1
	v_max_f32_e32 v68, 1.0, v1
	v_cvt_f32_ubyte0_e32 v1, v145
	v_max_f32_e32 v70, 1.0, v1
	v_cvt_f32_ubyte1_e32 v1, v144
	v_max_f32_e32 v69, 1.0, v1
	v_cvt_f32_ubyte1_e32 v1, v145
	v_pk_mul_f32 v[68:69], v[68:69], s[16:17] op_sel_hi:[1,0]
	v_max_f32_e32 v71, 1.0, v1
	v_pk_mul_f32 v[64:65], v[64:65], v[68:69]
	v_pk_mul_f32 v[68:69], v[70:71], s[16:17] op_sel_hi:[1,0]
	v_cvt_f32_ubyte2_e32 v1, v144
	v_pk_mul_f32 v[60:61], v[60:61], v[68:69]
	v_max_f32_e32 v68, 1.0, v1
	v_cvt_f32_ubyte2_e32 v1, v145
	v_max_f32_e32 v70, 1.0, v1
	v_cvt_f32_ubyte3_e32 v1, v144
	v_max_f32_e32 v69, 1.0, v1
	v_cvt_f32_ubyte3_e32 v1, v145
	v_pk_mul_f32 v[68:69], v[68:69], s[16:17] op_sel_hi:[1,0]
	v_max_f32_e32 v71, 1.0, v1
	v_pk_mul_f32 v[66:67], v[66:67], v[68:69]
	v_pk_mul_f32 v[68:69], v[70:71], s[16:17] op_sel_hi:[1,0]
	v_cvt_f32_ubyte0_e32 v1, v146
	v_pk_mul_f32 v[68:69], v[62:63], v[68:69]
	v_cvt_pk_bf16_f32 v62, v64, v65
	v_cvt_pk_bf16_f32 v64, v60, v61
	v_add_co_u32_e32 v60, vcc, s66, v2
	v_cvt_pk_bf16_f32 v63, v66, v67
	v_cvt_pk_bf16_f32 v65, v68, v69
	v_addc_co_u32_e32 v61, vcc, 0, v3, vcc
	global_store_dwordx4 v[60:61], v[62:65], off
	v_add_co_u32_e32 v2, vcc, s68, v2
	s_nop 0
	v_max_f32_e32 v62, 1.0, v1
	v_cvt_f32_ubyte0_e32 v1, v147
	v_max_f32_e32 v64, 1.0, v1
	v_cvt_f32_ubyte1_e32 v1, v146
	v_max_f32_e32 v63, 1.0, v1
	v_cvt_f32_ubyte1_e32 v1, v147
	v_pk_mul_f32 v[62:63], v[62:63], s[16:17] op_sel_hi:[1,0]
	v_max_f32_e32 v65, 1.0, v1
	v_pk_mul_f32 v[56:57], v[56:57], v[62:63]
	v_pk_mul_f32 v[62:63], v[64:65], s[16:17] op_sel_hi:[1,0]
	v_cvt_f32_ubyte2_e32 v1, v146
	v_pk_mul_f32 v[62:63], v[52:53], v[62:63]
	v_max_f32_e32 v52, 1.0, v1
	v_cvt_f32_ubyte2_e32 v1, v147
	v_max_f32_e32 v64, 1.0, v1
	v_cvt_f32_ubyte3_e32 v1, v146
	v_max_f32_e32 v53, 1.0, v1
	v_cvt_f32_ubyte3_e32 v1, v147
	v_pk_mul_f32 v[52:53], v[52:53], s[16:17] op_sel_hi:[1,0]
	v_max_f32_e32 v65, 1.0, v1
	v_pk_mul_f32 v[58:59], v[58:59], v[52:53]
	v_pk_mul_f32 v[52:53], v[64:65], s[16:17] op_sel_hi:[1,0]
	v_addc_co_u32_e32 v3, vcc, 0, v3, vcc
	v_pk_mul_f32 v[64:65], v[54:55], v[52:53]
	v_cvt_pk_bf16_f32 v52, v56, v57
	v_cvt_pk_bf16_f32 v53, v58, v59
	v_cvt_pk_bf16_f32 v54, v62, v63
	v_cvt_pk_bf16_f32 v55, v64, v65
	v_cvt_f32_ubyte0_e32 v1, v140
	global_store_dwordx4 v[2:3], v[52:55], off
	s_and_b64 vcc, exec, s[4:5]
	s_nop 0
	v_max_f32_e32 v52, 1.0, v1
	v_cvt_f32_ubyte0_e32 v1, v141
	v_max_f32_e32 v54, 1.0, v1
	v_cvt_f32_ubyte1_e32 v1, v140
	v_max_f32_e32 v53, 1.0, v1
	v_cvt_f32_ubyte1_e32 v1, v141
	v_pk_mul_f32 v[52:53], v[52:53], s[16:17] op_sel_hi:[1,0]
	v_max_f32_e32 v55, 1.0, v1
	v_pk_mul_f32 v[48:49], v[48:49], v[52:53]
	v_pk_mul_f32 v[52:53], v[54:55], s[16:17] op_sel_hi:[1,0]
	v_cvt_f32_ubyte2_e32 v1, v140
	v_pk_mul_f32 v[52:53], v[44:45], v[52:53]
	v_max_f32_e32 v44, 1.0, v1
	v_cvt_f32_ubyte2_e32 v1, v141
	v_max_f32_e32 v54, 1.0, v1
	v_cvt_f32_ubyte3_e32 v1, v140
	v_max_f32_e32 v45, 1.0, v1
	v_cvt_f32_ubyte3_e32 v1, v141
	v_pk_mul_f32 v[44:45], v[44:45], s[16:17] op_sel_hi:[1,0]
	v_max_f32_e32 v55, 1.0, v1
	v_pk_mul_f32 v[50:51], v[50:51], v[44:45]
	v_pk_mul_f32 v[44:45], v[54:55], s[16:17] op_sel_hi:[1,0]
	v_cvt_f32_ubyte0_e32 v1, v142
	v_pk_mul_f32 v[54:55], v[46:47], v[44:45]
	v_cvt_pk_bf16_f32 v44, v48, v49
	v_cvt_pk_bf16_f32 v45, v50, v51
	v_cvt_pk_bf16_f32 v46, v52, v53
	v_cvt_pk_bf16_f32 v47, v54, v55
	global_store_dwordx4 v[60:61], v[44:47], off offset:1024
	s_nop 1
	v_max_f32_e32 v44, 1.0, v1
	v_cvt_f32_ubyte0_e32 v1, v143
	v_max_f32_e32 v46, 1.0, v1
	v_cvt_f32_ubyte1_e32 v1, v142
	v_max_f32_e32 v45, 1.0, v1
	v_cvt_f32_ubyte1_e32 v1, v143
	v_pk_mul_f32 v[44:45], v[44:45], s[16:17] op_sel_hi:[1,0]
	v_max_f32_e32 v47, 1.0, v1
	v_pk_mul_f32 v[40:41], v[40:41], v[44:45]
	v_pk_mul_f32 v[44:45], v[46:47], s[16:17] op_sel_hi:[1,0]
	v_cvt_f32_ubyte2_e32 v1, v142
	v_pk_mul_f32 v[44:45], v[36:37], v[44:45]
	v_max_f32_e32 v36, 1.0, v1
	v_cvt_f32_ubyte2_e32 v1, v143
	v_max_f32_e32 v46, 1.0, v1
	v_cvt_f32_ubyte3_e32 v1, v142
	v_max_f32_e32 v37, 1.0, v1
	v_cvt_f32_ubyte3_e32 v1, v143
	v_pk_mul_f32 v[36:37], v[36:37], s[16:17] op_sel_hi:[1,0]
	v_max_f32_e32 v47, 1.0, v1
	v_pk_mul_f32 v[42:43], v[42:43], v[36:37]
	v_pk_mul_f32 v[36:37], v[46:47], s[16:17] op_sel_hi:[1,0]
	v_cvt_f32_ubyte0_e32 v1, v136
	v_pk_mul_f32 v[46:47], v[38:39], v[36:37]
	v_cvt_pk_bf16_f32 v36, v40, v41
	v_cvt_pk_bf16_f32 v37, v42, v43
	v_cvt_pk_bf16_f32 v38, v44, v45
	v_cvt_pk_bf16_f32 v39, v46, v47
	global_store_dwordx4 v[2:3], v[36:39], off offset:1024
	s_nop 1
	v_max_f32_e32 v36, 1.0, v1
	v_cvt_f32_ubyte0_e32 v1, v137
	v_max_f32_e32 v38, 1.0, v1
	v_cvt_f32_ubyte1_e32 v1, v136
	v_max_f32_e32 v37, 1.0, v1
	v_cvt_f32_ubyte1_e32 v1, v137
	v_pk_mul_f32 v[36:37], v[36:37], s[16:17] op_sel_hi:[1,0]
	v_max_f32_e32 v39, 1.0, v1
	v_pk_mul_f32 v[32:33], v[32:33], v[36:37]
	v_pk_mul_f32 v[36:37], v[38:39], s[16:17] op_sel_hi:[1,0]
	v_cvt_f32_ubyte2_e32 v1, v136
	v_pk_mul_f32 v[36:37], v[28:29], v[36:37]
	v_max_f32_e32 v28, 1.0, v1
	v_cvt_f32_ubyte2_e32 v1, v137
	v_max_f32_e32 v38, 1.0, v1
	v_cvt_f32_ubyte3_e32 v1, v136
	v_max_f32_e32 v29, 1.0, v1
	v_cvt_f32_ubyte3_e32 v1, v137
	v_pk_mul_f32 v[28:29], v[28:29], s[16:17] op_sel_hi:[1,0]
	v_max_f32_e32 v39, 1.0, v1
	v_pk_mul_f32 v[34:35], v[34:35], v[28:29]
	v_pk_mul_f32 v[28:29], v[38:39], s[16:17] op_sel_hi:[1,0]
	v_cvt_f32_ubyte0_e32 v1, v138
	v_pk_mul_f32 v[38:39], v[30:31], v[28:29]
	v_cvt_pk_bf16_f32 v28, v32, v33
	v_cvt_pk_bf16_f32 v29, v34, v35
	v_cvt_pk_bf16_f32 v30, v36, v37
	v_cvt_pk_bf16_f32 v31, v38, v39
	global_store_dwordx4 v[60:61], v[28:31], off offset:2048
	s_nop 1
	v_max_f32_e32 v28, 1.0, v1
	v_cvt_f32_ubyte0_e32 v1, v139
	v_max_f32_e32 v30, 1.0, v1
	v_cvt_f32_ubyte1_e32 v1, v138
	v_max_f32_e32 v29, 1.0, v1
	v_cvt_f32_ubyte1_e32 v1, v139
	v_pk_mul_f32 v[28:29], v[28:29], s[16:17] op_sel_hi:[1,0]
	v_max_f32_e32 v31, 1.0, v1
	v_pk_mul_f32 v[24:25], v[24:25], v[28:29]
	v_pk_mul_f32 v[28:29], v[30:31], s[16:17] op_sel_hi:[1,0]
	v_cvt_f32_ubyte2_e32 v1, v138
	v_pk_mul_f32 v[28:29], v[20:21], v[28:29]
	v_max_f32_e32 v20, 1.0, v1
	v_cvt_f32_ubyte2_e32 v1, v139
	v_max_f32_e32 v30, 1.0, v1
	v_cvt_f32_ubyte3_e32 v1, v138
	v_max_f32_e32 v21, 1.0, v1
	v_cvt_f32_ubyte3_e32 v1, v139
	v_pk_mul_f32 v[20:21], v[20:21], s[16:17] op_sel_hi:[1,0]
	v_max_f32_e32 v31, 1.0, v1
	v_pk_mul_f32 v[26:27], v[26:27], v[20:21]
	v_pk_mul_f32 v[20:21], v[30:31], s[16:17] op_sel_hi:[1,0]
	v_cvt_f32_ubyte0_e32 v1, v132
	v_pk_mul_f32 v[30:31], v[22:23], v[20:21]
	v_cvt_pk_bf16_f32 v20, v24, v25
	v_cvt_pk_bf16_f32 v21, v26, v27
	v_cvt_pk_bf16_f32 v22, v28, v29
	v_cvt_pk_bf16_f32 v23, v30, v31
	global_store_dwordx4 v[2:3], v[20:23], off offset:2048
	s_nop 1
	v_max_f32_e32 v20, 1.0, v1
	v_cvt_f32_ubyte0_e32 v1, v133
	v_max_f32_e32 v22, 1.0, v1
	v_cvt_f32_ubyte1_e32 v1, v132
	v_max_f32_e32 v21, 1.0, v1
	v_cvt_f32_ubyte1_e32 v1, v133
	v_pk_mul_f32 v[20:21], v[20:21], s[16:17] op_sel_hi:[1,0]
	v_max_f32_e32 v23, 1.0, v1
	v_pk_mul_f32 v[16:17], v[16:17], v[20:21]
	v_pk_mul_f32 v[20:21], v[22:23], s[16:17] op_sel_hi:[1,0]
	v_cvt_f32_ubyte2_e32 v1, v132
	v_pk_mul_f32 v[20:21], v[12:13], v[20:21]
	v_max_f32_e32 v12, 1.0, v1
	v_cvt_f32_ubyte2_e32 v1, v133
	v_max_f32_e32 v22, 1.0, v1
	v_cvt_f32_ubyte3_e32 v1, v132
	v_max_f32_e32 v13, 1.0, v1
	v_cvt_f32_ubyte3_e32 v1, v133
	v_pk_mul_f32 v[12:13], v[12:13], s[16:17] op_sel_hi:[1,0]
	v_max_f32_e32 v23, 1.0, v1
	v_pk_mul_f32 v[18:19], v[18:19], v[12:13]
	v_pk_mul_f32 v[12:13], v[22:23], s[16:17] op_sel_hi:[1,0]
	v_cvt_f32_ubyte0_e32 v1, v134
	v_pk_mul_f32 v[22:23], v[14:15], v[12:13]
	v_cvt_pk_bf16_f32 v12, v16, v17
	v_cvt_pk_bf16_f32 v13, v18, v19
	v_cvt_pk_bf16_f32 v14, v20, v21
	v_cvt_pk_bf16_f32 v15, v22, v23
	global_store_dwordx4 v[60:61], v[12:15], off offset:3072
	s_nop 1
	v_max_f32_e32 v12, 1.0, v1
	v_cvt_f32_ubyte0_e32 v1, v135
	v_max_f32_e32 v14, 1.0, v1
	v_cvt_f32_ubyte1_e32 v1, v134
	v_max_f32_e32 v13, 1.0, v1
	v_cvt_f32_ubyte1_e32 v1, v135
	v_pk_mul_f32 v[12:13], v[12:13], s[16:17] op_sel_hi:[1,0]
	v_max_f32_e32 v15, 1.0, v1
	v_pk_mul_f32 v[8:9], v[8:9], v[12:13]
	v_pk_mul_f32 v[12:13], v[14:15], s[16:17] op_sel_hi:[1,0]
	v_cvt_f32_ubyte2_e32 v1, v134
	v_pk_mul_f32 v[12:13], v[4:5], v[12:13]
	v_max_f32_e32 v4, 1.0, v1
	v_cvt_f32_ubyte2_e32 v1, v135
	v_max_f32_e32 v14, 1.0, v1
	v_cvt_f32_ubyte3_e32 v1, v134
	v_max_f32_e32 v5, 1.0, v1
	v_cvt_f32_ubyte3_e32 v1, v135
	v_pk_mul_f32 v[4:5], v[4:5], s[16:17] op_sel_hi:[1,0]
	v_max_f32_e32 v15, 1.0, v1
	v_pk_mul_f32 v[10:11], v[10:11], v[4:5]
	v_pk_mul_f32 v[4:5], v[14:15], s[16:17] op_sel_hi:[1,0]
	s_nop 0
	v_pk_mul_f32 v[14:15], v[6:7], v[4:5]
	v_cvt_pk_bf16_f32 v4, v8, v9
	v_cvt_pk_bf16_f32 v5, v10, v11
	v_cvt_pk_bf16_f32 v6, v12, v13
	v_cvt_pk_bf16_f32 v7, v14, v15
	global_store_dwordx4 v[2:3], v[4:7], off offset:3072
	s_cbranch_vccnz .LBB0_451

.LBB0_449:
	s_cmp_lg_u32 s46, 0x80000
	s_cbranch_scc1 .LBB0_448
	v_mov_b32_e32 v1, v209
	v_mov_b32_e32 v2, v208
	s_nop 0
	v_lshlrev_b32_e32 v2, 4, v2
	v_lshl_add_u32 v2, v1, 8, v2
	v_ashrrev_i32_e32 v3, 31, v2
	v_lshl_add_u64 v[2:3], s[44:45], 0, v[2:3]
	v_add_co_u32_e32 v132, vcc, 0x40000, v2
	s_nop 1
	v_addc_co_u32_e32 v133, vcc, 0, v3, vcc
	global_load_dwordx4 v[212:215], v[2:3], off nt
	global_load_dwordx4 v[180:183], v[2:3], off offset:1024 nt
	global_load_dwordx4 v[216:219], v[132:133], off
	global_load_dwordx4 v[184:187], v[132:133], off offset:1024
	global_load_dwordx4 v[172:175], v[2:3], off offset:2048 nt
	global_load_dwordx4 v[164:167], v[2:3], off offset:3072 nt
	global_load_dwordx4 v[176:179], v[132:133], off offset:2048
	global_load_dwordx4 v[168:171], v[132:133], off offset:3072
	v_add_co_u32_e32 v132, vcc, s76, v2
	s_nop 1
	v_addc_co_u32_e32 v133, vcc, 0, v3, vcc
	v_add_co_u32_e32 v2, vcc, s77, v2
	s_nop 1
	v_addc_co_u32_e32 v3, vcc, 0, v3, vcc
	global_load_dwordx4 v[156:159], v[132:133], off
	global_load_dwordx4 v[148:151], v[132:133], off offset:1024
	global_load_dwordx4 v[160:163], v[2:3], off nt
	global_load_dwordx4 v[152:155], v[2:3], off offset:1024 nt
	global_load_dwordx4 v[140:143], v[132:133], off offset:2048
	s_nop 0
	global_load_dwordx4 v[132:135], v[132:133], off offset:3072
	s_nop 0
	global_load_dwordx4 v[144:147], v[2:3], off offset:2048 nt
	global_load_dwordx4 v[136:139], v[2:3], off offset:3072 nt
	s_waitcnt vmcnt(0)
	v_cvt_f32_ubyte0_e32 v1, v216
	v_max_f32_e32 v1, 1.0, v1
	v_rcp_f32_e32 v2, v1
	v_cvt_f32_ubyte1_e32 v1, v216
	v_max_f32_e32 v1, 1.0, v1
	v_rcp_f32_e32 v3, v1
	v_cvt_f32_ubyte2_e32 v1, v216
	v_max_f32_e32 v1, 1.0, v1
	v_rcp_f32_e32 v220, v1
	v_cvt_f32_ubyte3_e32 v1, v216
	v_max_f32_e32 v1, 1.0, v1
	v_rcp_f32_e32 v221, v1
	v_cvt_f32_ubyte1_e32 v225, v212
	v_cvt_f32_ubyte0_e32 v224, v212
	v_cvt_f32_ubyte0_e32 v1, v217
	v_pk_mul_f32 v[2:3], v[2:3], v[224:225]
	v_max_f32_e32 v1, 1.0, v1
	v_pk_mul_f32 v[128:129], v[128:129], v[2:3]
	v_rcp_f32_e32 v2, v1
	v_cvt_f32_ubyte1_e32 v1, v217
	v_max_f32_e32 v1, 1.0, v1
	v_rcp_f32_e32 v3, v1
	v_cvt_f32_ubyte2_e32 v1, v217
	v_max_f32_e32 v1, 1.0, v1
	v_rcp_f32_e32 v216, v1
	v_cvt_f32_ubyte3_e32 v1, v217
	v_cvt_f32_ubyte3_e32 v223, v212
	v_cvt_f32_ubyte2_e32 v222, v212
	v_max_f32_e32 v1, 1.0, v1
	v_pk_mul_f32 v[220:221], v[220:221], v[222:223]
	v_rcp_f32_e32 v217, v1
	v_cvt_f32_ubyte1_e32 v223, v213
	v_cvt_f32_ubyte0_e32 v222, v213
	v_cvt_f32_ubyte0_e32 v1, v218
	v_pk_mul_f32 v[2:3], v[2:3], v[222:223]
	v_max_f32_e32 v1, 1.0, v1
	v_pk_mul_f32 v[124:125], v[124:125], v[2:3]
	v_rcp_f32_e32 v2, v1
	v_cvt_f32_ubyte1_e32 v1, v218
	v_max_f32_e32 v1, 1.0, v1
	v_pk_mul_f32 v[130:131], v[130:131], v[220:221]
	v_cvt_f32_ubyte3_e32 v221, v213
	v_cvt_f32_ubyte2_e32 v220, v213
	v_rcp_f32_e32 v3, v1
	v_cvt_f32_ubyte2_e32 v1, v218
	v_pk_mul_f32 v[212:213], v[216:217], v[220:221]
	v_max_f32_e32 v1, 1.0, v1
	v_pk_mul_f32 v[126:127], v[126:127], v[212:213]
	v_rcp_f32_e32 v212, v1
	v_cvt_f32_ubyte3_e32 v1, v218
	v_max_f32_e32 v1, 1.0, v1
	v_rcp_f32_e32 v213, v1
	v_cvt_f32_ubyte1_e32 v221, v214
	v_cvt_f32_ubyte0_e32 v220, v214
	v_cvt_f32_ubyte0_e32 v1, v219
	v_pk_mul_f32 v[2:3], v[2:3], v[220:221]
	v_max_f32_e32 v1, 1.0, v1
	v_pk_mul_f32 v[120:121], v[120:121], v[2:3]
	v_rcp_f32_e32 v2, v1
	v_cvt_f32_ubyte1_e32 v1, v219
	v_max_f32_e32 v1, 1.0, v1
	v_cvt_f32_ubyte3_e32 v217, v214
	v_cvt_f32_ubyte2_e32 v216, v214
	v_rcp_f32_e32 v3, v1
	v_cvt_f32_ubyte2_e32 v1, v219
	v_pk_mul_f32 v[212:213], v[212:213], v[216:217]
	v_max_f32_e32 v1, 1.0, v1
	v_pk_mul_f32 v[122:123], v[122:123], v[212:213]
	v_rcp_f32_e32 v212, v1
	v_cvt_f32_ubyte3_e32 v1, v219
	v_max_f32_e32 v1, 1.0, v1
	v_rcp_f32_e32 v213, v1
	v_cvt_f32_ubyte1_e32 v219, v215
	v_cvt_f32_ubyte0_e32 v218, v215
	v_cvt_f32_ubyte0_e32 v1, v184
	v_pk_mul_f32 v[2:3], v[2:3], v[218:219]
	v_max_f32_e32 v1, 1.0, v1
	v_pk_mul_f32 v[116:117], v[116:117], v[2:3]
	v_rcp_f32_e32 v2, v1
	v_cvt_f32_ubyte1_e32 v1, v184
	v_max_f32_e32 v1, 1.0, v1
	v_cvt_f32_ubyte3_e32 v217, v215
	v_cvt_f32_ubyte2_e32 v216, v215
	v_rcp_f32_e32 v3, v1
	v_cvt_f32_ubyte2_e32 v1, v184
	v_pk_mul_f32 v[212:213], v[212:213], v[216:217]
	v_max_f32_e32 v1, 1.0, v1
	v_pk_mul_f32 v[118:119], v[118:119], v[212:213]
	v_rcp_f32_e32 v212, v1
	v_cvt_f32_ubyte3_e32 v1, v184
	v_max_f32_e32 v1, 1.0, v1
	v_rcp_f32_e32 v213, v1
	v_cvt_f32_ubyte1_e32 v217, v180
	v_cvt_f32_ubyte0_e32 v216, v180
	v_cvt_f32_ubyte0_e32 v1, v185
	v_pk_mul_f32 v[2:3], v[2:3], v[216:217]
	v_max_f32_e32 v1, 1.0, v1
	v_pk_mul_f32 v[112:113], v[112:113], v[2:3]
	v_rcp_f32_e32 v2, v1
	v_cvt_f32_ubyte1_e32 v1, v185
	v_max_f32_e32 v1, 1.0, v1
	v_rcp_f32_e32 v3, v1
	v_cvt_f32_ubyte2_e32 v1, v185
	v_max_f32_e32 v1, 1.0, v1
	v_rcp_f32_e32 v184, v1
	v_cvt_f32_ubyte3_e32 v1, v185
	v_cvt_f32_ubyte3_e32 v215, v180
	v_cvt_f32_ubyte2_e32 v214, v180
	v_max_f32_e32 v1, 1.0, v1
	v_pk_mul_f32 v[212:213], v[212:213], v[214:215]
	v_rcp_f32_e32 v185, v1
	v_cvt_f32_ubyte1_e32 v215, v181
	v_cvt_f32_ubyte0_e32 v214, v181
	v_cvt_f32_ubyte0_e32 v1, v186
	v_pk_mul_f32 v[2:3], v[2:3], v[214:215]
	v_max_f32_e32 v1, 1.0, v1
	v_pk_mul_f32 v[108:109], v[108:109], v[2:3]
	v_rcp_f32_e32 v2, v1
	v_cvt_f32_ubyte1_e32 v1, v186
	v_max_f32_e32 v1, 1.0, v1
	v_pk_mul_f32 v[114:115], v[114:115], v[212:213]
	v_cvt_f32_ubyte3_e32 v213, v181
	v_cvt_f32_ubyte2_e32 v212, v181
	v_rcp_f32_e32 v3, v1
	v_cvt_f32_ubyte2_e32 v1, v186
	v_pk_mul_f32 v[180:181], v[184:185], v[212:213]
	v_max_f32_e32 v1, 1.0, v1
	v_pk_mul_f32 v[110:111], v[110:111], v[180:181]
	v_rcp_f32_e32 v180, v1
	v_cvt_f32_ubyte3_e32 v1, v186
	v_max_f32_e32 v1, 1.0, v1
	v_rcp_f32_e32 v181, v1
	v_cvt_f32_ubyte1_e32 v213, v182
	v_cvt_f32_ubyte0_e32 v212, v182
	v_cvt_f32_ubyte0_e32 v1, v187
	v_pk_mul_f32 v[2:3], v[2:3], v[212:213]
	v_max_f32_e32 v1, 1.0, v1
	v_pk_mul_f32 v[104:105], v[104:105], v[2:3]
	v_rcp_f32_e32 v2, v1
	v_cvt_f32_ubyte1_e32 v1, v187
	v_max_f32_e32 v1, 1.0, v1
	v_cvt_f32_ubyte3_e32 v185, v182
	v_cvt_f32_ubyte2_e32 v184, v182
	v_rcp_f32_e32 v3, v1
	v_cvt_f32_ubyte2_e32 v1, v187
	v_pk_mul_f32 v[180:181], v[180:181], v[184:185]
	v_max_f32_e32 v1, 1.0, v1
	v_pk_mul_f32 v[106:107], v[106:107], v[180:181]
	v_rcp_f32_e32 v180, v1
	v_cvt_f32_ubyte3_e32 v1, v187
	v_max_f32_e32 v1, 1.0, v1
	v_rcp_f32_e32 v181, v1
	v_cvt_f32_ubyte3_e32 v185, v183
	v_cvt_f32_ubyte2_e32 v184, v183
	v_cvt_f32_ubyte1_e32 v187, v183
	v_cvt_f32_ubyte0_e32 v186, v183
	v_pk_mul_f32 v[2:3], v[2:3], v[186:187]
	v_pk_mul_f32 v[180:181], v[180:181], v[184:185]
	v_pk_mul_f32 v[100:101], v[100:101], v[2:3]
	v_pk_mul_f32 v[102:103], v[102:103], v[180:181]
	v_cvt_f32_ubyte0_e32 v1, v176
	v_max_f32_e32 v1, 1.0, v1
	v_rcp_f32_e32 v2, v1
	v_cvt_f32_ubyte1_e32 v1, v176
	v_max_f32_e32 v1, 1.0, v1
	v_rcp_f32_e32 v3, v1
	v_cvt_f32_ubyte2_e32 v1, v176
	v_max_f32_e32 v1, 1.0, v1
	v_rcp_f32_e32 v180, v1
	v_cvt_f32_ubyte3_e32 v1, v176
	v_max_f32_e32 v1, 1.0, v1
	v_rcp_f32_e32 v181, v1
	v_cvt_f32_ubyte1_e32 v185, v172
	v_cvt_f32_ubyte0_e32 v184, v172
	v_cvt_f32_ubyte0_e32 v1, v177
	v_pk_mul_f32 v[2:3], v[2:3], v[184:185]
	v_max_f32_e32 v1, 1.0, v1
	v_pk_mul_f32 v[96:97], v[96:97], v[2:3]
	v_rcp_f32_e32 v2, v1
	v_cvt_f32_ubyte1_e32 v1, v177
	v_max_f32_e32 v1, 1.0, v1
	v_rcp_f32_e32 v3, v1
	v_cvt_f32_ubyte2_e32 v1, v177
	v_max_f32_e32 v1, 1.0, v1
	v_rcp_f32_e32 v176, v1
	v_cvt_f32_ubyte3_e32 v1, v177
	v_cvt_f32_ubyte3_e32 v183, v172
	v_cvt_f32_ubyte2_e32 v182, v172
	v_max_f32_e32 v1, 1.0, v1
	v_pk_mul_f32 v[180:181], v[180:181], v[182:183]
	v_rcp_f32_e32 v177, v1
	v_cvt_f32_ubyte1_e32 v183, v173
	v_cvt_f32_ubyte0_e32 v182, v173
	v_cvt_f32_ubyte0_e32 v1, v178
	v_pk_mul_f32 v[2:3], v[2:3], v[182:183]
	v_max_f32_e32 v1, 1.0, v1
	v_pk_mul_f32 v[92:93], v[92:93], v[2:3]
	v_rcp_f32_e32 v2, v1
	v_cvt_f32_ubyte1_e32 v1, v178
	v_max_f32_e32 v1, 1.0, v1
	v_pk_mul_f32 v[98:99], v[98:99], v[180:181]
	v_cvt_f32_ubyte3_e32 v181, v173
	v_cvt_f32_ubyte2_e32 v180, v173
	v_rcp_f32_e32 v3, v1
	v_cvt_f32_ubyte2_e32 v1, v178
	v_pk_mul_f32 v[172:173], v[176:177], v[180:181]
	v_max_f32_e32 v1, 1.0, v1
	v_pk_mul_f32 v[94:95], v[94:95], v[172:173]
	v_rcp_f32_e32 v172, v1
	v_cvt_f32_ubyte3_e32 v1, v178
	v_max_f32_e32 v1, 1.0, v1
	v_rcp_f32_e32 v173, v1
	v_cvt_f32_ubyte1_e32 v181, v174
	v_cvt_f32_ubyte0_e32 v180, v174
	v_cvt_f32_ubyte0_e32 v1, v179
	v_pk_mul_f32 v[2:3], v[2:3], v[180:181]
	v_max_f32_e32 v1, 1.0, v1
	v_pk_mul_f32 v[88:89], v[88:89], v[2:3]
	v_rcp_f32_e32 v2, v1
	v_cvt_f32_ubyte1_e32 v1, v179
	v_max_f32_e32 v1, 1.0, v1
	v_cvt_f32_ubyte3_e32 v177, v174
	v_cvt_f32_ubyte2_e32 v176, v174
	v_rcp_f32_e32 v3, v1
	v_cvt_f32_ubyte2_e32 v1, v179
	v_pk_mul_f32 v[172:173], v[172:173], v[176:177]
	v_max_f32_e32 v1, 1.0, v1
	v_pk_mul_f32 v[90:91], v[90:91], v[172:173]
	v_rcp_f32_e32 v172, v1
	v_cvt_f32_ubyte3_e32 v1, v179
	v_max_f32_e32 v1, 1.0, v1
	v_rcp_f32_e32 v173, v1
	v_cvt_f32_ubyte1_e32 v179, v175
	v_cvt_f32_ubyte0_e32 v178, v175
	v_cvt_f32_ubyte0_e32 v1, v168
	v_pk_mul_f32 v[2:3], v[2:3], v[178:179]
	v_max_f32_e32 v1, 1.0, v1
	v_pk_mul_f32 v[84:85], v[84:85], v[2:3]
	v_rcp_f32_e32 v2, v1
	v_cvt_f32_ubyte1_e32 v1, v168
	v_max_f32_e32 v1, 1.0, v1
	v_cvt_f32_ubyte3_e32 v177, v175
	v_cvt_f32_ubyte2_e32 v176, v175
	v_rcp_f32_e32 v3, v1
	v_cvt_f32_ubyte2_e32 v1, v168
	v_pk_mul_f32 v[172:173], v[172:173], v[176:177]
	v_max_f32_e32 v1, 1.0, v1
	v_pk_mul_f32 v[86:87], v[86:87], v[172:173]
	v_rcp_f32_e32 v172, v1
	v_cvt_f32_ubyte3_e32 v1, v168
	v_max_f32_e32 v1, 1.0, v1
	v_rcp_f32_e32 v173, v1
	v_cvt_f32_ubyte1_e32 v177, v164
	v_cvt_f32_ubyte0_e32 v176, v164
	v_cvt_f32_ubyte0_e32 v1, v169
	v_pk_mul_f32 v[2:3], v[2:3], v[176:177]
	v_max_f32_e32 v1, 1.0, v1
	v_pk_mul_f32 v[80:81], v[80:81], v[2:3]
	v_rcp_f32_e32 v2, v1
	v_cvt_f32_ubyte1_e32 v1, v169
	v_max_f32_e32 v1, 1.0, v1
	v_rcp_f32_e32 v3, v1
	v_cvt_f32_ubyte2_e32 v1, v169
	v_max_f32_e32 v1, 1.0, v1
	v_rcp_f32_e32 v168, v1
	v_cvt_f32_ubyte3_e32 v1, v169
	v_cvt_f32_ubyte3_e32 v175, v164
	v_cvt_f32_ubyte2_e32 v174, v164
	v_max_f32_e32 v1, 1.0, v1
	v_pk_mul_f32 v[172:173], v[172:173], v[174:175]
	v_rcp_f32_e32 v169, v1
	v_cvt_f32_ubyte1_e32 v175, v165
	v_cvt_f32_ubyte0_e32 v174, v165
	v_cvt_f32_ubyte0_e32 v1, v170
	v_pk_mul_f32 v[2:3], v[2:3], v[174:175]
	v_max_f32_e32 v1, 1.0, v1
	v_pk_mul_f32 v[76:77], v[76:77], v[2:3]
	v_rcp_f32_e32 v2, v1
	v_cvt_f32_ubyte1_e32 v1, v170
	v_max_f32_e32 v1, 1.0, v1
	v_pk_mul_f32 v[82:83], v[82:83], v[172:173]
	v_cvt_f32_ubyte3_e32 v173, v165
	v_cvt_f32_ubyte2_e32 v172, v165
	v_rcp_f32_e32 v3, v1
	v_cvt_f32_ubyte2_e32 v1, v170
	v_pk_mul_f32 v[164:165], v[168:169], v[172:173]
	v_max_f32_e32 v1, 1.0, v1
	v_pk_mul_f32 v[78:79], v[78:79], v[164:165]
	v_rcp_f32_e32 v164, v1
	v_cvt_f32_ubyte3_e32 v1, v170
	v_max_f32_e32 v1, 1.0, v1
	v_rcp_f32_e32 v165, v1
	v_cvt_f32_ubyte1_e32 v173, v166
	v_cvt_f32_ubyte0_e32 v172, v166
	v_cvt_f32_ubyte0_e32 v1, v171
	v_pk_mul_f32 v[2:3], v[2:3], v[172:173]
	v_max_f32_e32 v1, 1.0, v1
	v_pk_mul_f32 v[72:73], v[72:73], v[2:3]
	v_rcp_f32_e32 v2, v1
	v_cvt_f32_ubyte1_e32 v1, v171
	v_max_f32_e32 v1, 1.0, v1
	v_cvt_f32_ubyte3_e32 v169, v166
	v_cvt_f32_ubyte2_e32 v168, v166
	v_rcp_f32_e32 v3, v1
	v_cvt_f32_ubyte2_e32 v1, v171
	v_pk_mul_f32 v[164:165], v[164:165], v[168:169]
	v_max_f32_e32 v1, 1.0, v1
	v_pk_mul_f32 v[74:75], v[74:75], v[164:165]
	v_rcp_f32_e32 v164, v1
	v_cvt_f32_ubyte3_e32 v1, v171
	v_max_f32_e32 v1, 1.0, v1
	v_rcp_f32_e32 v165, v1
	v_cvt_f32_ubyte3_e32 v169, v167
	v_cvt_f32_ubyte2_e32 v168, v167
	v_cvt_f32_ubyte1_e32 v171, v167
	v_cvt_f32_ubyte0_e32 v170, v167
	v_pk_mul_f32 v[2:3], v[2:3], v[170:171]
	v_pk_mul_f32 v[164:165], v[164:165], v[168:169]
	v_pk_mul_f32 v[68:69], v[68:69], v[2:3]
	v_pk_mul_f32 v[70:71], v[70:71], v[164:165]
	v_cvt_f32_ubyte0_e32 v1, v160
	v_max_f32_e32 v1, 1.0, v1
	v_rcp_f32_e32 v2, v1
	v_cvt_f32_ubyte1_e32 v1, v160
	v_max_f32_e32 v1, 1.0, v1
	v_rcp_f32_e32 v3, v1
	v_cvt_f32_ubyte2_e32 v1, v160
	v_max_f32_e32 v1, 1.0, v1
	v_rcp_f32_e32 v164, v1
	v_cvt_f32_ubyte3_e32 v1, v160
	v_max_f32_e32 v1, 1.0, v1
	v_rcp_f32_e32 v165, v1
	v_cvt_f32_ubyte1_e32 v169, v156
	v_cvt_f32_ubyte0_e32 v168, v156
	v_cvt_f32_ubyte0_e32 v1, v161
	v_pk_mul_f32 v[2:3], v[2:3], v[168:169]
	v_max_f32_e32 v1, 1.0, v1
	v_pk_mul_f32 v[64:65], v[64:65], v[2:3]
	v_rcp_f32_e32 v2, v1
	v_cvt_f32_ubyte1_e32 v1, v161
	v_max_f32_e32 v1, 1.0, v1
	v_rcp_f32_e32 v3, v1
	v_cvt_f32_ubyte2_e32 v1, v161
	v_max_f32_e32 v1, 1.0, v1
	v_rcp_f32_e32 v160, v1
	v_cvt_f32_ubyte3_e32 v1, v161
	v_cvt_f32_ubyte3_e32 v167, v156
	v_cvt_f32_ubyte2_e32 v166, v156
	v_max_f32_e32 v1, 1.0, v1
	v_pk_mul_f32 v[164:165], v[164:165], v[166:167]
	v_rcp_f32_e32 v161, v1
	v_cvt_f32_ubyte1_e32 v167, v157
	v_cvt_f32_ubyte0_e32 v166, v157
	v_cvt_f32_ubyte0_e32 v1, v162
	v_pk_mul_f32 v[2:3], v[2:3], v[166:167]
	v_max_f32_e32 v1, 1.0, v1
	v_pk_mul_f32 v[60:61], v[60:61], v[2:3]
	v_rcp_f32_e32 v2, v1
	v_cvt_f32_ubyte1_e32 v1, v162
	v_max_f32_e32 v1, 1.0, v1
	v_pk_mul_f32 v[66:67], v[66:67], v[164:165]
	v_cvt_f32_ubyte3_e32 v165, v157
	v_cvt_f32_ubyte2_e32 v164, v157
	v_rcp_f32_e32 v3, v1
	v_cvt_f32_ubyte2_e32 v1, v162
	v_pk_mul_f32 v[156:157], v[160:161], v[164:165]
	v_max_f32_e32 v1, 1.0, v1
	v_pk_mul_f32 v[62:63], v[62:63], v[156:157]
	v_rcp_f32_e32 v156, v1
	v_cvt_f32_ubyte3_e32 v1, v162
	v_max_f32_e32 v1, 1.0, v1
	v_rcp_f32_e32 v157, v1
	v_cvt_f32_ubyte1_e32 v165, v158
	v_cvt_f32_ubyte0_e32 v164, v158
	v_cvt_f32_ubyte0_e32 v1, v163
	v_pk_mul_f32 v[2:3], v[2:3], v[164:165]
	v_max_f32_e32 v1, 1.0, v1
	v_pk_mul_f32 v[56:57], v[56:57], v[2:3]
	v_rcp_f32_e32 v2, v1
	v_cvt_f32_ubyte1_e32 v1, v163
	v_max_f32_e32 v1, 1.0, v1
	v_cvt_f32_ubyte3_e32 v161, v158
	v_cvt_f32_ubyte2_e32 v160, v158
	v_rcp_f32_e32 v3, v1
	v_cvt_f32_ubyte2_e32 v1, v163
	v_pk_mul_f32 v[156:157], v[156:157], v[160:161]
	v_max_f32_e32 v1, 1.0, v1
	v_pk_mul_f32 v[58:59], v[58:59], v[156:157]
	v_rcp_f32_e32 v156, v1
	v_cvt_f32_ubyte3_e32 v1, v163
	v_max_f32_e32 v1, 1.0, v1
	v_rcp_f32_e32 v157, v1
	v_cvt_f32_ubyte1_e32 v163, v159
	v_cvt_f32_ubyte0_e32 v162, v159
	v_cvt_f32_ubyte0_e32 v1, v152
	v_pk_mul_f32 v[2:3], v[2:3], v[162:163]
	v_max_f32_e32 v1, 1.0, v1
	v_pk_mul_f32 v[52:53], v[52:53], v[2:3]
	v_rcp_f32_e32 v2, v1
	v_cvt_f32_ubyte1_e32 v1, v152
	v_max_f32_e32 v1, 1.0, v1
	v_cvt_f32_ubyte3_e32 v161, v159
	v_cvt_f32_ubyte2_e32 v160, v159
	v_rcp_f32_e32 v3, v1
	v_cvt_f32_ubyte2_e32 v1, v152
	v_pk_mul_f32 v[156:157], v[156:157], v[160:161]
	v_max_f32_e32 v1, 1.0, v1
	v_pk_mul_f32 v[54:55], v[54:55], v[156:157]
	v_rcp_f32_e32 v156, v1
	v_cvt_f32_ubyte3_e32 v1, v152
	v_max_f32_e32 v1, 1.0, v1
	v_rcp_f32_e32 v157, v1
	v_cvt_f32_ubyte1_e32 v161, v148
	v_cvt_f32_ubyte0_e32 v160, v148
	v_cvt_f32_ubyte0_e32 v1, v153
	v_pk_mul_f32 v[2:3], v[2:3], v[160:161]
	v_max_f32_e32 v1, 1.0, v1
	v_pk_mul_f32 v[48:49], v[48:49], v[2:3]
	v_rcp_f32_e32 v2, v1
	v_cvt_f32_ubyte1_e32 v1, v153
	v_max_f32_e32 v1, 1.0, v1
	v_rcp_f32_e32 v3, v1
	v_cvt_f32_ubyte2_e32 v1, v153
	v_max_f32_e32 v1, 1.0, v1
	v_rcp_f32_e32 v152, v1
	v_cvt_f32_ubyte3_e32 v1, v153
	v_cvt_f32_ubyte3_e32 v159, v148
	v_cvt_f32_ubyte2_e32 v158, v148
	v_max_f32_e32 v1, 1.0, v1
	v_pk_mul_f32 v[156:157], v[156:157], v[158:159]
	v_rcp_f32_e32 v153, v1
	v_cvt_f32_ubyte1_e32 v159, v149
	v_cvt_f32_ubyte0_e32 v158, v149
	v_cvt_f32_ubyte0_e32 v1, v154
	v_pk_mul_f32 v[2:3], v[2:3], v[158:159]
	v_max_f32_e32 v1, 1.0, v1
	v_pk_mul_f32 v[44:45], v[44:45], v[2:3]
	v_rcp_f32_e32 v2, v1
	v_cvt_f32_ubyte1_e32 v1, v154
	v_max_f32_e32 v1, 1.0, v1
	v_pk_mul_f32 v[50:51], v[50:51], v[156:157]
	v_cvt_f32_ubyte3_e32 v157, v149
	v_cvt_f32_ubyte2_e32 v156, v149
	v_rcp_f32_e32 v3, v1
	v_cvt_f32_ubyte2_e32 v1, v154
	v_pk_mul_f32 v[148:149], v[152:153], v[156:157]
	v_max_f32_e32 v1, 1.0, v1
	v_pk_mul_f32 v[46:47], v[46:47], v[148:149]
	v_rcp_f32_e32 v148, v1
	v_cvt_f32_ubyte3_e32 v1, v154
	v_max_f32_e32 v1, 1.0, v1
	v_rcp_f32_e32 v149, v1
	v_cvt_f32_ubyte1_e32 v157, v150
	v_cvt_f32_ubyte0_e32 v156, v150
	v_cvt_f32_ubyte0_e32 v1, v155
	v_pk_mul_f32 v[2:3], v[2:3], v[156:157]
	v_max_f32_e32 v1, 1.0, v1
	v_pk_mul_f32 v[40:41], v[40:41], v[2:3]
	v_rcp_f32_e32 v2, v1
	v_cvt_f32_ubyte1_e32 v1, v155
	v_max_f32_e32 v1, 1.0, v1
	v_cvt_f32_ubyte3_e32 v153, v150
	v_cvt_f32_ubyte2_e32 v152, v150
	v_rcp_f32_e32 v3, v1
	v_cvt_f32_ubyte2_e32 v1, v155
	v_pk_mul_f32 v[148:149], v[148:149], v[152:153]
	v_max_f32_e32 v1, 1.0, v1
	v_pk_mul_f32 v[42:43], v[42:43], v[148:149]
	v_rcp_f32_e32 v148, v1
	v_cvt_f32_ubyte3_e32 v1, v155
	v_max_f32_e32 v1, 1.0, v1
	v_rcp_f32_e32 v149, v1
	v_cvt_f32_ubyte3_e32 v153, v151
	v_cvt_f32_ubyte2_e32 v152, v151
	v_cvt_f32_ubyte1_e32 v155, v151
	v_cvt_f32_ubyte0_e32 v154, v151
	v_pk_mul_f32 v[2:3], v[2:3], v[154:155]
	v_pk_mul_f32 v[148:149], v[148:149], v[152:153]
	v_pk_mul_f32 v[36:37], v[36:37], v[2:3]
	v_pk_mul_f32 v[38:39], v[38:39], v[148:149]
	v_cvt_f32_ubyte0_e32 v1, v144
	v_max_f32_e32 v1, 1.0, v1
	v_rcp_f32_e32 v2, v1
	v_cvt_f32_ubyte1_e32 v1, v144
	v_max_f32_e32 v1, 1.0, v1
	v_rcp_f32_e32 v3, v1
	v_cvt_f32_ubyte2_e32 v1, v144
	v_max_f32_e32 v1, 1.0, v1
	v_rcp_f32_e32 v148, v1
	v_cvt_f32_ubyte3_e32 v1, v144
	v_max_f32_e32 v1, 1.0, v1
	v_rcp_f32_e32 v149, v1
	v_cvt_f32_ubyte1_e32 v153, v140
	v_cvt_f32_ubyte0_e32 v152, v140
	v_cvt_f32_ubyte0_e32 v1, v145
	v_pk_mul_f32 v[2:3], v[2:3], v[152:153]
	v_max_f32_e32 v1, 1.0, v1
	v_pk_mul_f32 v[32:33], v[32:33], v[2:3]
	v_rcp_f32_e32 v2, v1
	v_cvt_f32_ubyte1_e32 v1, v145
	v_max_f32_e32 v1, 1.0, v1
	v_rcp_f32_e32 v3, v1
	v_cvt_f32_ubyte2_e32 v1, v145
	v_max_f32_e32 v1, 1.0, v1
	v_rcp_f32_e32 v144, v1
	v_cvt_f32_ubyte3_e32 v1, v145
	v_cvt_f32_ubyte3_e32 v151, v140
	v_cvt_f32_ubyte2_e32 v150, v140
	v_max_f32_e32 v1, 1.0, v1
	v_pk_mul_f32 v[148:149], v[148:149], v[150:151]
	v_rcp_f32_e32 v145, v1
	v_cvt_f32_ubyte1_e32 v151, v141
	v_cvt_f32_ubyte0_e32 v150, v141
	v_cvt_f32_ubyte0_e32 v1, v146
	v_pk_mul_f32 v[2:3], v[2:3], v[150:151]
	v_max_f32_e32 v1, 1.0, v1
	v_pk_mul_f32 v[28:29], v[28:29], v[2:3]
	v_rcp_f32_e32 v2, v1
	v_cvt_f32_ubyte1_e32 v1, v146
	v_max_f32_e32 v1, 1.0, v1
	v_pk_mul_f32 v[34:35], v[34:35], v[148:149]
	v_cvt_f32_ubyte3_e32 v149, v141
	v_cvt_f32_ubyte2_e32 v148, v141
	v_rcp_f32_e32 v3, v1
	v_cvt_f32_ubyte2_e32 v1, v146
	v_pk_mul_f32 v[140:141], v[144:145], v[148:149]
	v_max_f32_e32 v1, 1.0, v1
	v_pk_mul_f32 v[30:31], v[30:31], v[140:141]
	v_rcp_f32_e32 v140, v1
	v_cvt_f32_ubyte3_e32 v1, v146
	v_max_f32_e32 v1, 1.0, v1
	v_rcp_f32_e32 v141, v1
	v_cvt_f32_ubyte1_e32 v149, v142
	v_cvt_f32_ubyte0_e32 v148, v142
	v_cvt_f32_ubyte0_e32 v1, v147
	v_pk_mul_f32 v[2:3], v[2:3], v[148:149]
	v_max_f32_e32 v1, 1.0, v1
	v_pk_mul_f32 v[24:25], v[24:25], v[2:3]
	v_rcp_f32_e32 v2, v1
	v_cvt_f32_ubyte1_e32 v1, v147
	v_max_f32_e32 v1, 1.0, v1
	v_cvt_f32_ubyte3_e32 v145, v142
	v_cvt_f32_ubyte2_e32 v144, v142
	v_rcp_f32_e32 v3, v1
	v_cvt_f32_ubyte2_e32 v1, v147
	v_pk_mul_f32 v[140:141], v[140:141], v[144:145]
	v_max_f32_e32 v1, 1.0, v1
	v_pk_mul_f32 v[26:27], v[26:27], v[140:141]
	v_rcp_f32_e32 v140, v1
	v_cvt_f32_ubyte3_e32 v1, v147
	v_max_f32_e32 v1, 1.0, v1
	v_rcp_f32_e32 v141, v1
	v_cvt_f32_ubyte1_e32 v147, v143
	v_cvt_f32_ubyte0_e32 v146, v143
	v_cvt_f32_ubyte0_e32 v1, v136
	v_pk_mul_f32 v[2:3], v[2:3], v[146:147]
	v_max_f32_e32 v1, 1.0, v1
	v_pk_mul_f32 v[20:21], v[20:21], v[2:3]
	v_rcp_f32_e32 v2, v1
	v_cvt_f32_ubyte1_e32 v1, v136
	v_max_f32_e32 v1, 1.0, v1
	v_cvt_f32_ubyte3_e32 v145, v143
	v_cvt_f32_ubyte2_e32 v144, v143
	v_rcp_f32_e32 v3, v1
	v_cvt_f32_ubyte2_e32 v1, v136
	v_pk_mul_f32 v[140:141], v[140:141], v[144:145]
	v_max_f32_e32 v1, 1.0, v1
	v_pk_mul_f32 v[22:23], v[22:23], v[140:141]
	v_rcp_f32_e32 v140, v1
	v_cvt_f32_ubyte3_e32 v1, v136
	v_max_f32_e32 v1, 1.0, v1
	v_rcp_f32_e32 v141, v1
	v_cvt_f32_ubyte1_e32 v145, v132
	v_cvt_f32_ubyte0_e32 v144, v132
	v_cvt_f32_ubyte0_e32 v1, v137
	v_pk_mul_f32 v[2:3], v[2:3], v[144:145]
	v_max_f32_e32 v1, 1.0, v1
	v_pk_mul_f32 v[16:17], v[16:17], v[2:3]
	v_rcp_f32_e32 v2, v1
	v_cvt_f32_ubyte1_e32 v1, v137
	v_max_f32_e32 v1, 1.0, v1
	v_rcp_f32_e32 v3, v1
	v_cvt_f32_ubyte2_e32 v1, v137
	v_max_f32_e32 v1, 1.0, v1
	v_rcp_f32_e32 v136, v1
	v_cvt_f32_ubyte3_e32 v1, v137
	v_cvt_f32_ubyte3_e32 v143, v132
	v_cvt_f32_ubyte2_e32 v142, v132
	v_max_f32_e32 v1, 1.0, v1
	v_pk_mul_f32 v[140:141], v[140:141], v[142:143]
	v_rcp_f32_e32 v137, v1
	v_cvt_f32_ubyte1_e32 v143, v133
	v_cvt_f32_ubyte0_e32 v142, v133
	v_cvt_f32_ubyte0_e32 v1, v138
	v_pk_mul_f32 v[2:3], v[2:3], v[142:143]
	v_max_f32_e32 v1, 1.0, v1
	v_pk_mul_f32 v[12:13], v[12:13], v[2:3]
	v_rcp_f32_e32 v2, v1
	v_cvt_f32_ubyte1_e32 v1, v138
	v_max_f32_e32 v1, 1.0, v1
	v_pk_mul_f32 v[18:19], v[18:19], v[140:141]
	v_cvt_f32_ubyte3_e32 v141, v133
	v_cvt_f32_ubyte2_e32 v140, v133
	v_rcp_f32_e32 v3, v1
	v_cvt_f32_ubyte2_e32 v1, v138
	v_pk_mul_f32 v[132:133], v[136:137], v[140:141]
	v_max_f32_e32 v1, 1.0, v1
	v_pk_mul_f32 v[14:15], v[14:15], v[132:133]
	v_rcp_f32_e32 v132, v1
	v_cvt_f32_ubyte3_e32 v1, v138
	v_max_f32_e32 v1, 1.0, v1
	v_rcp_f32_e32 v133, v1
	v_cvt_f32_ubyte1_e32 v141, v134
	v_cvt_f32_ubyte0_e32 v140, v134
	v_cvt_f32_ubyte0_e32 v1, v139
	v_pk_mul_f32 v[2:3], v[2:3], v[140:141]
	v_max_f32_e32 v1, 1.0, v1
	v_pk_mul_f32 v[8:9], v[8:9], v[2:3]
	v_rcp_f32_e32 v2, v1
	v_cvt_f32_ubyte1_e32 v1, v139
	v_max_f32_e32 v1, 1.0, v1
	v_cvt_f32_ubyte3_e32 v137, v134
	v_cvt_f32_ubyte2_e32 v136, v134
	v_rcp_f32_e32 v3, v1
	v_cvt_f32_ubyte2_e32 v1, v139
	v_pk_mul_f32 v[132:133], v[132:133], v[136:137]
	v_max_f32_e32 v1, 1.0, v1
	v_pk_mul_f32 v[10:11], v[10:11], v[132:133]
	v_rcp_f32_e32 v132, v1
	v_cvt_f32_ubyte3_e32 v1, v139
	v_max_f32_e32 v1, 1.0, v1
	v_rcp_f32_e32 v133, v1
	v_cvt_f32_ubyte3_e32 v137, v135
	v_cvt_f32_ubyte2_e32 v136, v135
	v_cvt_f32_ubyte1_e32 v139, v135
	v_cvt_f32_ubyte0_e32 v138, v135
	v_pk_mul_f32 v[2:3], v[2:3], v[138:139]
	v_pk_mul_f32 v[132:133], v[132:133], v[136:137]
	v_pk_mul_f32 v[4:5], v[4:5], v[2:3]
	v_pk_mul_f32 v[6:7], v[6:7], v[132:133]
	s_branch .LBB0_448

.LBB0_620:
	v_ashrrev_i32_e32 v229, 4, v228
	s_lshl_b32 s0, s9, 5
	s_lshl_b32 s1, s8, 8
	s_barrier
	s_or_b32 s0, s1, s0
	v_lshlrev_b32_e32 v144, 3, v229
	v_add_u32_e32 v128, s0, v144
	s_lshr_b32 s0, s6, 4
	s_mulk_i32 s0, 0x1800
	s_ashr_i32 s1, s0, 31
	s_lshl_b64 s[0:1], s[0:1], 2
	s_add_u32 s0, s54, s0
	v_ashrrev_i32_e32 v129, 31, v128
	s_addc_u32 s1, s55, s1
	v_lshlrev_b64 v[212:213], 2, v[128:129]
	v_lshl_add_u64 v[146:147], s[0:1], 0, v[212:213]
	s_mov_b64 s[0:1], 0x285000
	v_lshl_add_u64 v[132:133], v[146:147], 0, s[0:1]
	s_mov_b32 s0, 0x285000
	v_add_co_u32_e32 v128, vcc, s0, v146
	s_mov_b32 s0, 0x284000
	s_nop 0
	v_addc_co_u32_e32 v129, vcc, 0, v147, vcc
	v_add_co_u32_e32 v150, vcc, s0, v146
	v_readlane_b32 s12, v251, 2
	s_nop 0
	v_addc_co_u32_e32 v151, vcc, 0, v147, vcc
	v_readlane_b32 s20, v251, 10
	v_readlane_b32 s21, v251, 11
	global_load_dwordx4 v[136:139], v[128:129], off
	s_nop 0
	global_load_dwordx4 v[128:131], v[132:133], off offset:528
	global_load_dwordx4 v[140:143], v[132:133], off offset:16
	s_nop 0
	global_load_dwordx4 v[132:135], v[132:133], off offset:512
	v_lshl_add_u64 v[216:217], s[20:21], 0, v[212:213]
	global_load_dwordx4 v[218:221], v[150:151], off
	global_load_dwordx4 v[208:211], v[216:217], off offset:16
	global_load_dwordx4 v[222:225], v[216:217], off
	v_add_u32_e32 v214, s7, v148
	s_ashr_i32 s7, s6, 31
	s_lshl_b64 s[0:1], s[6:7], 19
	s_add_u32 s0, s54, s0
	s_addc_u32 s1, s55, s1
	s_lshl_b32 s2, s8, 3
	s_or_b32 s2, s2, s9
	v_ashrrev_i32_e32 v145, 31, v144
	s_ashr_i32 s3, s2, 31
	v_ashrrev_i32_e32 v215, 31, v214
	v_lshl_add_u64 v[144:145], v[144:145], 1, s[0:1]
	s_lshl_b64 s[0:1], s[2:3], 14
	v_lshlrev_b64 v[148:149], 6, v[214:215]
	s_or_b32 s2, s2, 4
	v_lshl_add_u64 v[144:145], v[144:145], 0, v[148:149]
	s_mov_b64 s[4:5], 0x4c00000
	s_ashr_i32 s3, s2, 31
	v_lshl_add_u64 v[148:149], v[144:145], 0, s[4:5]
	s_lshl_b64 s[2:3], s[2:3], 14
	v_lshl_add_u64 v[150:151], v[148:149], 0, s[0:1]
	v_lshl_add_u64 v[148:149], v[148:149], 0, s[2:3]
	s_mov_b64 s[4:5], 0x4c00400
	global_load_dwordx4 v[204:207], v[150:151], off nt
	global_load_dwordx4 v[200:203], v[148:149], off nt
	v_lshl_add_u64 v[148:149], v[144:145], 0, s[4:5]
	v_lshl_add_u64 v[150:151], v[148:149], 0, s[0:1]
	v_lshl_add_u64 v[148:149], v[148:149], 0, s[2:3]
	s_mov_b64 s[4:5], 0x4c00800
	global_load_dwordx4 v[196:199], v[150:151], off nt
	global_load_dwordx4 v[192:195], v[148:149], off nt
	v_lshl_add_u64 v[148:149], v[144:145], 0, s[4:5]
	v_lshl_add_u64 v[150:151], v[148:149], 0, s[0:1]
	v_lshl_add_u64 v[148:149], v[148:149], 0, s[2:3]
	s_mov_b64 s[4:5], 0x4c00c00
	global_load_dwordx4 v[188:191], v[150:151], off nt
	global_load_dwordx4 v[184:187], v[148:149], off nt
	v_lshl_add_u64 v[148:149], v[144:145], 0, s[4:5]
	v_lshl_add_u64 v[150:151], v[148:149], 0, s[0:1]
	v_lshl_add_u64 v[148:149], v[148:149], 0, s[2:3]
	s_mov_b64 s[4:5], 0x4c02000
	global_load_dwordx4 v[180:183], v[150:151], off nt
	global_load_dwordx4 v[176:179], v[148:149], off nt
	v_lshl_add_u64 v[148:149], v[144:145], 0, s[4:5]
	v_lshl_add_u64 v[150:151], v[148:149], 0, s[0:1]
	v_lshl_add_u64 v[148:149], v[148:149], 0, s[2:3]
	s_mov_b64 s[4:5], 0x4c02400
	global_load_dwordx4 v[172:175], v[150:151], off nt
	global_load_dwordx4 v[168:171], v[148:149], off nt
	v_lshl_add_u64 v[148:149], v[144:145], 0, s[4:5]
	v_lshl_add_u64 v[150:151], v[148:149], 0, s[0:1]
	v_lshl_add_u64 v[148:149], v[148:149], 0, s[2:3]
	s_mov_b64 s[4:5], 0x4c02800
	global_load_dwordx4 v[164:167], v[150:151], off nt
	global_load_dwordx4 v[160:163], v[148:149], off nt
	v_lshl_add_u64 v[148:149], v[144:145], 0, s[4:5]
	s_mov_b64 s[4:5], 0x284000
	v_lshl_add_u64 v[226:227], v[146:147], 0, s[4:5]
	v_lshl_add_u64 v[150:151], v[148:149], 0, s[0:1]
	v_lshl_add_u64 v[148:149], v[148:149], 0, s[2:3]
	global_load_dwordx4 v[230:233], v[226:227], off offset:16
	global_load_dwordx4 v[156:159], v[150:151], off nt
	global_load_dwordx4 v[152:155], v[148:149], off nt
	s_mov_b64 s[4:5], 0x4c02c00
	v_lshl_add_u64 v[144:145], v[144:145], 0, s[4:5]
	v_lshl_add_u64 v[146:147], v[144:145], 0, s[0:1]
	v_lshl_add_u64 v[144:145], v[144:145], 0, s[2:3]
	global_load_dwordx4 v[148:151], v[146:147], off nt
	s_nop 0
	global_load_dwordx4 v[144:147], v[144:145], off nt
	s_nop 0
	global_load_dwordx4 v[234:237], v[226:227], off offset:528
	v_readlane_b32 s13, v251, 3
	v_readlane_b32 s14, v251, 4
	v_readlane_b32 s15, v251, 5
	v_readlane_b32 s16, v251, 6
	v_readlane_b32 s17, v251, 7
	v_readlane_b32 s18, v251, 8
	v_readlane_b32 s19, v251, 9
	v_readlane_b32 s22, v251, 12
	v_readlane_b32 s23, v251, 13
	v_readlane_b32 s24, v251, 14
	v_readlane_b32 s25, v251, 15
	v_readlane_b32 s26, v251, 16
	v_readlane_b32 s27, v251, 17
	s_waitcnt vmcnt(0)
	v_pk_add_f32 v[220:221], v[220:221], 1.0 op_sel_hi:[1,0]
	s_nop 0
	v_pk_mul_f32 v[242:243], v[224:225], v[220:221]
	v_pk_add_f32 v[218:219], v[218:219], 1.0 op_sel_hi:[1,0]
	v_div_scale_f32 v215, s[0:1], v242, v242, 1.0
	v_rcp_f32_e32 v220, v215
	v_pk_mul_f32 v[218:219], v[222:223], v[218:219]
	s_mov_b32 s0, 0xda24260
	v_div_scale_f32 v245, s[2:3], v219, v219, 1.0
	v_fma_f32 v221, -v215, v220, 1.0
	v_fmac_f32_e32 v220, v221, v220
	v_div_scale_f32 v221, vcc, 1.0, v242, 1.0
	v_mul_f32_e32 v222, v221, v220
	v_fma_f32 v223, -v215, v222, v221
	v_fmac_f32_e32 v222, v223, v220
	v_fma_f32 v215, -v215, v222, v221
	v_div_scale_f32 v221, s[2:3], v243, v243, 1.0
	v_rcp_f32_e32 v223, v221
	v_div_fmas_f32 v215, v215, v220, v222
	v_rcp_f32_e32 v246, v245
	v_div_fixup_f32 v215, v215, v242, 1.0
	v_fma_f32 v220, -v221, v223, 1.0
	v_fmac_f32_e32 v223, v220, v223
	v_div_scale_f32 v220, vcc, 1.0, v243, 1.0
	v_mul_f32_e32 v222, v220, v223
	v_fma_f32 v224, -v221, v222, v220
	v_fmac_f32_e32 v222, v224, v223
	v_fma_f32 v220, -v221, v222, v220
	v_div_scale_f32 v221, s[2:3], v218, v218, 1.0
	v_rcp_f32_e32 v224, v221
	v_div_fmas_f32 v220, v220, v223, v222
	v_div_fixup_f32 v244, v220, v243, 1.0
	v_fma_f32 v220, -v221, v224, 1.0
	v_fmac_f32_e32 v224, v220, v224
	v_div_scale_f32 v220, vcc, 1.0, v218, 1.0
	v_mul_f32_e32 v222, v220, v224
	v_fma_f32 v223, -v221, v222, v220
	v_fmac_f32_e32 v222, v223, v224
	v_fma_f32 v220, -v221, v222, v220
	v_div_fmas_f32 v220, v220, v224, v222
	v_div_fixup_f32 v247, v220, v218, 1.0
	v_fma_f32 v220, -v245, v246, 1.0
	v_fmac_f32_e32 v246, v220, v246
	v_div_scale_f32 v248, vcc, 1.0, v219, 1.0
	v_mul_f32_e32 v249, v248, v246
	v_fma_f32 v220, -v245, v249, v248
	v_fmac_f32_e32 v249, v220, v246
	global_load_dwordx4 v[220:223], v[226:227], off offset:512
	s_nop 0
	global_load_dwordx4 v[224:227], v[216:217], off offset:528
	global_load_dwordx4 v[238:241], v[216:217], off offset:512
	v_fma_f32 v216, -v245, v249, v248
	v_div_fmas_f32 v216, v216, v246, v249
	v_cmp_gt_f32_e64 vcc, |v243|, s0
	v_pk_add_f32 v[232:233], v[232:233], 1.0 op_sel_hi:[1,0]
	v_div_fixup_f32 v245, v216, v219, 1.0
	v_cndmask_b32_e32 v217, 0, v244, vcc
	v_cmp_gt_f32_e64 vcc, |v242|, s0
	v_pk_mul_f32 v[210:211], v[210:211], v[232:233]
	v_pk_add_f32 v[230:231], v[230:231], 1.0 op_sel_hi:[1,0]
	v_cndmask_b32_e32 v216, 0, v215, vcc
	v_div_scale_f32 v215, s[2:3], v210, v210, 1.0
	v_rcp_f32_e32 v232, v215
	v_cmp_gt_f32_e64 vcc, |v219|, s0
	v_pk_mul_f32 v[230:231], v[208:209], v[230:231]
	v_fma_f32 v208, -v215, v232, 1.0
	v_cndmask_b32_e32 v219, 0, v245, vcc
	v_cmp_gt_f32_e64 vcc, |v218|, s0
	v_fmac_f32_e32 v232, v208, v232
	s_waitcnt vmcnt(2)
	v_pk_add_f32 v[222:223], v[222:223], 1.0 op_sel_hi:[1,0]
	v_cndmask_b32_e32 v218, 0, v247, vcc
	v_div_scale_f32 v208, vcc, 1.0, v210, 1.0
	v_mul_f32_e32 v209, v208, v232
	v_fma_f32 v233, -v215, v209, v208
	v_fmac_f32_e32 v209, v233, v232
	v_fma_f32 v208, -v215, v209, v208
	v_div_scale_f32 v215, s[2:3], v211, v211, 1.0
	v_rcp_f32_e32 v233, v215
	v_div_fmas_f32 v208, v208, v232, v209
	v_div_fixup_f32 v208, v208, v210, 1.0
	s_waitcnt vmcnt(0)
	v_pk_mul_f32 v[222:223], v[240:241], v[222:223]
	v_fma_f32 v209, -v215, v233, 1.0
	v_fmac_f32_e32 v233, v209, v233
	v_div_scale_f32 v209, vcc, 1.0, v211, 1.0
	v_mul_f32_e32 v232, v209, v233
	v_fma_f32 v242, -v215, v232, v209
	v_fmac_f32_e32 v232, v242, v233
	v_fma_f32 v209, -v215, v232, v209
	v_div_scale_f32 v215, s[2:3], v230, v230, 1.0
	v_rcp_f32_e32 v242, v215
	v_div_fmas_f32 v209, v209, v233, v232
	v_div_fixup_f32 v209, v209, v211, 1.0
	v_pk_add_f32 v[220:221], v[220:221], 1.0 op_sel_hi:[1,0]
	v_fma_f32 v232, -v215, v242, 1.0
	v_fmac_f32_e32 v242, v232, v242
	v_div_scale_f32 v232, vcc, 1.0, v230, 1.0
	v_mul_f32_e32 v233, v232, v242
	v_fma_f32 v243, -v215, v233, v232
	v_fmac_f32_e32 v233, v243, v242
	v_fma_f32 v215, -v215, v233, v232
	v_div_scale_f32 v232, s[2:3], v231, v231, 1.0
	v_rcp_f32_e32 v243, v232
	v_div_fmas_f32 v215, v215, v242, v233
	v_div_fixup_f32 v215, v215, v230, 1.0
	v_fma_f32 v233, -v232, v243, 1.0
	v_fmac_f32_e32 v243, v233, v243
	v_div_scale_f32 v233, vcc, 1.0, v231, 1.0
	v_mul_f32_e32 v242, v233, v243
	v_fma_f32 v244, -v232, v242, v233
	v_fmac_f32_e32 v242, v244, v243
	v_fma_f32 v232, -v232, v242, v233
	v_div_fmas_f32 v232, v232, v243, v242
	v_cmp_gt_f32_e64 vcc, |v211|, s0
	v_div_fixup_f32 v232, v232, v231, 1.0
	s_nop 0
	v_cndmask_b32_e32 v209, 0, v209, vcc
	v_cmp_gt_f32_e64 vcc, |v210|, s0
	s_nop 1
	v_cndmask_b32_e32 v208, 0, v208, vcc
	v_cmp_gt_f32_e64 vcc, |v231|, s0
	s_nop 1
	v_cndmask_b32_e32 v211, 0, v232, vcc
	v_div_scale_f32 v232, s[2:3], v222, v222, 1.0
	v_rcp_f32_e32 v233, v232
	v_cmp_gt_f32_e64 vcc, |v230|, s0
	v_pk_mul_f32 v[230:231], v[238:239], v[220:221]
	s_nop 0
	v_cndmask_b32_e32 v210, 0, v215, vcc
	v_fma_f32 v215, -v232, v233, 1.0
	v_fmac_f32_e32 v233, v215, v233
	v_div_scale_f32 v215, vcc, 1.0, v222, 1.0
	v_mul_f32_e32 v220, v215, v233
	v_fma_f32 v221, -v232, v220, v215
	v_fmac_f32_e32 v220, v221, v233
	v_div_scale_f32 v221, s[2:3], v223, v223, 1.0
	v_fma_f32 v215, -v232, v220, v215
	v_rcp_f32_e32 v232, v221
	v_div_fmas_f32 v215, v215, v233, v220
	v_div_fixup_f32 v215, v215, v222, 1.0
	v_fma_f32 v220, -v221, v232, 1.0
	v_fmac_f32_e32 v232, v220, v232
	v_div_scale_f32 v220, vcc, 1.0, v223, 1.0
	v_mul_f32_e32 v233, v220, v232
	v_fma_f32 v238, -v221, v233, v220
	v_fmac_f32_e32 v233, v238, v232
	v_fma_f32 v220, -v221, v233, v220
	v_div_scale_f32 v221, s[2:3], v230, v230, 1.0
	v_rcp_f32_e32 v238, v221
	v_div_fmas_f32 v220, v220, v232, v233
	v_div_fixup_f32 v220, v220, v223, 1.0
	v_fma_f32 v232, -v221, v238, 1.0
	v_fmac_f32_e32 v238, v232, v238
	v_div_scale_f32 v232, vcc, 1.0, v230, 1.0
	v_mul_f32_e32 v233, v232, v238
	v_fma_f32 v239, -v221, v233, v232
	v_fmac_f32_e32 v233, v239, v238
	v_fma_f32 v221, -v221, v233, v232
	v_div_scale_f32 v232, s[2:3], v231, v231, 1.0
	v_rcp_f32_e32 v239, v232
	v_div_fmas_f32 v221, v221, v238, v233
	v_div_fixup_f32 v238, v221, v230, 1.0
	v_fma_f32 v221, -v232, v239, 1.0
	v_fmac_f32_e32 v239, v221, v239
	v_div_scale_f32 v221, vcc, 1.0, v231, 1.0
	v_mul_f32_e32 v233, v221, v239
	v_fma_f32 v240, -v232, v233, v221
	v_fmac_f32_e32 v233, v240, v239
	v_fma_f32 v221, -v232, v233, v221
	v_div_fmas_f32 v221, v221, v239, v233
	v_cmp_gt_f32_e64 vcc, |v223|, s0
	v_div_fixup_f32 v232, v221, v231, 1.0
	s_nop 0
	v_cndmask_b32_e32 v221, 0, v220, vcc
	v_cmp_gt_f32_e64 vcc, |v222|, s0
	s_nop 1
	v_cndmask_b32_e32 v220, 0, v215, vcc
	v_cmp_gt_f32_e64 vcc, |v231|, s0
	s_nop 1
	v_cndmask_b32_e32 v223, 0, v232, vcc
	v_pk_add_f32 v[232:233], v[236:237], 1.0 op_sel_hi:[1,0]
	v_cmp_gt_f32_e64 vcc, |v230|, s0
	v_pk_mul_f32 v[226:227], v[226:227], v[232:233]
	v_pk_add_f32 v[230:231], v[234:235], 1.0 op_sel_hi:[1,0]
	v_div_scale_f32 v215, s[2:3], v226, v226, 1.0
	v_rcp_f32_e32 v232, v215
	v_pk_mul_f32 v[230:231], v[224:225], v[230:231]
	v_cndmask_b32_e32 v222, 0, v238, vcc
	v_fma_f32 v224, -v215, v232, 1.0
	v_fmac_f32_e32 v232, v224, v232
	v_div_scale_f32 v224, vcc, 1.0, v226, 1.0
	v_mul_f32_e32 v225, v224, v232
	v_fma_f32 v233, -v215, v225, v224
	v_fmac_f32_e32 v225, v233, v232
	v_fma_f32 v215, -v215, v225, v224
	v_div_scale_f32 v224, s[2:3], v227, v227, 1.0
	v_rcp_f32_e32 v233, v224
	v_div_fmas_f32 v215, v215, v232, v225
	v_div_fixup_f32 v215, v215, v226, 1.0
	v_fma_f32 v225, -v224, v233, 1.0
	v_fmac_f32_e32 v233, v225, v233
	v_div_scale_f32 v225, vcc, 1.0, v227, 1.0
	v_mul_f32_e32 v232, v225, v233
	v_fma_f32 v234, -v224, v232, v225
	v_fmac_f32_e32 v232, v234, v233
	v_fma_f32 v224, -v224, v232, v225
	v_div_scale_f32 v225, s[2:3], v230, v230, 1.0
	v_rcp_f32_e32 v234, v225
	v_div_fmas_f32 v224, v224, v233, v232
	v_div_fixup_f32 v224, v224, v227, 1.0
	v_fma_f32 v232, -v225, v234, 1.0
	v_fmac_f32_e32 v234, v232, v234
	v_div_scale_f32 v232, vcc, 1.0, v230, 1.0
	v_mul_f32_e32 v233, v232, v234
	v_fma_f32 v235, -v225, v233, v232
	v_fmac_f32_e32 v233, v235, v234
	v_fma_f32 v225, -v225, v233, v232
	v_div_scale_f32 v232, s[2:3], v231, v231, 1.0
	v_rcp_f32_e32 v235, v232
	v_div_fmas_f32 v225, v225, v234, v233
	v_div_fixup_f32 v233, v225, v230, 1.0
	v_fma_f32 v225, -v232, v235, 1.0
	v_fmac_f32_e32 v235, v225, v235
	v_div_scale_f32 v225, vcc, 1.0, v231, 1.0
	v_mul_f32_e32 v234, v225, v235
	v_fma_f32 v236, -v232, v234, v225
	v_fmac_f32_e32 v234, v236, v235
	v_fma_f32 v225, -v232, v234, v225
	v_div_fmas_f32 v225, v225, v235, v234
	v_cmp_gt_f32_e64 vcc, |v227|, s0
	v_div_fixup_f32 v232, v225, v231, 1.0
	s_nop 0
	v_cndmask_b32_e32 v225, 0, v224, vcc
	v_cmp_gt_f32_e64 vcc, |v226|, s0
	s_nop 1
	v_cndmask_b32_e32 v224, 0, v215, vcc
	v_cmp_gt_f32_e64 vcc, |v231|, s0
	s_nop 1
	v_cndmask_b32_e32 v227, 0, v232, vcc
	v_cmp_gt_f32_e64 vcc, |v230|, s0
	s_nop 1
	v_cndmask_b32_e32 v226, 0, v233, vcc
	v_mbcnt_lo_u32_b32 v215, -1, 0
	v_mbcnt_hi_u32_b32 v234, -1, v215
	v_and_b32_e32 v230, 64, v234
	v_add_u32_e32 v235, 64, v230
	v_lshlrev_b32_e32 v230, 16, v204
	v_and_b32_e32 v231, 0xffff0000, v204
	v_lshlrev_b32_e32 v204, 16, v205
	v_and_b32_e32 v205, 0xffff0000, v205
	v_pk_mul_f32 v[204:205], v[216:217], v[204:205]
	v_pk_mul_f32 v[230:231], v[218:219], v[230:231]
	v_lshlrev_b32_e32 v232, 16, v206
	v_and_b32_e32 v233, 0xffff0000, v206
	v_pk_fma_f32 v[126:127], v[126:127], v[138:139], v[204:205]
	v_pk_fma_f32 v[124:125], v[124:125], v[136:137], v[230:231]
	v_pk_mul_f32 v[232:233], v[210:211], v[232:233]
	v_mul_f32_e32 v204, v125, v125
	v_mul_f32_e32 v205, v127, v127
	v_lshlrev_b32_e32 v206, 16, v207
	v_and_b32_e32 v207, 0xffff0000, v207
	v_pk_fma_f32 v[120:121], v[120:121], v[140:141], v[232:233]
	v_fmac_f32_e32 v204, v124, v124
	v_fmac_f32_e32 v205, v126, v126
	v_pk_mul_f32 v[206:207], v[208:209], v[206:207]
	v_add_f32_e32 v204, v204, v205
	v_mul_f32_e32 v205, v121, v121
	v_pk_fma_f32 v[122:123], v[122:123], v[142:143], v[206:207]
	v_fmac_f32_e32 v205, v120, v120
	v_add_f32_e32 v204, v204, v205
	v_mul_f32_e32 v205, v123, v123
	v_fmac_f32_e32 v205, v122, v122
	v_add_f32_e32 v230, v205, v204
	v_lshlrev_b32_e32 v204, 16, v200
	v_and_b32_e32 v205, 0xffff0000, v200
	v_lshlrev_b32_e32 v200, 16, v201
	v_and_b32_e32 v201, 0xffff0000, v201
	v_pk_mul_f32 v[200:201], v[220:221], v[200:201]
	v_pk_mul_f32 v[204:205], v[222:223], v[204:205]
	v_lshlrev_b32_e32 v206, 16, v202
	v_and_b32_e32 v207, 0xffff0000, v202
	v_pk_fma_f32 v[118:119], v[118:119], v[134:135], v[200:201]
	v_pk_fma_f32 v[116:117], v[116:117], v[132:133], v[204:205]
	v_pk_mul_f32 v[206:207], v[226:227], v[206:207]
	v_mul_f32_e32 v200, v117, v117
	v_mul_f32_e32 v201, v119, v119
	v_lshlrev_b32_e32 v202, 16, v203
	v_and_b32_e32 v203, 0xffff0000, v203
	v_pk_fma_f32 v[112:113], v[112:113], v[128:129], v[206:207]
	v_fmac_f32_e32 v200, v116, v116
	v_fmac_f32_e32 v201, v118, v118
	v_pk_mul_f32 v[202:203], v[224:225], v[202:203]
	v_add_f32_e32 v200, v200, v201
	v_mul_f32_e32 v201, v113, v113
	v_pk_fma_f32 v[114:115], v[114:115], v[130:131], v[202:203]
	v_fmac_f32_e32 v201, v112, v112
	v_xor_b32_e32 v215, 16, v234
	v_add_f32_e32 v200, v200, v201
	v_mul_f32_e32 v201, v115, v115
	v_cmp_lt_i32_e32 vcc, v215, v235
	v_fmac_f32_e32 v201, v114, v114
	v_add_f32_e32 v200, v201, v200
	v_cndmask_b32_e32 v215, v234, v215, vcc
	v_lshlrev_b32_e32 v215, 2, v215
	v_add_f32_e32 v200, v230, v200
	ds_bpermute_b32 v202, v215, v200
	v_xor_b32_e32 v201, 32, v234
	v_cmp_lt_i32_e32 vcc, v201, v235
	s_lshl_b32 s0, s9, 2
	s_add_i32 s0, s0, 0
	v_cndmask_b32_e32 v201, v234, v201, vcc
	v_lshlrev_b32_e32 v201, 2, v201
	s_waitcnt lgkmcnt(0)
	v_add_f32_e32 v202, v200, v202
	ds_bpermute_b32 v203, v201, v202
	v_cmp_eq_u32_e32 vcc, 0, v229
	v_lshl_add_u32 v200, v214, 4, s0
	s_and_saveexec_b64 s[0:1], vcc
	s_cbranch_execz .LBB0_622
	s_waitcnt lgkmcnt(0)
	v_add_f32_e32 v202, v202, v203
	ds_write_b32 v200, v202
